# INA epilogue: per-tile constant loads (mem gains, oml) hoisted out of row blocks; HGRN: ERHO scaling + GEMM1 LDS reads batched
# speedup vs baseline: 1.0424x; 1.0067x over previous
.LBB0_173:
	s_or_b64 exec, exec, s[8:9]
	s_waitcnt lgkmcnt(0)
	s_barrier
	ds_read_b128 v[48:51], v143
	ds_read_b128 v[222:225], v143 offset:32
	ds_read_b128 v[226:229], v143 offset:64
	ds_read_b128 v[230:233], v143 offset:96
	ds_read_b128 v[234:237], v143 offset:128
	s_waitcnt lgkmcnt(4)
	v_pk_mul_f32 v[16:17], v[16:17], v[48:49]
	v_pk_mul_f32 v[18:19], v[18:19], v[50:51]
	v_cvt_pk_bf16_f32 v48, v16, v17
	s_nop 0
	v_cvt_pk_bf16_f32 v49, v18, v19
	ds_write_b64 v181, v[48:49]
	ds_read_b128 v[48:51], v143 offset:160
	s_waitcnt lgkmcnt(5)
	v_pk_mul_f32 v[20:21], v[20:21], v[222:223]
	v_pk_mul_f32 v[22:23], v[22:23], v[224:225]
	v_cvt_pk_bf16_f32 v222, v20, v21
	s_nop 0
	v_cvt_pk_bf16_f32 v223, v22, v23
	ds_write_b64 v181, v[222:223] offset:16
	ds_read_b128 v[222:225], v143 offset:192
	s_waitcnt lgkmcnt(6)
	v_pk_mul_f32 v[24:25], v[24:25], v[226:227]
	v_pk_mul_f32 v[26:27], v[26:27], v[228:229]
	v_cvt_pk_bf16_f32 v226, v24, v25
	s_nop 0
	v_cvt_pk_bf16_f32 v227, v26, v27
	ds_write_b64 v181, v[226:227] offset:32
	ds_read_b128 v[226:229], v143 offset:224
	s_waitcnt lgkmcnt(7)
	v_pk_mul_f32 v[28:29], v[28:29], v[230:231]
	v_pk_mul_f32 v[30:31], v[30:31], v[232:233]
	v_cvt_pk_bf16_f32 v230, v28, v29
	s_nop 0
	v_cvt_pk_bf16_f32 v231, v30, v31
	ds_write_b64 v181, v[230:231] offset:48
	s_waitcnt lgkmcnt(7)
	v_pk_mul_f32 v[32:33], v[32:33], v[234:235]
	v_pk_mul_f32 v[34:35], v[34:35], v[236:237]
	v_cvt_pk_bf16_f32 v234, v32, v33
	s_nop 0
	v_cvt_pk_bf16_f32 v235, v34, v35
	ds_write_b64 v181, v[234:235] offset:64
	s_waitcnt lgkmcnt(6)
	v_pk_mul_f32 v[36:37], v[36:37], v[48:49]
	v_pk_mul_f32 v[38:39], v[38:39], v[50:51]
	v_cvt_pk_bf16_f32 v48, v36, v37
	s_nop 0
	v_cvt_pk_bf16_f32 v49, v38, v39
	ds_write_b64 v181, v[48:49] offset:80
	s_waitcnt lgkmcnt(5)
	v_pk_mul_f32 v[40:41], v[40:41], v[222:223]
	v_pk_mul_f32 v[42:43], v[42:43], v[224:225]
	v_cvt_pk_bf16_f32 v222, v40, v41
	s_nop 0
	v_cvt_pk_bf16_f32 v223, v42, v43
	ds_write_b64 v181, v[222:223] offset:96
	s_waitcnt lgkmcnt(4)
	v_pk_mul_f32 v[44:45], v[44:45], v[226:227]
	v_pk_mul_f32 v[46:47], v[46:47], v[228:229]
	v_cvt_pk_bf16_f32 v226, v44, v45
	s_nop 0
	v_cvt_pk_bf16_f32 v227, v46, v47
	ds_write_b64 v181, v[226:227] offset:112
	s_waitcnt lgkmcnt(0)
	s_barrier
	s_and_saveexec_b64 s[82:83], s[28:29]
	s_cbranch_execz .LBB0_175
	ds_read_b128 v[48:51], v173 offset:17408
	ds_read_b128 v[52:55], v174
	ds_read_b128 v[68:71], v173 offset:17440
	ds_read_b128 v[72:75], v174 offset:32
	ds_read_b128 v[76:79], v173 offset:17472
	ds_read_b128 v[80:83], v174 offset:64
	ds_read_b128 v[84:87], v173 offset:17504
	ds_read_b128 v[88:91], v174 offset:96
	ds_read_b128 v[92:95], v173 offset:17536
	ds_read_b128 v[96:99], v174 offset:128
	ds_read_b128 v[222:225], v173 offset:17568
	ds_read_b128 v[226:229], v174 offset:160
	ds_read_b128 v[230:233], v173 offset:17600
	ds_read_b128 v[234:237], v174 offset:192
	s_waitcnt lgkmcnt(12)
	v_mfma_f32_32x32x16_bf16 v[48:63], v[48:51], v[52:55], 0
	s_waitcnt lgkmcnt(10)
	v_mfma_f32_32x32x16_bf16 v[48:63], v[68:71], v[72:75], v[48:63]
	ds_read_b128 v[68:71], v173 offset:17632
	ds_read_b128 v[72:75], v174 offset:224
	s_waitcnt lgkmcnt(10)
	v_mfma_f32_32x32x16_bf16 v[48:63], v[76:79], v[80:83], v[48:63]
	s_waitcnt lgkmcnt(8)
	v_mfma_f32_32x32x16_bf16 v[48:63], v[84:87], v[88:91], v[48:63]
	s_waitcnt lgkmcnt(6)
	v_mfma_f32_32x32x16_bf16 v[48:63], v[92:95], v[96:99], v[48:63]
	s_waitcnt lgkmcnt(4)
	v_mfma_f32_32x32x16_bf16 v[48:63], v[222:225], v[226:229], v[48:63]
	s_waitcnt lgkmcnt(2)
	v_mfma_f32_32x32x16_bf16 v[48:63], v[230:233], v[234:237], v[48:63]
	s_waitcnt lgkmcnt(0)
	v_mfma_f32_32x32x16_bf16 v[48:63], v[68:71], v[72:75], v[48:63]
	s_nop 11
	v_cndmask_b32_e64 v48, v48, 0, s[50:51]
	v_cndmask_b32_e64 v49, 0, v49, s[52:53]
	v_cndmask_b32_e64 v50, v50, 0, s[54:55]
	v_cndmask_b32_e64 v51, v51, 0, s[56:57]
	v_cndmask_b32_e64 v52, v52, 0, s[58:59]
	v_cndmask_b32_e64 v53, v53, 0, s[60:61]
	v_cndmask_b32_e64 v54, v54, 0, s[62:63]
	v_cndmask_b32_e64 v55, v55, 0, s[64:65]
	v_cvt_pk_bf16_f32 v48, v48, v49
	v_cvt_pk_bf16_f32 v49, v50, v51
	v_cvt_pk_bf16_f32 v50, v52, v53
	v_cvt_pk_bf16_f32 v51, v54, v55
	v_cndmask_b32_e64 v56, v56, 0, s[66:67]
	v_cndmask_b32_e64 v57, v57, 0, s[68:69]
	v_cndmask_b32_e64 v58, v58, 0, s[70:71]
	v_cndmask_b32_e64 v59, v59, 0, s[72:73]
	v_cndmask_b32_e64 v60, v60, 0, s[74:75]
	v_cndmask_b32_e64 v61, v61, 0, s[76:77]
	v_cndmask_b32_e64 v62, v62, 0, s[78:79]
	v_cndmask_b32_e64 v63, v63, 0, s[80:81]
	v_cvt_pk_bf16_f32 v52, v56, v57
	v_cvt_pk_bf16_f32 v53, v58, v59
	v_cvt_pk_bf16_f32 v54, v60, v61
	v_cvt_pk_bf16_f32 v55, v62, v63
	ds_write2_b64 v204, v[48:49], v[50:51] offset1:2
	ds_write2_b64 v204, v[52:53], v[54:55] offset0:4 offset1:6

.LBB0_811:
	s_cmp_gt_i32 s71, 11
	s_cselect_b64 s[12:13], -1, 0
	s_add_i32 s73, s71, 2
	s_cmp_lt_u32 s73, 5
	s_cselect_b64 s[26:27], -1, 0
	s_add_i32 s0, s71, -6
	v_lshl_add_u32 v142, v152, 2, s66
	s_cmp_gt_u32 s0, 2
	ds_read2_b32 v[148:149], v142 offset1:16
	ds_read2_b32 v[146:147], v142 offset0:32 offset1:48
	ds_read2_b32 v[144:145], v142 offset0:64 offset1:80
	ds_read2_b32 v[142:143], v142 offset0:96 offset1:112
	v_lshlrev_b32_e32 v168, 3, v150
	s_cselect_b64 s[28:29], -1, 0
	s_and_b64 s[0:1], s[26:27], exec
	v_add_u32_e32 v175, s4, v152
	v_lshlrev_b32_e32 v151, 2, v151
	v_ashrrev_i32_e32 v169, 31, v168
	s_mov_b32 s0, 0x80a0000
	v_xor_b32_e32 v174, 64, v151
	v_xor_b32_e32 v173, 0x80, v151
	s_cselect_b32 s72, s0, 0x12e1d000
	s_waitcnt lgkmcnt(0)
	v_pk_mul_f32 v[164:165], v[128:129], v[148:149] op_sel_hi:[1,0]
	v_pk_mul_f32 v[166:167], v[126:127], v[148:149] op_sel_hi:[1,0]
	v_pk_mul_f32 v[160:161], v[124:125], v[148:149] op_sel_hi:[1,0]
	v_pk_mul_f32 v[162:163], v[122:123], v[148:149] op_sel_hi:[1,0]
	v_pk_mul_f32 v[154:155], v[120:121], v[148:149] op_sel_hi:[1,0]
	v_pk_mul_f32 v[156:157], v[118:119], v[148:149] op_sel_hi:[1,0]
	v_pk_mul_f32 v[150:151], v[116:117], v[148:149] op_sel_hi:[1,0]
	v_pk_mul_f32 v[152:153], v[114:115], v[148:149] op_sel_hi:[1,0]
	v_add_u32_e32 v158, s50, v175
	s_mov_b64 s[0:1], -1
	s_and_b64 vcc, exec, s[12:13]
	v_lshlrev_b64 v[126:127], 1, v[168:169]
	v_lshl_add_u64 v[128:129], v[168:169], 2, s[14:15]
	global_load_dwordx4 v[204:207], v[128:129], off
	global_load_dwordx4 v[208:211], v[128:129], off offset:16
	global_load_dwordx4 v[212:215], v[128:129], off offset:128
	global_load_dwordx4 v[216:219], v[128:129], off offset:144
	s_cbranch_vccz .LBB0_813
	v_mul_f32_e32 v116, v167, v167
	v_fmac_f32_e32 v116, v166, v166
	v_fmac_f32_e32 v116, v164, v164
	v_fmac_f32_e32 v116, v165, v165
	v_fmac_f32_e32 v116, v162, v162
	v_fmac_f32_e32 v116, v163, v163
	v_fmac_f32_e32 v116, v160, v160
	v_fmac_f32_e32 v116, v161, v161
	v_fmac_f32_e32 v116, v156, v156
	v_fmac_f32_e32 v116, v157, v157
	v_fmac_f32_e32 v116, v154, v154
	v_fmac_f32_e32 v116, v155, v155
	v_fmac_f32_e32 v116, v152, v152
	v_fmac_f32_e32 v116, v153, v153
	v_pk_mul_f32 v[114:115], v[150:151], v[150:151]
	s_mov_b64 s[0:1], 0
	v_add_f32_e32 v114, v114, v116
	v_add_f32_e32 v114, v115, v114
	ds_bpermute_b32 v115, v174, v114
	s_waitcnt lgkmcnt(0)
	v_add_f32_e32 v114, v114, v115
	ds_bpermute_b32 v115, v173, v114
	s_waitcnt lgkmcnt(0)
	v_add_f32_e32 v114, v114, v115
	v_fmamk_f32 v114, v114, 0x3c800000, v188
	v_rsq_f32_e32 v114, v114
	s_nop 0
	v_mul_f32_e32 v122, 0x3e38aa3b, v114
	s_nop 0
	s_nop 0
	v_mul_f32_e32 v123, v166, v122
	v_mul_f32_e32 v159, v156, v122
	s_waitcnt vmcnt(0)
	v_mul_f32_e32 v123, v204, v123
	v_mul_f32_e32 v118, v162, v122
	v_mul_f32_e32 v124, v208, v118
	v_mul_f32_e32 v114, v167, v122
	v_mul_f32_e32 v125, v205, v114
	v_mul_f32_e32 v114, v163, v122
	v_mul_f32_e32 v148, v209, v114
	v_mul_f32_e32 v114, v164, v122
	v_mul_f32_e32 v169, v206, v114
	v_mul_f32_e32 v114, v160, v122
	v_mul_f32_e32 v176, v210, v114
	v_mul_f32_e32 v114, v165, v122
	v_mul_f32_e32 v177, v207, v114
	v_mul_f32_e32 v114, v161, v122
	v_mul_f32_e32 v178, v211, v114
	s_nop 0
	s_nop 0
	s_nop 0
	v_mul_f32_e32 v179, v212, v159
	v_mul_f32_e32 v118, v152, v122
	v_mul_f32_e32 v180, v216, v118
	v_mul_f32_e32 v114, v157, v122
	v_mul_f32_e32 v181, v213, v114
	v_mul_f32_e32 v114, v153, v122
	v_mul_f32_e32 v182, v217, v114
	v_mul_f32_e32 v114, v154, v122
	v_mul_f32_e32 v183, v214, v114
	v_mul_f32_e32 v114, v150, v122
	v_ashrrev_i32_e32 v159, 31, v158
	v_mul_f32_e32 v184, v218, v114
	v_mul_f32_e32 v114, v155, v122
	v_lshlrev_b64 v[118:119], 9, v[158:159]
	v_mul_f32_e32 v185, v215, v114
	v_lshl_add_u64 v[120:121], s[18:19], 0, v[118:119]
	v_lshl_add_u64 v[118:119], s[20:21], 0, v[118:119]
	v_lshl_add_u64 v[118:119], v[118:119], 0, v[126:127]
	v_mul_f32_e32 v114, v151, v122
	v_add_co_u32_e32 v118, vcc, 0x3b6e9000, v118
	v_mul_f32_e32 v122, v219, v114
	v_cvt_pk_bf16_f32 v114, v123, v125
	v_cvt_pk_bf16_f32 v115, v169, v177
	v_cvt_pk_bf16_f32 v116, v124, v148
	v_cvt_pk_bf16_f32 v117, v176, v178
	v_lshl_add_u64 v[120:121], v[120:121], 0, v[126:127]
	v_addc_co_u32_e32 v119, vcc, 0, v119, vcc
	global_store_dwordx4 v[120:121], v[114:117], off
	s_nop 1
	v_cvt_pk_bf16_f32 v114, v179, v181
	v_cvt_pk_bf16_f32 v115, v183, v185
	v_cvt_pk_bf16_f32 v116, v180, v182
	v_cvt_pk_bf16_f32 v117, v184, v122
	global_store_dwordx4 v[118:119], v[114:117], off offset:320
.LBB0_813:
	s_mul_hi_i32 s4, s71, 0x55555556
	s_lshr_b32 s5, s4, 31
	s_add_i32 s4, s4, s5
	s_mul_i32 s4, s4, 3
	s_sub_i32 s4, s71, s4
	s_lshl_b32 s4, s4, 8
	s_or_b32 s4, s4, s45
	v_add_u32_e32 v122, s4, v168
	v_add_u32_e32 v124, 0x80, v122
	v_ashrrev_i32_e32 v123, 31, v122
	s_andn2_b64 vcc, exec, s[0:1]
	v_ashrrev_i32_e32 v125, 31, v124
	v_lshl_add_u64 v[236:237], v[122:123], 2, s[16:17]
	global_load_dwordx4 v[220:223], v[236:237], off
	global_load_dwordx4 v[224:227], v[236:237], off offset:16
	global_load_dwordx4 v[228:231], v[236:237], off offset:512
	global_load_dwordx4 v[232:235], v[236:237], off offset:528
	s_cbranch_vccnz .LBB0_833
	s_cmp_lt_i32 s71, 9
	s_cbranch_scc1 .LBB0_816
	s_cmp_gt_i32 s71, 11
	s_mov_b64 s[0:1], -1
	s_cselect_b64 s[4:5], -1, 0
	s_cbranch_execz .LBB0_817
	s_branch .LBB0_818

.LBB0_822:
	s_mov_b64 s[0:1], -1
	s_and_b64 vcc, exec, s[28:29]
	s_cbranch_vccz .LBB0_824
	v_lshl_add_u64 v[118:119], v[122:123], 2, s[16:17]
	s_nop 0
	s_nop 0
	s_nop 0
	v_mul_f32_e32 v148, 0x3fb8aa3b, v166
	v_exp_f32_e32 v148, v148
	s_mov_b32 s0, 0x800000
	s_mov_b32 s1, 0x3f317217
	s_mov_b32 s4, 0x7f800000
	v_add_f32_e32 v148, 1.0, v148
	v_rcp_f32_e32 v148, v148
	v_lshl_add_u64 v[176:177], v[168:169], 2, s[86:87]
	s_waitcnt vmcnt(0)
	v_mul_f32_e32 v118, v148, v220
	v_mul_f32_e32 v148, 0x3fb8aa3b, v162
	v_exp_f32_e32 v148, v148
	v_min_f32_e32 v118, 0x3f7fffef, v118
	v_add_f32_e32 v148, 1.0, v148
	v_rcp_f32_e32 v148, v148
	s_nop 0
	v_mul_f32_e32 v114, v148, v224
	v_min_f32_e32 v148, 0x3f7fffef, v114
	v_sub_f32_e32 v114, 1.0, v118
	v_cmp_gt_f32_e32 vcc, s0, v114
	s_nop 1
	v_cndmask_b32_e64 v118, 0, 32, vcc
	v_ldexp_f32 v114, v114, v118
	v_log_f32_e32 v114, v114
	s_nop 0
	v_mul_f32_e32 v118, 0x3f317217, v114
	v_fma_f32 v118, v114, s1, -v118
	v_fmac_f32_e32 v118, 0x3377d1cf, v114
	v_fmac_f32_e32 v118, 0x3f317217, v114
	v_cmp_lt_f32_e64 s[10:11], |v114|, s4
	s_nop 1
	v_cndmask_b32_e64 v114, v114, v118, s[10:11]
	v_cndmask_b32_e32 v118, 0, v199, vcc
	v_sub_f32_e32 v114, v114, v118
	v_sub_f32_e32 v118, 1.0, v148
	v_cmp_gt_f32_e32 vcc, s0, v118
	s_nop 1
	v_cndmask_b32_e64 v148, 0, 32, vcc
	v_ldexp_f32 v118, v118, v148
	v_log_f32_e32 v118, v118
	s_nop 0
	v_mul_f32_e32 v148, 0x3f317217, v118
	v_fma_f32 v148, v118, s1, -v148
	v_fmac_f32_e32 v148, 0x3377d1cf, v118
	v_fmac_f32_e32 v148, 0x3f317217, v118
	v_cmp_lt_f32_e64 s[10:11], |v118|, s4
	s_nop 1
	v_cndmask_b32_e64 v118, v118, v148, s[10:11]
	v_cndmask_b32_e32 v148, 0, v199, vcc
	v_sub_f32_e32 v118, v118, v148
	v_mul_f32_e32 v148, 0x3fb8aa3b, v167
	v_exp_f32_e32 v148, v148
	s_nop 0
	v_add_f32_e32 v148, 1.0, v148
	v_rcp_f32_e32 v148, v148
	s_nop 0
	v_mul_f32_e32 v119, v148, v221
	v_mul_f32_e32 v148, 0x3fb8aa3b, v163
	v_exp_f32_e32 v148, v148
	v_min_f32_e32 v119, 0x3f7fffef, v119
	v_add_f32_e32 v148, 1.0, v148
	v_rcp_f32_e32 v148, v148
	s_nop 0
	v_mul_f32_e32 v115, v148, v225
	v_min_f32_e32 v148, 0x3f7fffef, v115
	v_sub_f32_e32 v115, 1.0, v119
	v_cmp_gt_f32_e32 vcc, s0, v115
	s_nop 1
	v_cndmask_b32_e64 v119, 0, 32, vcc
	v_ldexp_f32 v115, v115, v119
	v_log_f32_e32 v115, v115
	s_nop 0
	v_mul_f32_e32 v119, 0x3f317217, v115
	v_fma_f32 v119, v115, s1, -v119
	v_fmac_f32_e32 v119, 0x3377d1cf, v115
	v_fmac_f32_e32 v119, 0x3f317217, v115
	v_cmp_lt_f32_e64 s[10:11], |v115|, s4
	s_nop 1
	v_cndmask_b32_e64 v115, v115, v119, s[10:11]
	v_cndmask_b32_e32 v119, 0, v199, vcc
	v_sub_f32_e32 v115, v115, v119
	v_sub_f32_e32 v119, 1.0, v148
	v_cmp_gt_f32_e32 vcc, s0, v119
	s_nop 1
	v_cndmask_b32_e64 v148, 0, 32, vcc
	v_ldexp_f32 v119, v119, v148
	v_log_f32_e32 v119, v119
	s_nop 0
	v_mul_f32_e32 v148, 0x3f317217, v119
	v_fma_f32 v148, v119, s1, -v148
	v_fmac_f32_e32 v148, 0x3377d1cf, v119
	v_fmac_f32_e32 v148, 0x3f317217, v119
	v_cmp_lt_f32_e64 s[10:11], |v119|, s4
	s_nop 1
	v_cndmask_b32_e64 v119, v119, v148, s[10:11]
	v_cndmask_b32_e32 v148, 0, v199, vcc
	v_sub_f32_e32 v119, v119, v148
	v_mul_f32_e32 v148, 0x3fb8aa3b, v164
	v_exp_f32_e32 v148, v148
	s_nop 0
	v_add_f32_e32 v148, 1.0, v148
	v_rcp_f32_e32 v148, v148
	s_nop 0
	v_mul_f32_e32 v120, v148, v222
	v_mul_f32_e32 v148, 0x3fb8aa3b, v160
	v_exp_f32_e32 v148, v148
	v_min_f32_e32 v120, 0x3f7fffef, v120
	v_add_f32_e32 v148, 1.0, v148
	v_rcp_f32_e32 v148, v148
	s_nop 0
	v_mul_f32_e32 v116, v148, v226
	v_min_f32_e32 v148, 0x3f7fffef, v116
	v_sub_f32_e32 v116, 1.0, v120
	v_cmp_gt_f32_e32 vcc, s0, v116
	s_nop 1
	v_cndmask_b32_e64 v120, 0, 32, vcc
	v_ldexp_f32 v116, v116, v120
	v_log_f32_e32 v116, v116
	s_nop 0
	v_mul_f32_e32 v120, 0x3f317217, v116
	v_fma_f32 v120, v116, s1, -v120
	v_fmac_f32_e32 v120, 0x3377d1cf, v116
	v_fmac_f32_e32 v120, 0x3f317217, v116
	v_cmp_lt_f32_e64 s[10:11], |v116|, s4
	s_nop 1
	v_cndmask_b32_e64 v116, v116, v120, s[10:11]
	v_cndmask_b32_e32 v120, 0, v199, vcc
	v_sub_f32_e32 v116, v116, v120
	v_sub_f32_e32 v120, 1.0, v148
	v_cmp_gt_f32_e32 vcc, s0, v120
	s_nop 1
	v_cndmask_b32_e64 v148, 0, 32, vcc
	v_ldexp_f32 v120, v120, v148
	v_log_f32_e32 v120, v120
	s_nop 0
	v_mul_f32_e32 v148, 0x3f317217, v120
	v_fma_f32 v148, v120, s1, -v148
	v_fmac_f32_e32 v148, 0x3377d1cf, v120
	v_fmac_f32_e32 v148, 0x3f317217, v120
	v_cmp_lt_f32_e64 s[10:11], |v120|, s4
	s_nop 1
	v_cndmask_b32_e64 v120, v120, v148, s[10:11]
	v_cndmask_b32_e32 v148, 0, v199, vcc
	v_sub_f32_e32 v120, v120, v148
	v_mul_f32_e32 v148, 0x3fb8aa3b, v165
	v_exp_f32_e32 v148, v148
	s_nop 0
	v_add_f32_e32 v148, 1.0, v148
	v_rcp_f32_e32 v148, v148
	s_nop 0
	v_mul_f32_e32 v121, v148, v223
	v_mul_f32_e32 v148, 0x3fb8aa3b, v161
	v_exp_f32_e32 v148, v148
	v_min_f32_e32 v121, 0x3f7fffef, v121
	v_add_f32_e32 v148, 1.0, v148
	v_rcp_f32_e32 v148, v148
	s_nop 0
	v_mul_f32_e32 v117, v148, v227
	v_min_f32_e32 v148, 0x3f7fffef, v117
	v_sub_f32_e32 v117, 1.0, v121
	v_cmp_gt_f32_e32 vcc, s0, v117
	s_nop 1
	v_cndmask_b32_e64 v121, 0, 32, vcc
	v_ldexp_f32 v117, v117, v121
	v_log_f32_e32 v117, v117
	s_nop 0
	v_mul_f32_e32 v121, 0x3f317217, v117
	v_fma_f32 v121, v117, s1, -v121
	v_fmac_f32_e32 v121, 0x3377d1cf, v117
	v_fmac_f32_e32 v121, 0x3f317217, v117
	v_cmp_lt_f32_e64 s[10:11], |v117|, s4
	s_nop 1
	v_cndmask_b32_e64 v117, v117, v121, s[10:11]
	v_cndmask_b32_e32 v121, 0, v199, vcc
	v_sub_f32_e32 v117, v117, v121
	v_sub_f32_e32 v121, 1.0, v148
	v_cmp_gt_f32_e32 vcc, s0, v121
	s_nop 1
	v_cndmask_b32_e64 v148, 0, 32, vcc
	v_ldexp_f32 v121, v121, v148
	v_log_f32_e32 v121, v121
	s_nop 0
	v_mul_f32_e32 v148, 0x3f317217, v121
	v_fma_f32 v148, v121, s1, -v148
	v_fmac_f32_e32 v148, 0x3377d1cf, v121
	v_fmac_f32_e32 v148, 0x3f317217, v121
	v_cmp_lt_f32_e64 s[10:11], |v121|, s4
	s_mov_b64 s[0:1], 0
	s_nop 0
	v_cndmask_b32_e64 v121, v121, v148, s[10:11]
	v_cndmask_b32_e32 v148, 0, v199, vcc
	v_sub_f32_e32 v121, v121, v148
	global_store_dwordx4 v[176:177], v[114:117], off
	global_store_dwordx4 v[176:177], v[118:121], off offset:16

.LBB0_833:
	s_nop 1
	v_mov_b32_e32 v114, v149
	v_pk_mul_f32 v[116:117], v[108:109], v[114:115] op_sel_hi:[1,0]
	v_pk_mul_f32 v[108:109], v[98:99], v[114:115] op_sel_hi:[1,0]
	v_cndmask_b32_e64 v98, 0, 1, s[12:13]
	v_pk_mul_f32 v[120:121], v[112:113], v[114:115] op_sel_hi:[1,0]
	v_pk_mul_f32 v[148:149], v[110:111], v[114:115] op_sel_hi:[1,0]
	v_pk_mul_f32 v[118:119], v[106:107], v[114:115] op_sel_hi:[1,0]
	v_pk_mul_f32 v[110:111], v[104:105], v[114:115] op_sel_hi:[1,0]
	v_pk_mul_f32 v[112:113], v[102:103], v[114:115] op_sel_hi:[1,0]
	v_pk_mul_f32 v[106:107], v[100:101], v[114:115] op_sel_hi:[1,0]
	v_add_u32_e32 v114, s83, v175
	v_cmp_ne_u32_e64 s[10:11], 1, v98
	s_andn2_b64 vcc, exec, s[12:13]
	s_mov_b64 s[0:1], -1
	s_cbranch_vccnz .LBB0_835
	v_mul_f32_e32 v100, v149, v149
	v_fmac_f32_e32 v100, v148, v148
	v_fmac_f32_e32 v100, v120, v120
	v_fmac_f32_e32 v100, v121, v121
	v_fmac_f32_e32 v100, v118, v118
	v_fmac_f32_e32 v100, v119, v119
	v_fmac_f32_e32 v100, v116, v116
	v_fmac_f32_e32 v100, v117, v117
	v_fmac_f32_e32 v100, v112, v112
	v_fmac_f32_e32 v100, v113, v113
	v_fmac_f32_e32 v100, v110, v110
	v_fmac_f32_e32 v100, v111, v111
	v_fmac_f32_e32 v100, v108, v108
	v_fmac_f32_e32 v100, v109, v109
	v_pk_mul_f32 v[98:99], v[106:107], v[106:107]
	s_mov_b64 s[0:1], 0
	v_add_f32_e32 v98, v98, v100
	v_add_f32_e32 v98, v99, v98
	ds_bpermute_b32 v99, v174, v98
	s_waitcnt lgkmcnt(0)
	v_add_f32_e32 v98, v98, v99
	ds_bpermute_b32 v99, v173, v98
	s_waitcnt lgkmcnt(0)
	v_add_f32_e32 v98, v98, v99
	v_fmamk_f32 v98, v98, 0x3c800000, v188
	v_rsq_f32_e32 v98, v98
	s_nop 0
	v_mul_f32_e32 v115, 0x3e38aa3b, v98
	s_nop 0
	s_nop 0
	v_mul_f32_e32 v150, v148, v115
	v_mul_f32_e32 v158, v112, v115
	s_nop 0
	v_mul_f32_e32 v150, v204, v150
	v_mul_f32_e32 v102, v118, v115
	v_mul_f32_e32 v151, v208, v102
	v_mul_f32_e32 v98, v149, v115
	v_mul_f32_e32 v152, v205, v98
	v_mul_f32_e32 v98, v119, v115
	v_mul_f32_e32 v153, v209, v98
	v_mul_f32_e32 v98, v120, v115
	v_mul_f32_e32 v154, v206, v98
	v_mul_f32_e32 v98, v116, v115
	v_mul_f32_e32 v155, v210, v98
	v_mul_f32_e32 v98, v121, v115
	v_mul_f32_e32 v156, v207, v98
	v_mul_f32_e32 v98, v117, v115
	v_mul_f32_e32 v157, v211, v98
	s_nop 0
	s_nop 0
	s_nop 0
	v_mul_f32_e32 v158, v212, v158
	v_mul_f32_e32 v102, v108, v115
	v_mul_f32_e32 v159, v216, v102
	v_mul_f32_e32 v98, v113, v115
	v_mul_f32_e32 v160, v213, v98
	v_mul_f32_e32 v98, v109, v115
	v_mul_f32_e32 v161, v217, v98
	v_mul_f32_e32 v98, v110, v115
	v_mul_f32_e32 v162, v214, v98
	v_mul_f32_e32 v98, v106, v115
	v_mul_f32_e32 v163, v218, v98
	v_mul_f32_e32 v98, v111, v115
	v_mul_f32_e32 v164, v215, v98
	v_mul_f32_e32 v98, v107, v115
	v_ashrrev_i32_e32 v115, 31, v114
	v_lshlrev_b64 v[102:103], 9, v[114:115]
	v_lshl_add_u64 v[104:105], s[18:19], 0, v[102:103]
	v_lshl_add_u64 v[102:103], s[20:21], 0, v[102:103]
	v_lshl_add_u64 v[102:103], v[102:103], 0, v[126:127]
	v_add_co_u32_e32 v102, vcc, 0x3b6e9000, v102
	v_mul_f32_e32 v165, v219, v98
	v_cvt_pk_bf16_f32 v98, v150, v152
	v_cvt_pk_bf16_f32 v99, v154, v156
	v_cvt_pk_bf16_f32 v100, v151, v153
	v_cvt_pk_bf16_f32 v101, v155, v157
	v_lshl_add_u64 v[104:105], v[104:105], 0, v[126:127]
	v_addc_co_u32_e32 v103, vcc, 0, v103, vcc
	global_store_dwordx4 v[104:105], v[98:101], off
	s_nop 1
	v_cvt_pk_bf16_f32 v98, v158, v160
	v_cvt_pk_bf16_f32 v99, v162, v164
	v_cvt_pk_bf16_f32 v100, v159, v161
	v_cvt_pk_bf16_f32 v101, v163, v165
	global_store_dwordx4 v[102:103], v[98:101], off offset:320
.LBB0_835:
	s_andn2_b64 vcc, exec, s[0:1]
	s_cbranch_vccnz .LBB0_852
	v_mad_i64_i32 v[150:151], s[0:1], v114, s33, v[122:123]
	s_cmp_gt_i32 s71, 8
	s_mov_b64 s[0:1], -1
	s_cbranch_scc1 .LBB0_842
	s_cmp_lt_u32 s73, 5
	s_cselect_b64 s[0:1], -1, 0
	s_cmp_gt_u32 s73, 4
	s_cbranch_scc0 .LBB0_842
	s_andn2_b64 vcc, exec, s[28:29]
	s_mov_b64 s[4:5], -1
	s_cbranch_vccnz .LBB0_840
	v_lshl_add_u64 v[102:103], v[122:123], 2, s[16:17]
	s_nop 0
	s_nop 0
	s_nop 0
	v_mul_f32_e32 v115, 0x3fb8aa3b, v148
	v_exp_f32_e32 v115, v115
	s_mov_b32 s4, 0x800000
	s_mov_b32 s5, 0x3f317217
	s_mov_b32 s76, 0x7f800000
	v_add_f32_e32 v115, 1.0, v115
	v_rcp_f32_e32 v115, v115
	v_lshl_add_u64 v[152:153], v[150:151], 2, s[86:87]
	s_nop 0
	v_mul_f32_e32 v102, v115, v220
	v_mul_f32_e32 v115, 0x3fb8aa3b, v118
	v_exp_f32_e32 v115, v115
	v_min_f32_e32 v102, 0x3f7fffef, v102
	v_add_f32_e32 v115, 1.0, v115
	v_rcp_f32_e32 v115, v115
	s_nop 0
	v_mul_f32_e32 v98, v115, v224
	v_min_f32_e32 v115, 0x3f7fffef, v98
	v_sub_f32_e32 v98, 1.0, v102
	v_cmp_gt_f32_e32 vcc, s4, v98
	s_nop 1
	v_cndmask_b32_e64 v102, 0, 32, vcc
	v_ldexp_f32 v98, v98, v102
	v_log_f32_e32 v98, v98
	s_nop 0
	v_mul_f32_e32 v102, 0x3f317217, v98
	v_fma_f32 v102, v98, s5, -v102
	v_fmac_f32_e32 v102, 0x3377d1cf, v98
	v_fmac_f32_e32 v102, 0x3f317217, v98
	v_cmp_lt_f32_e64 s[12:13], |v98|, s76
	s_nop 1
	v_cndmask_b32_e64 v98, v98, v102, s[12:13]
	v_cndmask_b32_e32 v102, 0, v199, vcc
	v_sub_f32_e32 v98, v98, v102
	v_sub_f32_e32 v102, 1.0, v115
	v_cmp_gt_f32_e32 vcc, s4, v102
	s_nop 1
	v_cndmask_b32_e64 v115, 0, 32, vcc
	v_ldexp_f32 v102, v102, v115
	v_log_f32_e32 v102, v102
	s_nop 0
	v_mul_f32_e32 v115, 0x3f317217, v102
	v_fma_f32 v115, v102, s5, -v115
	v_fmac_f32_e32 v115, 0x3377d1cf, v102
	v_fmac_f32_e32 v115, 0x3f317217, v102
	v_cmp_lt_f32_e64 s[12:13], |v102|, s76
	s_nop 1
	v_cndmask_b32_e64 v102, v102, v115, s[12:13]
	v_cndmask_b32_e32 v115, 0, v199, vcc
	v_sub_f32_e32 v102, v102, v115
	v_mul_f32_e32 v115, 0x3fb8aa3b, v149
	v_exp_f32_e32 v115, v115
	s_nop 0
	v_add_f32_e32 v115, 1.0, v115
	v_rcp_f32_e32 v115, v115
	s_nop 0
	v_mul_f32_e32 v103, v115, v221
	v_mul_f32_e32 v115, 0x3fb8aa3b, v119
	v_exp_f32_e32 v115, v115
	v_min_f32_e32 v103, 0x3f7fffef, v103
	v_add_f32_e32 v115, 1.0, v115
	v_rcp_f32_e32 v115, v115
	s_nop 0
	v_mul_f32_e32 v99, v115, v225
	v_min_f32_e32 v115, 0x3f7fffef, v99
	v_sub_f32_e32 v99, 1.0, v103
	v_cmp_gt_f32_e32 vcc, s4, v99
	s_nop 1
	v_cndmask_b32_e64 v103, 0, 32, vcc
	v_ldexp_f32 v99, v99, v103
	v_log_f32_e32 v99, v99
	s_nop 0
	v_mul_f32_e32 v103, 0x3f317217, v99
	v_fma_f32 v103, v99, s5, -v103
	v_fmac_f32_e32 v103, 0x3377d1cf, v99
	v_fmac_f32_e32 v103, 0x3f317217, v99
	v_cmp_lt_f32_e64 s[12:13], |v99|, s76
	s_nop 1
	v_cndmask_b32_e64 v99, v99, v103, s[12:13]
	v_cndmask_b32_e32 v103, 0, v199, vcc
	v_sub_f32_e32 v99, v99, v103
	v_sub_f32_e32 v103, 1.0, v115
	v_cmp_gt_f32_e32 vcc, s4, v103
	s_nop 1
	v_cndmask_b32_e64 v115, 0, 32, vcc
	v_ldexp_f32 v103, v103, v115
	v_log_f32_e32 v103, v103
	s_nop 0
	v_mul_f32_e32 v115, 0x3f317217, v103
	v_fma_f32 v115, v103, s5, -v115
	v_fmac_f32_e32 v115, 0x3377d1cf, v103
	v_fmac_f32_e32 v115, 0x3f317217, v103
	v_cmp_lt_f32_e64 s[12:13], |v103|, s76
	s_nop 1
	v_cndmask_b32_e64 v103, v103, v115, s[12:13]
	v_cndmask_b32_e32 v115, 0, v199, vcc
	v_sub_f32_e32 v103, v103, v115
	v_mul_f32_e32 v115, 0x3fb8aa3b, v120
	v_exp_f32_e32 v115, v115
	s_nop 0
	v_add_f32_e32 v115, 1.0, v115
	v_rcp_f32_e32 v115, v115
	s_nop 0
	v_mul_f32_e32 v104, v115, v222
	v_mul_f32_e32 v115, 0x3fb8aa3b, v116
	v_exp_f32_e32 v115, v115
	v_min_f32_e32 v104, 0x3f7fffef, v104
	v_add_f32_e32 v115, 1.0, v115
	v_rcp_f32_e32 v115, v115
	s_nop 0
	v_mul_f32_e32 v100, v115, v226
	v_min_f32_e32 v115, 0x3f7fffef, v100
	v_sub_f32_e32 v100, 1.0, v104
	v_cmp_gt_f32_e32 vcc, s4, v100
	s_nop 1
	v_cndmask_b32_e64 v104, 0, 32, vcc
	v_ldexp_f32 v100, v100, v104
	v_log_f32_e32 v100, v100
	s_nop 0
	v_mul_f32_e32 v104, 0x3f317217, v100
	v_fma_f32 v104, v100, s5, -v104
	v_fmac_f32_e32 v104, 0x3377d1cf, v100
	v_fmac_f32_e32 v104, 0x3f317217, v100
	v_cmp_lt_f32_e64 s[12:13], |v100|, s76
	s_nop 1
	v_cndmask_b32_e64 v100, v100, v104, s[12:13]
	v_cndmask_b32_e32 v104, 0, v199, vcc
	v_sub_f32_e32 v100, v100, v104
	v_sub_f32_e32 v104, 1.0, v115
	v_cmp_gt_f32_e32 vcc, s4, v104
	s_nop 1
	v_cndmask_b32_e64 v115, 0, 32, vcc
	v_ldexp_f32 v104, v104, v115
	v_log_f32_e32 v104, v104
	s_nop 0
	v_mul_f32_e32 v115, 0x3f317217, v104
	v_fma_f32 v115, v104, s5, -v115
	v_fmac_f32_e32 v115, 0x3377d1cf, v104
	v_fmac_f32_e32 v115, 0x3f317217, v104
	v_cmp_lt_f32_e64 s[12:13], |v104|, s76
	s_nop 1
	v_cndmask_b32_e64 v104, v104, v115, s[12:13]
	v_cndmask_b32_e32 v115, 0, v199, vcc
	v_sub_f32_e32 v104, v104, v115
	v_mul_f32_e32 v115, 0x3fb8aa3b, v121
	v_exp_f32_e32 v115, v115
	s_nop 0
	v_add_f32_e32 v115, 1.0, v115
	v_rcp_f32_e32 v115, v115
	s_nop 0
	v_mul_f32_e32 v105, v115, v223
	v_mul_f32_e32 v115, 0x3fb8aa3b, v117
	v_exp_f32_e32 v115, v115
	v_min_f32_e32 v105, 0x3f7fffef, v105
	v_add_f32_e32 v115, 1.0, v115
	v_rcp_f32_e32 v115, v115
	s_nop 0
	v_mul_f32_e32 v101, v115, v227
	v_min_f32_e32 v115, 0x3f7fffef, v101
	v_sub_f32_e32 v101, 1.0, v105
	v_cmp_gt_f32_e32 vcc, s4, v101
	s_nop 1
	v_cndmask_b32_e64 v105, 0, 32, vcc
	v_ldexp_f32 v101, v101, v105
	v_log_f32_e32 v101, v101
	s_nop 0
	v_mul_f32_e32 v105, 0x3f317217, v101
	v_fma_f32 v105, v101, s5, -v105
	v_fmac_f32_e32 v105, 0x3377d1cf, v101
	v_fmac_f32_e32 v105, 0x3f317217, v101
	v_cmp_lt_f32_e64 s[12:13], |v101|, s76
	s_nop 1
	v_cndmask_b32_e64 v101, v101, v105, s[12:13]
	v_cndmask_b32_e32 v105, 0, v199, vcc
	v_sub_f32_e32 v101, v101, v105
	v_sub_f32_e32 v105, 1.0, v115
	v_cmp_gt_f32_e32 vcc, s4, v105
	s_nop 1
	v_cndmask_b32_e64 v115, 0, 32, vcc
	v_ldexp_f32 v105, v105, v115
	v_log_f32_e32 v105, v105
	s_nop 0
	v_mul_f32_e32 v115, 0x3f317217, v105
	v_fma_f32 v115, v105, s5, -v115
	v_fmac_f32_e32 v115, 0x3377d1cf, v105
	v_fmac_f32_e32 v115, 0x3f317217, v105
	v_cmp_lt_f32_e64 s[12:13], |v105|, s76
	s_mov_b64 s[4:5], 0
	s_nop 0
	v_cndmask_b32_e64 v105, v105, v115, s[12:13]
	v_cndmask_b32_e32 v115, 0, v199, vcc
	v_sub_f32_e32 v105, v105, v115
	global_store_dwordx4 v[152:153], v[98:101], off
	global_store_dwordx4 v[152:153], v[102:105], off offset:16

.LBB0_844:
	s_nop 1
	v_mad_i64_i32 v[98:99], s[0:1], v114, s33, 0
	v_lshl_add_u64 v[114:115], v[98:99], 0, v[124:125]
	s_cmp_gt_i32 s71, 8
	s_mov_b64 s[0:1], -1
	s_cbranch_scc1 .LBB0_850
	s_cmp_lt_u32 s73, 5
	s_cselect_b64 s[0:1], -1, 0
	s_cmp_gt_u32 s73, 4
	s_cbranch_scc0 .LBB0_850
	s_andn2_b64 vcc, exec, s[28:29]
	s_mov_b64 s[4:5], -1
	s_cbranch_vccnz .LBB0_848
	v_lshl_add_u64 v[102:103], v[122:123], 2, s[16:17]
	s_nop 0
	s_nop 0
	s_nop 0
	v_mul_f32_e32 v116, 0x3fb8aa3b, v112
	v_exp_f32_e32 v116, v116
	s_mov_b32 s4, 0x800000
	s_mov_b32 s5, 0x3f317217
	s_mov_b32 s76, 0x7f800000
	v_add_f32_e32 v116, 1.0, v116
	v_rcp_f32_e32 v116, v116
	s_nop 0
	v_mul_f32_e32 v102, v116, v228
	v_mul_f32_e32 v116, 0x3fb8aa3b, v108
	v_exp_f32_e32 v116, v116
	v_min_f32_e32 v102, 0x3f7fffef, v102
	v_add_f32_e32 v116, 1.0, v116
	v_rcp_f32_e32 v116, v116
	s_nop 0
	v_mul_f32_e32 v98, v116, v232
	v_min_f32_e32 v116, 0x3f7fffef, v98
	v_sub_f32_e32 v98, 1.0, v102
	v_cmp_gt_f32_e32 vcc, s4, v98
	s_nop 1
	v_cndmask_b32_e64 v102, 0, 32, vcc
	v_ldexp_f32 v98, v98, v102
	v_log_f32_e32 v98, v98
	s_nop 0
	v_mul_f32_e32 v102, 0x3f317217, v98
	v_fma_f32 v102, v98, s5, -v102
	v_fmac_f32_e32 v102, 0x3377d1cf, v98
	v_fmac_f32_e32 v102, 0x3f317217, v98
	v_cmp_lt_f32_e64 s[12:13], |v98|, s76
	s_nop 1
	v_cndmask_b32_e64 v98, v98, v102, s[12:13]
	v_cndmask_b32_e32 v102, 0, v199, vcc
	v_sub_f32_e32 v98, v98, v102
	v_sub_f32_e32 v102, 1.0, v116
	v_cmp_gt_f32_e32 vcc, s4, v102
	s_nop 1
	v_cndmask_b32_e64 v116, 0, 32, vcc
	v_ldexp_f32 v102, v102, v116
	v_log_f32_e32 v102, v102
	s_nop 0
	v_mul_f32_e32 v116, 0x3f317217, v102
	v_fma_f32 v116, v102, s5, -v116
	v_fmac_f32_e32 v116, 0x3377d1cf, v102
	v_fmac_f32_e32 v116, 0x3f317217, v102
	v_cmp_lt_f32_e64 s[12:13], |v102|, s76
	s_nop 1
	v_cndmask_b32_e64 v102, v102, v116, s[12:13]
	v_cndmask_b32_e32 v116, 0, v199, vcc
	v_sub_f32_e32 v102, v102, v116
	v_mul_f32_e32 v116, 0x3fb8aa3b, v113
	v_exp_f32_e32 v116, v116
	s_nop 0
	v_add_f32_e32 v116, 1.0, v116
	v_rcp_f32_e32 v116, v116
	s_nop 0
	v_mul_f32_e32 v103, v116, v229
	v_mul_f32_e32 v116, 0x3fb8aa3b, v109
	v_exp_f32_e32 v116, v116
	v_min_f32_e32 v103, 0x3f7fffef, v103
	v_add_f32_e32 v116, 1.0, v116
	v_rcp_f32_e32 v116, v116
	s_nop 0
	v_mul_f32_e32 v99, v116, v233
	v_min_f32_e32 v116, 0x3f7fffef, v99
	v_sub_f32_e32 v99, 1.0, v103
	v_cmp_gt_f32_e32 vcc, s4, v99
	s_nop 1
	v_cndmask_b32_e64 v103, 0, 32, vcc
	v_ldexp_f32 v99, v99, v103
	v_log_f32_e32 v99, v99
	s_nop 0
	v_mul_f32_e32 v103, 0x3f317217, v99
	v_fma_f32 v103, v99, s5, -v103
	v_fmac_f32_e32 v103, 0x3377d1cf, v99
	v_fmac_f32_e32 v103, 0x3f317217, v99
	v_cmp_lt_f32_e64 s[12:13], |v99|, s76
	s_nop 1
	v_cndmask_b32_e64 v99, v99, v103, s[12:13]
	v_cndmask_b32_e32 v103, 0, v199, vcc
	v_sub_f32_e32 v99, v99, v103
	v_sub_f32_e32 v103, 1.0, v116
	v_cmp_gt_f32_e32 vcc, s4, v103
	s_nop 1
	v_cndmask_b32_e64 v116, 0, 32, vcc
	v_ldexp_f32 v103, v103, v116
	v_log_f32_e32 v103, v103
	s_nop 0
	v_mul_f32_e32 v116, 0x3f317217, v103
	v_fma_f32 v116, v103, s5, -v116
	v_fmac_f32_e32 v116, 0x3377d1cf, v103
	v_fmac_f32_e32 v116, 0x3f317217, v103
	v_cmp_lt_f32_e64 s[12:13], |v103|, s76
	s_nop 1
	v_cndmask_b32_e64 v103, v103, v116, s[12:13]
	v_cndmask_b32_e32 v116, 0, v199, vcc
	v_sub_f32_e32 v103, v103, v116
	v_mul_f32_e32 v116, 0x3fb8aa3b, v110
	v_exp_f32_e32 v116, v116
	s_nop 0
	v_add_f32_e32 v116, 1.0, v116
	v_rcp_f32_e32 v116, v116
	s_nop 0
	v_mul_f32_e32 v104, v116, v230
	v_mul_f32_e32 v116, 0x3fb8aa3b, v106
	v_exp_f32_e32 v116, v116
	v_min_f32_e32 v104, 0x3f7fffef, v104
	v_add_f32_e32 v116, 1.0, v116
	v_rcp_f32_e32 v116, v116
	s_nop 0
	v_mul_f32_e32 v100, v116, v234
	v_min_f32_e32 v116, 0x3f7fffef, v100
	v_sub_f32_e32 v100, 1.0, v104
	v_cmp_gt_f32_e32 vcc, s4, v100
	s_nop 1
	v_cndmask_b32_e64 v104, 0, 32, vcc
	v_ldexp_f32 v100, v100, v104
	v_log_f32_e32 v100, v100
	s_nop 0
	v_mul_f32_e32 v104, 0x3f317217, v100
	v_fma_f32 v104, v100, s5, -v104
	v_fmac_f32_e32 v104, 0x3377d1cf, v100
	v_fmac_f32_e32 v104, 0x3f317217, v100
	v_cmp_lt_f32_e64 s[12:13], |v100|, s76
	s_nop 1
	v_cndmask_b32_e64 v100, v100, v104, s[12:13]
	v_cndmask_b32_e32 v104, 0, v199, vcc
	v_sub_f32_e32 v100, v100, v104
	v_sub_f32_e32 v104, 1.0, v116
	v_cmp_gt_f32_e32 vcc, s4, v104
	s_nop 1
	v_cndmask_b32_e64 v116, 0, 32, vcc
	v_ldexp_f32 v104, v104, v116
	v_log_f32_e32 v104, v104
	s_nop 0
	v_mul_f32_e32 v116, 0x3f317217, v104
	v_fma_f32 v116, v104, s5, -v116
	v_fmac_f32_e32 v116, 0x3377d1cf, v104
	v_fmac_f32_e32 v116, 0x3f317217, v104
	v_cmp_lt_f32_e64 s[12:13], |v104|, s76
	s_nop 1
	v_cndmask_b32_e64 v104, v104, v116, s[12:13]
	v_cndmask_b32_e32 v116, 0, v199, vcc
	v_sub_f32_e32 v104, v104, v116
	v_mul_f32_e32 v116, 0x3fb8aa3b, v111
	v_exp_f32_e32 v116, v116
	s_nop 0
	v_add_f32_e32 v116, 1.0, v116
	v_rcp_f32_e32 v116, v116
	s_nop 0
	v_mul_f32_e32 v105, v116, v231
	v_mul_f32_e32 v116, 0x3fb8aa3b, v107
	v_exp_f32_e32 v116, v116
	v_min_f32_e32 v105, 0x3f7fffef, v105
	v_add_f32_e32 v116, 1.0, v116
	v_rcp_f32_e32 v116, v116
	s_nop 0
	v_mul_f32_e32 v101, v116, v235
	v_min_f32_e32 v116, 0x3f7fffef, v101
	v_sub_f32_e32 v101, 1.0, v105
	v_cmp_gt_f32_e32 vcc, s4, v101
	s_nop 1
	v_cndmask_b32_e64 v105, 0, 32, vcc
	v_ldexp_f32 v101, v101, v105
	v_log_f32_e32 v101, v101
	s_nop 0
	v_mul_f32_e32 v105, 0x3f317217, v101
	v_fma_f32 v105, v101, s5, -v105
	v_fmac_f32_e32 v105, 0x3377d1cf, v101
	v_fmac_f32_e32 v105, 0x3f317217, v101
	v_cmp_lt_f32_e64 s[12:13], |v101|, s76
	s_nop 1
	v_cndmask_b32_e64 v101, v101, v105, s[12:13]
	v_cndmask_b32_e32 v105, 0, v199, vcc
	v_sub_f32_e32 v101, v101, v105
	v_sub_f32_e32 v105, 1.0, v116
	v_cmp_gt_f32_e32 vcc, s4, v105
	s_nop 1
	v_cndmask_b32_e64 v116, 0, 32, vcc
	v_ldexp_f32 v105, v105, v116
	v_log_f32_e32 v105, v105
	s_nop 0
	v_mul_f32_e32 v116, 0x3f317217, v105
	v_fma_f32 v116, v105, s5, -v116
	v_fmac_f32_e32 v116, 0x3377d1cf, v105
	v_fmac_f32_e32 v116, 0x3f317217, v105
	v_cmp_lt_f32_e64 s[12:13], |v105|, s76
	s_mov_b64 s[4:5], 0
	s_nop 0
	v_cndmask_b32_e64 v105, v105, v116, s[12:13]
	v_cndmask_b32_e32 v116, 0, v199, vcc
	v_sub_f32_e32 v105, v105, v116
	v_lshl_add_u64 v[116:117], v[114:115], 2, s[86:87]
	global_store_dwordx4 v[116:117], v[98:101], off
	global_store_dwordx4 v[116:117], v[102:105], off offset:16

.LBB0_852:
	v_pk_mul_f32 v[104:105], v[96:97], v[146:147] op_sel_hi:[1,0]
	v_pk_mul_f32 v[106:107], v[94:95], v[146:147] op_sel_hi:[1,0]
	v_pk_mul_f32 v[100:101], v[92:93], v[146:147] op_sel_hi:[1,0]
	v_pk_mul_f32 v[102:103], v[90:91], v[146:147] op_sel_hi:[1,0]
	v_pk_mul_f32 v[94:95], v[88:89], v[146:147] op_sel_hi:[1,0]
	v_pk_mul_f32 v[96:97], v[86:87], v[146:147] op_sel_hi:[1,0]
	v_pk_mul_f32 v[90:91], v[84:85], v[146:147] op_sel_hi:[1,0]
	v_pk_mul_f32 v[92:93], v[82:83], v[146:147] op_sel_hi:[1,0]
	v_add_u32_e32 v98, s91, v175
	s_and_b64 vcc, exec, s[10:11]
	s_mov_b64 s[0:1], -1
	s_cbranch_vccnz .LBB0_854
	v_mul_f32_e32 v84, v107, v107
	v_fmac_f32_e32 v84, v106, v106
	v_fmac_f32_e32 v84, v104, v104
	v_fmac_f32_e32 v84, v105, v105
	v_fmac_f32_e32 v84, v102, v102
	v_fmac_f32_e32 v84, v103, v103
	v_fmac_f32_e32 v84, v100, v100
	v_fmac_f32_e32 v84, v101, v101
	v_fmac_f32_e32 v84, v96, v96
	v_fmac_f32_e32 v84, v97, v97
	v_fmac_f32_e32 v84, v94, v94
	v_fmac_f32_e32 v84, v95, v95
	v_fmac_f32_e32 v84, v92, v92
	v_fmac_f32_e32 v84, v93, v93
	v_pk_mul_f32 v[82:83], v[90:91], v[90:91]
	s_mov_b64 s[0:1], 0
	v_add_f32_e32 v82, v82, v84
	v_add_f32_e32 v82, v83, v82
	ds_bpermute_b32 v83, v174, v82
	s_waitcnt lgkmcnt(0)
	v_add_f32_e32 v82, v82, v83
	ds_bpermute_b32 v83, v173, v82
	s_waitcnt lgkmcnt(0)
	v_add_f32_e32 v82, v82, v83
	v_fmamk_f32 v82, v82, 0x3c800000, v188
	v_rsq_f32_e32 v82, v82
	s_nop 0
	v_mul_f32_e32 v99, 0x3e38aa3b, v82
	s_nop 0
	s_nop 0
	v_mul_f32_e32 v108, v106, v99
	v_mul_f32_e32 v116, v96, v99
	s_nop 0
	v_mul_f32_e32 v108, v204, v108
	v_mul_f32_e32 v86, v102, v99
	v_mul_f32_e32 v109, v208, v86
	v_mul_f32_e32 v82, v107, v99
	v_mul_f32_e32 v110, v205, v82
	v_mul_f32_e32 v82, v103, v99
	v_mul_f32_e32 v111, v209, v82
	v_mul_f32_e32 v82, v104, v99
	v_mul_f32_e32 v112, v206, v82
	v_mul_f32_e32 v82, v100, v99
	v_mul_f32_e32 v113, v210, v82
	v_mul_f32_e32 v82, v105, v99
	v_mul_f32_e32 v114, v207, v82
	v_mul_f32_e32 v82, v101, v99
	v_mul_f32_e32 v115, v211, v82
	s_nop 0
	s_nop 0
	s_nop 0
	v_mul_f32_e32 v116, v212, v116
	v_mul_f32_e32 v86, v92, v99
	v_mul_f32_e32 v117, v216, v86
	v_mul_f32_e32 v82, v97, v99
	v_mul_f32_e32 v118, v213, v82
	v_mul_f32_e32 v82, v93, v99
	v_mul_f32_e32 v119, v217, v82
	v_mul_f32_e32 v82, v94, v99
	v_mul_f32_e32 v120, v214, v82
	v_mul_f32_e32 v82, v90, v99
	v_mul_f32_e32 v121, v218, v82
	v_mul_f32_e32 v82, v95, v99
	v_mul_f32_e32 v146, v215, v82
	v_mul_f32_e32 v82, v91, v99
	v_ashrrev_i32_e32 v99, 31, v98
	v_lshlrev_b64 v[86:87], 9, v[98:99]
	v_lshl_add_u64 v[88:89], s[18:19], 0, v[86:87]
	v_lshl_add_u64 v[86:87], s[20:21], 0, v[86:87]
	v_lshl_add_u64 v[86:87], v[86:87], 0, v[126:127]
	v_add_co_u32_e32 v86, vcc, 0x3b6e9000, v86
	v_mul_f32_e32 v148, v219, v82
	v_cvt_pk_bf16_f32 v82, v108, v110
	v_cvt_pk_bf16_f32 v83, v112, v114
	v_cvt_pk_bf16_f32 v84, v109, v111
	v_cvt_pk_bf16_f32 v85, v113, v115
	v_lshl_add_u64 v[88:89], v[88:89], 0, v[126:127]
	v_addc_co_u32_e32 v87, vcc, 0, v87, vcc
	global_store_dwordx4 v[88:89], v[82:85], off
	s_nop 1
	v_cvt_pk_bf16_f32 v82, v116, v118
	v_cvt_pk_bf16_f32 v83, v120, v146
	v_cvt_pk_bf16_f32 v84, v117, v119
	v_cvt_pk_bf16_f32 v85, v121, v148
	global_store_dwordx4 v[86:87], v[82:85], off offset:320
.LBB0_854:
	s_andn2_b64 vcc, exec, s[0:1]
	s_cbranch_vccnz .LBB0_871
	v_mad_i64_i32 v[108:109], s[0:1], v98, s33, v[122:123]
	s_cmp_gt_i32 s71, 8
	s_mov_b64 s[0:1], -1
	s_cbranch_scc1 .LBB0_861
	s_cmp_lt_u32 s73, 5
	s_cselect_b64 s[0:1], -1, 0
	s_cmp_gt_u32 s73, 4
	s_cbranch_scc0 .LBB0_861
	s_andn2_b64 vcc, exec, s[28:29]
	s_mov_b64 s[4:5], -1
	s_cbranch_vccnz .LBB0_859
	v_lshl_add_u64 v[86:87], v[122:123], 2, s[16:17]
	s_nop 0
	s_nop 0
	s_nop 0
	v_mul_f32_e32 v99, 0x3fb8aa3b, v106
	v_exp_f32_e32 v99, v99
	s_mov_b32 s4, 0x800000
	s_mov_b32 s5, 0x3f317217
	s_mov_b32 s76, 0x7f800000
	v_add_f32_e32 v99, 1.0, v99
	v_rcp_f32_e32 v99, v99
	v_lshl_add_u64 v[110:111], v[108:109], 2, s[86:87]
	s_nop 0
	v_mul_f32_e32 v86, v99, v220
	v_mul_f32_e32 v99, 0x3fb8aa3b, v102
	v_exp_f32_e32 v99, v99
	v_min_f32_e32 v86, 0x3f7fffef, v86
	v_add_f32_e32 v99, 1.0, v99
	v_rcp_f32_e32 v99, v99
	s_nop 0
	v_mul_f32_e32 v82, v99, v224
	v_min_f32_e32 v99, 0x3f7fffef, v82
	v_sub_f32_e32 v82, 1.0, v86
	v_cmp_gt_f32_e32 vcc, s4, v82
	s_nop 1
	v_cndmask_b32_e64 v86, 0, 32, vcc
	v_ldexp_f32 v82, v82, v86
	v_log_f32_e32 v82, v82
	s_nop 0
	v_mul_f32_e32 v86, 0x3f317217, v82
	v_fma_f32 v86, v82, s5, -v86
	v_fmac_f32_e32 v86, 0x3377d1cf, v82
	v_fmac_f32_e32 v86, 0x3f317217, v82
	v_cmp_lt_f32_e64 s[12:13], |v82|, s76
	s_nop 1
	v_cndmask_b32_e64 v82, v82, v86, s[12:13]
	v_cndmask_b32_e32 v86, 0, v199, vcc
	v_sub_f32_e32 v82, v82, v86
	v_sub_f32_e32 v86, 1.0, v99
	v_cmp_gt_f32_e32 vcc, s4, v86
	s_nop 1
	v_cndmask_b32_e64 v99, 0, 32, vcc
	v_ldexp_f32 v86, v86, v99
	v_log_f32_e32 v86, v86
	s_nop 0
	v_mul_f32_e32 v99, 0x3f317217, v86
	v_fma_f32 v99, v86, s5, -v99
	v_fmac_f32_e32 v99, 0x3377d1cf, v86
	v_fmac_f32_e32 v99, 0x3f317217, v86
	v_cmp_lt_f32_e64 s[12:13], |v86|, s76
	s_nop 1
	v_cndmask_b32_e64 v86, v86, v99, s[12:13]
	v_cndmask_b32_e32 v99, 0, v199, vcc
	v_sub_f32_e32 v86, v86, v99
	v_mul_f32_e32 v99, 0x3fb8aa3b, v107
	v_exp_f32_e32 v99, v99
	s_nop 0
	v_add_f32_e32 v99, 1.0, v99
	v_rcp_f32_e32 v99, v99
	s_nop 0
	v_mul_f32_e32 v87, v99, v221
	v_mul_f32_e32 v99, 0x3fb8aa3b, v103
	v_exp_f32_e32 v99, v99
	v_min_f32_e32 v87, 0x3f7fffef, v87
	v_add_f32_e32 v99, 1.0, v99
	v_rcp_f32_e32 v99, v99
	s_nop 0
	v_mul_f32_e32 v83, v99, v225
	v_min_f32_e32 v99, 0x3f7fffef, v83
	v_sub_f32_e32 v83, 1.0, v87
	v_cmp_gt_f32_e32 vcc, s4, v83
	s_nop 1
	v_cndmask_b32_e64 v87, 0, 32, vcc
	v_ldexp_f32 v83, v83, v87
	v_log_f32_e32 v83, v83
	s_nop 0
	v_mul_f32_e32 v87, 0x3f317217, v83
	v_fma_f32 v87, v83, s5, -v87
	v_fmac_f32_e32 v87, 0x3377d1cf, v83
	v_fmac_f32_e32 v87, 0x3f317217, v83
	v_cmp_lt_f32_e64 s[12:13], |v83|, s76
	s_nop 1
	v_cndmask_b32_e64 v83, v83, v87, s[12:13]
	v_cndmask_b32_e32 v87, 0, v199, vcc
	v_sub_f32_e32 v83, v83, v87
	v_sub_f32_e32 v87, 1.0, v99
	v_cmp_gt_f32_e32 vcc, s4, v87
	s_nop 1
	v_cndmask_b32_e64 v99, 0, 32, vcc
	v_ldexp_f32 v87, v87, v99
	v_log_f32_e32 v87, v87
	s_nop 0
	v_mul_f32_e32 v99, 0x3f317217, v87
	v_fma_f32 v99, v87, s5, -v99
	v_fmac_f32_e32 v99, 0x3377d1cf, v87
	v_fmac_f32_e32 v99, 0x3f317217, v87
	v_cmp_lt_f32_e64 s[12:13], |v87|, s76
	s_nop 1
	v_cndmask_b32_e64 v87, v87, v99, s[12:13]
	v_cndmask_b32_e32 v99, 0, v199, vcc
	v_sub_f32_e32 v87, v87, v99
	v_mul_f32_e32 v99, 0x3fb8aa3b, v104
	v_exp_f32_e32 v99, v99
	s_nop 0
	v_add_f32_e32 v99, 1.0, v99
	v_rcp_f32_e32 v99, v99
	s_nop 0
	v_mul_f32_e32 v88, v99, v222
	v_mul_f32_e32 v99, 0x3fb8aa3b, v100
	v_exp_f32_e32 v99, v99
	v_min_f32_e32 v88, 0x3f7fffef, v88
	v_add_f32_e32 v99, 1.0, v99
	v_rcp_f32_e32 v99, v99
	s_nop 0
	v_mul_f32_e32 v84, v99, v226
	v_min_f32_e32 v99, 0x3f7fffef, v84
	v_sub_f32_e32 v84, 1.0, v88
	v_cmp_gt_f32_e32 vcc, s4, v84
	s_nop 1
	v_cndmask_b32_e64 v88, 0, 32, vcc
	v_ldexp_f32 v84, v84, v88
	v_log_f32_e32 v84, v84
	s_nop 0
	v_mul_f32_e32 v88, 0x3f317217, v84
	v_fma_f32 v88, v84, s5, -v88
	v_fmac_f32_e32 v88, 0x3377d1cf, v84
	v_fmac_f32_e32 v88, 0x3f317217, v84
	v_cmp_lt_f32_e64 s[12:13], |v84|, s76
	s_nop 1
	v_cndmask_b32_e64 v84, v84, v88, s[12:13]
	v_cndmask_b32_e32 v88, 0, v199, vcc
	v_sub_f32_e32 v84, v84, v88
	v_sub_f32_e32 v88, 1.0, v99
	v_cmp_gt_f32_e32 vcc, s4, v88
	s_nop 1
	v_cndmask_b32_e64 v99, 0, 32, vcc
	v_ldexp_f32 v88, v88, v99
	v_log_f32_e32 v88, v88
	s_nop 0
	v_mul_f32_e32 v99, 0x3f317217, v88
	v_fma_f32 v99, v88, s5, -v99
	v_fmac_f32_e32 v99, 0x3377d1cf, v88
	v_fmac_f32_e32 v99, 0x3f317217, v88
	v_cmp_lt_f32_e64 s[12:13], |v88|, s76
	s_nop 1
	v_cndmask_b32_e64 v88, v88, v99, s[12:13]
	v_cndmask_b32_e32 v99, 0, v199, vcc
	v_sub_f32_e32 v88, v88, v99
	v_mul_f32_e32 v99, 0x3fb8aa3b, v105
	v_exp_f32_e32 v99, v99
	s_nop 0
	v_add_f32_e32 v99, 1.0, v99
	v_rcp_f32_e32 v99, v99
	s_nop 0
	v_mul_f32_e32 v89, v99, v223
	v_mul_f32_e32 v99, 0x3fb8aa3b, v101
	v_exp_f32_e32 v99, v99
	v_min_f32_e32 v89, 0x3f7fffef, v89
	v_add_f32_e32 v99, 1.0, v99
	v_rcp_f32_e32 v99, v99
	s_nop 0
	v_mul_f32_e32 v85, v99, v227
	v_min_f32_e32 v99, 0x3f7fffef, v85
	v_sub_f32_e32 v85, 1.0, v89
	v_cmp_gt_f32_e32 vcc, s4, v85
	s_nop 1
	v_cndmask_b32_e64 v89, 0, 32, vcc
	v_ldexp_f32 v85, v85, v89
	v_log_f32_e32 v85, v85
	s_nop 0
	v_mul_f32_e32 v89, 0x3f317217, v85
	v_fma_f32 v89, v85, s5, -v89
	v_fmac_f32_e32 v89, 0x3377d1cf, v85
	v_fmac_f32_e32 v89, 0x3f317217, v85
	v_cmp_lt_f32_e64 s[12:13], |v85|, s76
	s_nop 1
	v_cndmask_b32_e64 v85, v85, v89, s[12:13]
	v_cndmask_b32_e32 v89, 0, v199, vcc
	v_sub_f32_e32 v85, v85, v89
	v_sub_f32_e32 v89, 1.0, v99
	v_cmp_gt_f32_e32 vcc, s4, v89
	s_nop 1
	v_cndmask_b32_e64 v99, 0, 32, vcc
	v_ldexp_f32 v89, v89, v99
	v_log_f32_e32 v89, v89
	s_nop 0
	v_mul_f32_e32 v99, 0x3f317217, v89
	v_fma_f32 v99, v89, s5, -v99
	v_fmac_f32_e32 v99, 0x3377d1cf, v89
	v_fmac_f32_e32 v99, 0x3f317217, v89
	v_cmp_lt_f32_e64 s[12:13], |v89|, s76
	s_mov_b64 s[4:5], 0
	s_nop 0
	v_cndmask_b32_e64 v89, v89, v99, s[12:13]
	v_cndmask_b32_e32 v99, 0, v199, vcc
	v_sub_f32_e32 v89, v89, v99
	global_store_dwordx4 v[110:111], v[82:85], off
	global_store_dwordx4 v[110:111], v[86:89], off offset:16

.LBB0_863:
	s_nop 1
	v_mad_i64_i32 v[82:83], s[0:1], v98, s33, 0
	v_lshl_add_u64 v[98:99], v[82:83], 0, v[124:125]
	s_cmp_gt_i32 s71, 8
	s_mov_b64 s[0:1], -1
	s_cbranch_scc1 .LBB0_869
	s_cmp_lt_u32 s73, 5
	s_cselect_b64 s[0:1], -1, 0
	s_cmp_gt_u32 s73, 4
	s_cbranch_scc0 .LBB0_869
	s_andn2_b64 vcc, exec, s[28:29]
	s_mov_b64 s[4:5], -1
	s_cbranch_vccnz .LBB0_867
	v_lshl_add_u64 v[86:87], v[122:123], 2, s[16:17]
	s_nop 0
	s_nop 0
	s_nop 0
	v_mul_f32_e32 v100, 0x3fb8aa3b, v96
	v_exp_f32_e32 v100, v100
	s_mov_b32 s4, 0x800000
	s_mov_b32 s5, 0x3f317217
	s_mov_b32 s76, 0x7f800000
	v_add_f32_e32 v100, 1.0, v100
	v_rcp_f32_e32 v100, v100
	s_nop 0
	v_mul_f32_e32 v86, v100, v228
	v_mul_f32_e32 v100, 0x3fb8aa3b, v92
	v_exp_f32_e32 v100, v100
	v_min_f32_e32 v86, 0x3f7fffef, v86
	v_add_f32_e32 v100, 1.0, v100
	v_rcp_f32_e32 v100, v100
	s_nop 0
	v_mul_f32_e32 v82, v100, v232
	v_min_f32_e32 v100, 0x3f7fffef, v82
	v_sub_f32_e32 v82, 1.0, v86
	v_cmp_gt_f32_e32 vcc, s4, v82
	s_nop 1
	v_cndmask_b32_e64 v86, 0, 32, vcc
	v_ldexp_f32 v82, v82, v86
	v_log_f32_e32 v82, v82
	s_nop 0
	v_mul_f32_e32 v86, 0x3f317217, v82
	v_fma_f32 v86, v82, s5, -v86
	v_fmac_f32_e32 v86, 0x3377d1cf, v82
	v_fmac_f32_e32 v86, 0x3f317217, v82
	v_cmp_lt_f32_e64 s[12:13], |v82|, s76
	s_nop 1
	v_cndmask_b32_e64 v82, v82, v86, s[12:13]
	v_cndmask_b32_e32 v86, 0, v199, vcc
	v_sub_f32_e32 v82, v82, v86
	v_sub_f32_e32 v86, 1.0, v100
	v_cmp_gt_f32_e32 vcc, s4, v86
	s_nop 1
	v_cndmask_b32_e64 v100, 0, 32, vcc
	v_ldexp_f32 v86, v86, v100
	v_log_f32_e32 v86, v86
	s_nop 0
	v_mul_f32_e32 v100, 0x3f317217, v86
	v_fma_f32 v100, v86, s5, -v100
	v_fmac_f32_e32 v100, 0x3377d1cf, v86
	v_fmac_f32_e32 v100, 0x3f317217, v86
	v_cmp_lt_f32_e64 s[12:13], |v86|, s76
	s_nop 1
	v_cndmask_b32_e64 v86, v86, v100, s[12:13]
	v_cndmask_b32_e32 v100, 0, v199, vcc
	v_sub_f32_e32 v86, v86, v100
	v_mul_f32_e32 v100, 0x3fb8aa3b, v97
	v_exp_f32_e32 v100, v100
	s_nop 0
	v_add_f32_e32 v100, 1.0, v100
	v_rcp_f32_e32 v100, v100
	s_nop 0
	v_mul_f32_e32 v87, v100, v229
	v_mul_f32_e32 v100, 0x3fb8aa3b, v93
	v_exp_f32_e32 v100, v100
	v_min_f32_e32 v87, 0x3f7fffef, v87
	v_add_f32_e32 v100, 1.0, v100
	v_rcp_f32_e32 v100, v100
	s_nop 0
	v_mul_f32_e32 v83, v100, v233
	v_min_f32_e32 v100, 0x3f7fffef, v83
	v_sub_f32_e32 v83, 1.0, v87
	v_cmp_gt_f32_e32 vcc, s4, v83
	s_nop 1
	v_cndmask_b32_e64 v87, 0, 32, vcc
	v_ldexp_f32 v83, v83, v87
	v_log_f32_e32 v83, v83
	s_nop 0
	v_mul_f32_e32 v87, 0x3f317217, v83
	v_fma_f32 v87, v83, s5, -v87
	v_fmac_f32_e32 v87, 0x3377d1cf, v83
	v_fmac_f32_e32 v87, 0x3f317217, v83
	v_cmp_lt_f32_e64 s[12:13], |v83|, s76
	s_nop 1
	v_cndmask_b32_e64 v83, v83, v87, s[12:13]
	v_cndmask_b32_e32 v87, 0, v199, vcc
	v_sub_f32_e32 v83, v83, v87
	v_sub_f32_e32 v87, 1.0, v100
	v_cmp_gt_f32_e32 vcc, s4, v87
	s_nop 1
	v_cndmask_b32_e64 v100, 0, 32, vcc
	v_ldexp_f32 v87, v87, v100
	v_log_f32_e32 v87, v87
	s_nop 0
	v_mul_f32_e32 v100, 0x3f317217, v87
	v_fma_f32 v100, v87, s5, -v100
	v_fmac_f32_e32 v100, 0x3377d1cf, v87
	v_fmac_f32_e32 v100, 0x3f317217, v87
	v_cmp_lt_f32_e64 s[12:13], |v87|, s76
	s_nop 1
	v_cndmask_b32_e64 v87, v87, v100, s[12:13]
	v_cndmask_b32_e32 v100, 0, v199, vcc
	v_sub_f32_e32 v87, v87, v100
	v_mul_f32_e32 v100, 0x3fb8aa3b, v94
	v_exp_f32_e32 v100, v100
	s_nop 0
	v_add_f32_e32 v100, 1.0, v100
	v_rcp_f32_e32 v100, v100
	s_nop 0
	v_mul_f32_e32 v88, v100, v230
	v_mul_f32_e32 v100, 0x3fb8aa3b, v90
	v_exp_f32_e32 v100, v100
	v_min_f32_e32 v88, 0x3f7fffef, v88
	v_add_f32_e32 v100, 1.0, v100
	v_rcp_f32_e32 v100, v100
	s_nop 0
	v_mul_f32_e32 v84, v100, v234
	v_min_f32_e32 v100, 0x3f7fffef, v84
	v_sub_f32_e32 v84, 1.0, v88
	v_cmp_gt_f32_e32 vcc, s4, v84
	s_nop 1
	v_cndmask_b32_e64 v88, 0, 32, vcc
	v_ldexp_f32 v84, v84, v88
	v_log_f32_e32 v84, v84
	s_nop 0
	v_mul_f32_e32 v88, 0x3f317217, v84
	v_fma_f32 v88, v84, s5, -v88
	v_fmac_f32_e32 v88, 0x3377d1cf, v84
	v_fmac_f32_e32 v88, 0x3f317217, v84
	v_cmp_lt_f32_e64 s[12:13], |v84|, s76
	s_nop 1
	v_cndmask_b32_e64 v84, v84, v88, s[12:13]
	v_cndmask_b32_e32 v88, 0, v199, vcc
	v_sub_f32_e32 v84, v84, v88
	v_sub_f32_e32 v88, 1.0, v100
	v_cmp_gt_f32_e32 vcc, s4, v88
	s_nop 1
	v_cndmask_b32_e64 v100, 0, 32, vcc
	v_ldexp_f32 v88, v88, v100
	v_log_f32_e32 v88, v88
	s_nop 0
	v_mul_f32_e32 v100, 0x3f317217, v88
	v_fma_f32 v100, v88, s5, -v100
	v_fmac_f32_e32 v100, 0x3377d1cf, v88
	v_fmac_f32_e32 v100, 0x3f317217, v88
	v_cmp_lt_f32_e64 s[12:13], |v88|, s76
	s_nop 1
	v_cndmask_b32_e64 v88, v88, v100, s[12:13]
	v_cndmask_b32_e32 v100, 0, v199, vcc
	v_sub_f32_e32 v88, v88, v100
	v_mul_f32_e32 v100, 0x3fb8aa3b, v95
	v_exp_f32_e32 v100, v100
	s_nop 0
	v_add_f32_e32 v100, 1.0, v100
	v_rcp_f32_e32 v100, v100
	s_nop 0
	v_mul_f32_e32 v89, v100, v231
	v_mul_f32_e32 v100, 0x3fb8aa3b, v91
	v_exp_f32_e32 v100, v100
	v_min_f32_e32 v89, 0x3f7fffef, v89
	v_add_f32_e32 v100, 1.0, v100
	v_rcp_f32_e32 v100, v100
	s_nop 0
	v_mul_f32_e32 v85, v100, v235
	v_min_f32_e32 v100, 0x3f7fffef, v85
	v_sub_f32_e32 v85, 1.0, v89
	v_cmp_gt_f32_e32 vcc, s4, v85
	s_nop 1
	v_cndmask_b32_e64 v89, 0, 32, vcc
	v_ldexp_f32 v85, v85, v89
	v_log_f32_e32 v85, v85
	s_nop 0
	v_mul_f32_e32 v89, 0x3f317217, v85
	v_fma_f32 v89, v85, s5, -v89
	v_fmac_f32_e32 v89, 0x3377d1cf, v85
	v_fmac_f32_e32 v89, 0x3f317217, v85
	v_cmp_lt_f32_e64 s[12:13], |v85|, s76
	s_nop 1
	v_cndmask_b32_e64 v85, v85, v89, s[12:13]
	v_cndmask_b32_e32 v89, 0, v199, vcc
	v_sub_f32_e32 v85, v85, v89
	v_sub_f32_e32 v89, 1.0, v100
	v_cmp_gt_f32_e32 vcc, s4, v89
	s_nop 1
	v_cndmask_b32_e64 v100, 0, 32, vcc
	v_ldexp_f32 v89, v89, v100
	v_log_f32_e32 v89, v89
	s_nop 0
	v_mul_f32_e32 v100, 0x3f317217, v89
	v_fma_f32 v100, v89, s5, -v100
	v_fmac_f32_e32 v100, 0x3377d1cf, v89
	v_fmac_f32_e32 v100, 0x3f317217, v89
	v_cmp_lt_f32_e64 s[12:13], |v89|, s76
	s_mov_b64 s[4:5], 0
	s_nop 0
	v_cndmask_b32_e64 v89, v89, v100, s[12:13]
	v_cndmask_b32_e32 v100, 0, v199, vcc
	v_sub_f32_e32 v89, v89, v100
	v_lshl_add_u64 v[100:101], v[98:99], 2, s[86:87]
	global_store_dwordx4 v[100:101], v[82:85], off
	global_store_dwordx4 v[100:101], v[86:89], off offset:16

.LBB0_871:
	s_nop 1
	v_mov_b32_e32 v82, v147
	v_pk_mul_f32 v[88:89], v[80:81], v[82:83] op_sel_hi:[1,0]
	v_pk_mul_f32 v[90:91], v[78:79], v[82:83] op_sel_hi:[1,0]
	v_pk_mul_f32 v[84:85], v[76:77], v[82:83] op_sel_hi:[1,0]
	v_pk_mul_f32 v[86:87], v[74:75], v[82:83] op_sel_hi:[1,0]
	v_pk_mul_f32 v[78:79], v[72:73], v[82:83] op_sel_hi:[1,0]
	v_pk_mul_f32 v[80:81], v[70:71], v[82:83] op_sel_hi:[1,0]
	v_pk_mul_f32 v[74:75], v[68:69], v[82:83] op_sel_hi:[1,0]
	v_pk_mul_f32 v[76:77], v[66:67], v[82:83] op_sel_hi:[1,0]
	v_add_u32_e32 v82, s51, v175
	s_and_b64 vcc, exec, s[10:11]
	s_mov_b64 s[0:1], -1
	s_cbranch_vccnz .LBB0_873
	v_mul_f32_e32 v68, v91, v91
	v_fmac_f32_e32 v68, v90, v90
	v_fmac_f32_e32 v68, v88, v88
	v_fmac_f32_e32 v68, v89, v89
	v_fmac_f32_e32 v68, v86, v86
	v_fmac_f32_e32 v68, v87, v87
	v_fmac_f32_e32 v68, v84, v84
	v_fmac_f32_e32 v68, v85, v85
	v_fmac_f32_e32 v68, v80, v80
	v_fmac_f32_e32 v68, v81, v81
	v_fmac_f32_e32 v68, v78, v78
	v_fmac_f32_e32 v68, v79, v79
	v_fmac_f32_e32 v68, v76, v76
	v_fmac_f32_e32 v68, v77, v77
	v_pk_mul_f32 v[66:67], v[74:75], v[74:75]
	s_mov_b64 s[0:1], 0
	v_add_f32_e32 v66, v66, v68
	v_add_f32_e32 v66, v67, v66
	ds_bpermute_b32 v67, v174, v66
	s_waitcnt lgkmcnt(0)
	v_add_f32_e32 v66, v66, v67
	ds_bpermute_b32 v67, v173, v66
	s_waitcnt lgkmcnt(0)
	v_add_f32_e32 v66, v66, v67
	v_fmamk_f32 v66, v66, 0x3c800000, v188
	v_rsq_f32_e32 v66, v66
	s_nop 0
	v_mul_f32_e32 v83, 0x3e38aa3b, v66
	s_nop 0
	s_nop 0
	v_mul_f32_e32 v92, v90, v83
	v_mul_f32_e32 v100, v80, v83
	s_nop 0
	v_mul_f32_e32 v92, v204, v92
	v_mul_f32_e32 v70, v86, v83
	v_mul_f32_e32 v93, v208, v70
	v_mul_f32_e32 v66, v91, v83
	v_mul_f32_e32 v94, v205, v66
	v_mul_f32_e32 v66, v87, v83
	v_mul_f32_e32 v95, v209, v66
	v_mul_f32_e32 v66, v88, v83
	v_mul_f32_e32 v96, v206, v66
	v_mul_f32_e32 v66, v84, v83
	v_mul_f32_e32 v97, v210, v66
	v_mul_f32_e32 v66, v89, v83
	v_mul_f32_e32 v98, v207, v66
	v_mul_f32_e32 v66, v85, v83
	v_mul_f32_e32 v99, v211, v66
	s_nop 0
	s_nop 0
	s_nop 0
	v_mul_f32_e32 v100, v212, v100
	v_mul_f32_e32 v70, v76, v83
	v_mul_f32_e32 v101, v216, v70
	v_mul_f32_e32 v66, v81, v83
	v_mul_f32_e32 v102, v213, v66
	v_mul_f32_e32 v66, v77, v83
	v_mul_f32_e32 v103, v217, v66
	v_mul_f32_e32 v66, v78, v83
	v_mul_f32_e32 v104, v214, v66
	v_mul_f32_e32 v66, v74, v83
	v_mul_f32_e32 v105, v218, v66
	v_mul_f32_e32 v66, v79, v83
	v_mul_f32_e32 v106, v215, v66
	v_mul_f32_e32 v66, v75, v83
	v_ashrrev_i32_e32 v83, 31, v82
	v_lshlrev_b64 v[70:71], 9, v[82:83]
	v_lshl_add_u64 v[72:73], s[18:19], 0, v[70:71]
	v_lshl_add_u64 v[70:71], s[20:21], 0, v[70:71]
	v_lshl_add_u64 v[70:71], v[70:71], 0, v[126:127]
	v_add_co_u32_e32 v70, vcc, 0x3b6e9000, v70
	v_mul_f32_e32 v107, v219, v66
	v_cvt_pk_bf16_f32 v66, v92, v94
	v_cvt_pk_bf16_f32 v67, v96, v98
	v_cvt_pk_bf16_f32 v68, v93, v95
	v_cvt_pk_bf16_f32 v69, v97, v99
	v_lshl_add_u64 v[72:73], v[72:73], 0, v[126:127]
	v_addc_co_u32_e32 v71, vcc, 0, v71, vcc
	global_store_dwordx4 v[72:73], v[66:69], off
	s_nop 1
	v_cvt_pk_bf16_f32 v66, v100, v102
	v_cvt_pk_bf16_f32 v67, v104, v106
	v_cvt_pk_bf16_f32 v68, v101, v103
	v_cvt_pk_bf16_f32 v69, v105, v107
	global_store_dwordx4 v[70:71], v[66:69], off offset:320
.LBB0_873:
	s_andn2_b64 vcc, exec, s[0:1]
	s_cbranch_vccnz .LBB0_890
	v_mad_i64_i32 v[92:93], s[0:1], v82, s33, v[122:123]
	s_cmp_gt_i32 s71, 8
	s_mov_b64 s[0:1], -1
	s_cbranch_scc1 .LBB0_880
	s_cmp_lt_u32 s73, 5
	s_cselect_b64 s[0:1], -1, 0
	s_cmp_gt_u32 s73, 4
	s_cbranch_scc0 .LBB0_880
	s_andn2_b64 vcc, exec, s[28:29]
	s_mov_b64 s[4:5], -1
	s_cbranch_vccnz .LBB0_878
	v_lshl_add_u64 v[70:71], v[122:123], 2, s[16:17]
	s_nop 0
	s_nop 0
	s_nop 0
	v_mul_f32_e32 v83, 0x3fb8aa3b, v90
	v_exp_f32_e32 v83, v83
	s_mov_b32 s4, 0x800000
	s_mov_b32 s5, 0x3f317217
	s_mov_b32 s76, 0x7f800000
	v_add_f32_e32 v83, 1.0, v83
	v_rcp_f32_e32 v83, v83
	v_lshl_add_u64 v[94:95], v[92:93], 2, s[86:87]
	s_nop 0
	v_mul_f32_e32 v70, v83, v220
	v_mul_f32_e32 v83, 0x3fb8aa3b, v86
	v_exp_f32_e32 v83, v83
	v_min_f32_e32 v70, 0x3f7fffef, v70
	v_add_f32_e32 v83, 1.0, v83
	v_rcp_f32_e32 v83, v83
	s_nop 0
	v_mul_f32_e32 v66, v83, v224
	v_min_f32_e32 v83, 0x3f7fffef, v66
	v_sub_f32_e32 v66, 1.0, v70
	v_cmp_gt_f32_e32 vcc, s4, v66
	s_nop 1
	v_cndmask_b32_e64 v70, 0, 32, vcc
	v_ldexp_f32 v66, v66, v70
	v_log_f32_e32 v66, v66
	s_nop 0
	v_mul_f32_e32 v70, 0x3f317217, v66
	v_fma_f32 v70, v66, s5, -v70
	v_fmac_f32_e32 v70, 0x3377d1cf, v66
	v_fmac_f32_e32 v70, 0x3f317217, v66
	v_cmp_lt_f32_e64 s[12:13], |v66|, s76
	s_nop 1
	v_cndmask_b32_e64 v66, v66, v70, s[12:13]
	v_cndmask_b32_e32 v70, 0, v199, vcc
	v_sub_f32_e32 v66, v66, v70
	v_sub_f32_e32 v70, 1.0, v83
	v_cmp_gt_f32_e32 vcc, s4, v70
	s_nop 1
	v_cndmask_b32_e64 v83, 0, 32, vcc
	v_ldexp_f32 v70, v70, v83
	v_log_f32_e32 v70, v70
	s_nop 0
	v_mul_f32_e32 v83, 0x3f317217, v70
	v_fma_f32 v83, v70, s5, -v83
	v_fmac_f32_e32 v83, 0x3377d1cf, v70
	v_fmac_f32_e32 v83, 0x3f317217, v70
	v_cmp_lt_f32_e64 s[12:13], |v70|, s76
	s_nop 1
	v_cndmask_b32_e64 v70, v70, v83, s[12:13]
	v_cndmask_b32_e32 v83, 0, v199, vcc
	v_sub_f32_e32 v70, v70, v83
	v_mul_f32_e32 v83, 0x3fb8aa3b, v91
	v_exp_f32_e32 v83, v83
	s_nop 0
	v_add_f32_e32 v83, 1.0, v83
	v_rcp_f32_e32 v83, v83
	s_nop 0
	v_mul_f32_e32 v71, v83, v221
	v_mul_f32_e32 v83, 0x3fb8aa3b, v87
	v_exp_f32_e32 v83, v83
	v_min_f32_e32 v71, 0x3f7fffef, v71
	v_add_f32_e32 v83, 1.0, v83
	v_rcp_f32_e32 v83, v83
	s_nop 0
	v_mul_f32_e32 v67, v83, v225
	v_min_f32_e32 v83, 0x3f7fffef, v67
	v_sub_f32_e32 v67, 1.0, v71
	v_cmp_gt_f32_e32 vcc, s4, v67
	s_nop 1
	v_cndmask_b32_e64 v71, 0, 32, vcc
	v_ldexp_f32 v67, v67, v71
	v_log_f32_e32 v67, v67
	s_nop 0
	v_mul_f32_e32 v71, 0x3f317217, v67
	v_fma_f32 v71, v67, s5, -v71
	v_fmac_f32_e32 v71, 0x3377d1cf, v67
	v_fmac_f32_e32 v71, 0x3f317217, v67
	v_cmp_lt_f32_e64 s[12:13], |v67|, s76
	s_nop 1
	v_cndmask_b32_e64 v67, v67, v71, s[12:13]
	v_cndmask_b32_e32 v71, 0, v199, vcc
	v_sub_f32_e32 v67, v67, v71
	v_sub_f32_e32 v71, 1.0, v83
	v_cmp_gt_f32_e32 vcc, s4, v71
	s_nop 1
	v_cndmask_b32_e64 v83, 0, 32, vcc
	v_ldexp_f32 v71, v71, v83
	v_log_f32_e32 v71, v71
	s_nop 0
	v_mul_f32_e32 v83, 0x3f317217, v71
	v_fma_f32 v83, v71, s5, -v83
	v_fmac_f32_e32 v83, 0x3377d1cf, v71
	v_fmac_f32_e32 v83, 0x3f317217, v71
	v_cmp_lt_f32_e64 s[12:13], |v71|, s76
	s_nop 1
	v_cndmask_b32_e64 v71, v71, v83, s[12:13]
	v_cndmask_b32_e32 v83, 0, v199, vcc
	v_sub_f32_e32 v71, v71, v83
	v_mul_f32_e32 v83, 0x3fb8aa3b, v88
	v_exp_f32_e32 v83, v83
	s_nop 0
	v_add_f32_e32 v83, 1.0, v83
	v_rcp_f32_e32 v83, v83
	s_nop 0
	v_mul_f32_e32 v72, v83, v222
	v_mul_f32_e32 v83, 0x3fb8aa3b, v84
	v_exp_f32_e32 v83, v83
	v_min_f32_e32 v72, 0x3f7fffef, v72
	v_add_f32_e32 v83, 1.0, v83
	v_rcp_f32_e32 v83, v83
	s_nop 0
	v_mul_f32_e32 v68, v83, v226
	v_min_f32_e32 v83, 0x3f7fffef, v68
	v_sub_f32_e32 v68, 1.0, v72
	v_cmp_gt_f32_e32 vcc, s4, v68
	s_nop 1
	v_cndmask_b32_e64 v72, 0, 32, vcc
	v_ldexp_f32 v68, v68, v72
	v_log_f32_e32 v68, v68
	s_nop 0
	v_mul_f32_e32 v72, 0x3f317217, v68
	v_fma_f32 v72, v68, s5, -v72
	v_fmac_f32_e32 v72, 0x3377d1cf, v68
	v_fmac_f32_e32 v72, 0x3f317217, v68
	v_cmp_lt_f32_e64 s[12:13], |v68|, s76
	s_nop 1
	v_cndmask_b32_e64 v68, v68, v72, s[12:13]
	v_cndmask_b32_e32 v72, 0, v199, vcc
	v_sub_f32_e32 v68, v68, v72
	v_sub_f32_e32 v72, 1.0, v83
	v_cmp_gt_f32_e32 vcc, s4, v72
	s_nop 1
	v_cndmask_b32_e64 v83, 0, 32, vcc
	v_ldexp_f32 v72, v72, v83
	v_log_f32_e32 v72, v72
	s_nop 0
	v_mul_f32_e32 v83, 0x3f317217, v72
	v_fma_f32 v83, v72, s5, -v83
	v_fmac_f32_e32 v83, 0x3377d1cf, v72
	v_fmac_f32_e32 v83, 0x3f317217, v72
	v_cmp_lt_f32_e64 s[12:13], |v72|, s76
	s_nop 1
	v_cndmask_b32_e64 v72, v72, v83, s[12:13]
	v_cndmask_b32_e32 v83, 0, v199, vcc
	v_sub_f32_e32 v72, v72, v83
	v_mul_f32_e32 v83, 0x3fb8aa3b, v89
	v_exp_f32_e32 v83, v83
	s_nop 0
	v_add_f32_e32 v83, 1.0, v83
	v_rcp_f32_e32 v83, v83
	s_nop 0
	v_mul_f32_e32 v73, v83, v223
	v_mul_f32_e32 v83, 0x3fb8aa3b, v85
	v_exp_f32_e32 v83, v83
	v_min_f32_e32 v73, 0x3f7fffef, v73
	v_add_f32_e32 v83, 1.0, v83
	v_rcp_f32_e32 v83, v83
	s_nop 0
	v_mul_f32_e32 v69, v83, v227
	v_min_f32_e32 v83, 0x3f7fffef, v69
	v_sub_f32_e32 v69, 1.0, v73
	v_cmp_gt_f32_e32 vcc, s4, v69
	s_nop 1
	v_cndmask_b32_e64 v73, 0, 32, vcc
	v_ldexp_f32 v69, v69, v73
	v_log_f32_e32 v69, v69
	s_nop 0
	v_mul_f32_e32 v73, 0x3f317217, v69
	v_fma_f32 v73, v69, s5, -v73
	v_fmac_f32_e32 v73, 0x3377d1cf, v69
	v_fmac_f32_e32 v73, 0x3f317217, v69
	v_cmp_lt_f32_e64 s[12:13], |v69|, s76
	s_nop 1
	v_cndmask_b32_e64 v69, v69, v73, s[12:13]
	v_cndmask_b32_e32 v73, 0, v199, vcc
	v_sub_f32_e32 v69, v69, v73
	v_sub_f32_e32 v73, 1.0, v83
	v_cmp_gt_f32_e32 vcc, s4, v73
	s_nop 1
	v_cndmask_b32_e64 v83, 0, 32, vcc
	v_ldexp_f32 v73, v73, v83
	v_log_f32_e32 v73, v73
	s_nop 0
	v_mul_f32_e32 v83, 0x3f317217, v73
	v_fma_f32 v83, v73, s5, -v83
	v_fmac_f32_e32 v83, 0x3377d1cf, v73
	v_fmac_f32_e32 v83, 0x3f317217, v73
	v_cmp_lt_f32_e64 s[12:13], |v73|, s76
	s_mov_b64 s[4:5], 0
	s_nop 0
	v_cndmask_b32_e64 v73, v73, v83, s[12:13]
	v_cndmask_b32_e32 v83, 0, v199, vcc
	v_sub_f32_e32 v73, v73, v83
	global_store_dwordx4 v[94:95], v[66:69], off
	global_store_dwordx4 v[94:95], v[70:73], off offset:16

.LBB0_882:
	s_nop 1
	v_mad_i64_i32 v[66:67], s[0:1], v82, s33, 0
	v_lshl_add_u64 v[82:83], v[66:67], 0, v[124:125]
	s_cmp_gt_i32 s71, 8
	s_mov_b64 s[0:1], -1
	s_cbranch_scc1 .LBB0_888
	s_cmp_lt_u32 s73, 5
	s_cselect_b64 s[0:1], -1, 0
	s_cmp_gt_u32 s73, 4
	s_cbranch_scc0 .LBB0_888
	s_andn2_b64 vcc, exec, s[28:29]
	s_mov_b64 s[4:5], -1
	s_cbranch_vccnz .LBB0_886
	v_lshl_add_u64 v[70:71], v[122:123], 2, s[16:17]
	s_nop 0
	s_nop 0
	s_nop 0
	v_mul_f32_e32 v84, 0x3fb8aa3b, v80
	v_exp_f32_e32 v84, v84
	s_mov_b32 s4, 0x800000
	s_mov_b32 s5, 0x3f317217
	s_mov_b32 s76, 0x7f800000
	v_add_f32_e32 v84, 1.0, v84
	v_rcp_f32_e32 v84, v84
	s_nop 0
	v_mul_f32_e32 v70, v84, v228
	v_mul_f32_e32 v84, 0x3fb8aa3b, v76
	v_exp_f32_e32 v84, v84
	v_min_f32_e32 v70, 0x3f7fffef, v70
	v_add_f32_e32 v84, 1.0, v84
	v_rcp_f32_e32 v84, v84
	s_nop 0
	v_mul_f32_e32 v66, v84, v232
	v_min_f32_e32 v84, 0x3f7fffef, v66
	v_sub_f32_e32 v66, 1.0, v70
	v_cmp_gt_f32_e32 vcc, s4, v66
	s_nop 1
	v_cndmask_b32_e64 v70, 0, 32, vcc
	v_ldexp_f32 v66, v66, v70
	v_log_f32_e32 v66, v66
	s_nop 0
	v_mul_f32_e32 v70, 0x3f317217, v66
	v_fma_f32 v70, v66, s5, -v70
	v_fmac_f32_e32 v70, 0x3377d1cf, v66
	v_fmac_f32_e32 v70, 0x3f317217, v66
	v_cmp_lt_f32_e64 s[12:13], |v66|, s76
	s_nop 1
	v_cndmask_b32_e64 v66, v66, v70, s[12:13]
	v_cndmask_b32_e32 v70, 0, v199, vcc
	v_sub_f32_e32 v66, v66, v70
	v_sub_f32_e32 v70, 1.0, v84
	v_cmp_gt_f32_e32 vcc, s4, v70
	s_nop 1
	v_cndmask_b32_e64 v84, 0, 32, vcc
	v_ldexp_f32 v70, v70, v84
	v_log_f32_e32 v70, v70
	s_nop 0
	v_mul_f32_e32 v84, 0x3f317217, v70
	v_fma_f32 v84, v70, s5, -v84
	v_fmac_f32_e32 v84, 0x3377d1cf, v70
	v_fmac_f32_e32 v84, 0x3f317217, v70
	v_cmp_lt_f32_e64 s[12:13], |v70|, s76
	s_nop 1
	v_cndmask_b32_e64 v70, v70, v84, s[12:13]
	v_cndmask_b32_e32 v84, 0, v199, vcc
	v_sub_f32_e32 v70, v70, v84
	v_mul_f32_e32 v84, 0x3fb8aa3b, v81
	v_exp_f32_e32 v84, v84
	s_nop 0
	v_add_f32_e32 v84, 1.0, v84
	v_rcp_f32_e32 v84, v84
	s_nop 0
	v_mul_f32_e32 v71, v84, v229
	v_mul_f32_e32 v84, 0x3fb8aa3b, v77
	v_exp_f32_e32 v84, v84
	v_min_f32_e32 v71, 0x3f7fffef, v71
	v_add_f32_e32 v84, 1.0, v84
	v_rcp_f32_e32 v84, v84
	s_nop 0
	v_mul_f32_e32 v67, v84, v233
	v_min_f32_e32 v84, 0x3f7fffef, v67
	v_sub_f32_e32 v67, 1.0, v71
	v_cmp_gt_f32_e32 vcc, s4, v67
	s_nop 1
	v_cndmask_b32_e64 v71, 0, 32, vcc
	v_ldexp_f32 v67, v67, v71
	v_log_f32_e32 v67, v67
	s_nop 0
	v_mul_f32_e32 v71, 0x3f317217, v67
	v_fma_f32 v71, v67, s5, -v71
	v_fmac_f32_e32 v71, 0x3377d1cf, v67
	v_fmac_f32_e32 v71, 0x3f317217, v67
	v_cmp_lt_f32_e64 s[12:13], |v67|, s76
	s_nop 1
	v_cndmask_b32_e64 v67, v67, v71, s[12:13]
	v_cndmask_b32_e32 v71, 0, v199, vcc
	v_sub_f32_e32 v67, v67, v71
	v_sub_f32_e32 v71, 1.0, v84
	v_cmp_gt_f32_e32 vcc, s4, v71
	s_nop 1
	v_cndmask_b32_e64 v84, 0, 32, vcc
	v_ldexp_f32 v71, v71, v84
	v_log_f32_e32 v71, v71
	s_nop 0
	v_mul_f32_e32 v84, 0x3f317217, v71
	v_fma_f32 v84, v71, s5, -v84
	v_fmac_f32_e32 v84, 0x3377d1cf, v71
	v_fmac_f32_e32 v84, 0x3f317217, v71
	v_cmp_lt_f32_e64 s[12:13], |v71|, s76
	s_nop 1
	v_cndmask_b32_e64 v71, v71, v84, s[12:13]
	v_cndmask_b32_e32 v84, 0, v199, vcc
	v_sub_f32_e32 v71, v71, v84
	v_mul_f32_e32 v84, 0x3fb8aa3b, v78
	v_exp_f32_e32 v84, v84
	s_nop 0
	v_add_f32_e32 v84, 1.0, v84
	v_rcp_f32_e32 v84, v84
	s_nop 0
	v_mul_f32_e32 v72, v84, v230
	v_mul_f32_e32 v84, 0x3fb8aa3b, v74
	v_exp_f32_e32 v84, v84
	v_min_f32_e32 v72, 0x3f7fffef, v72
	v_add_f32_e32 v84, 1.0, v84
	v_rcp_f32_e32 v84, v84
	s_nop 0
	v_mul_f32_e32 v68, v84, v234
	v_min_f32_e32 v84, 0x3f7fffef, v68
	v_sub_f32_e32 v68, 1.0, v72
	v_cmp_gt_f32_e32 vcc, s4, v68
	s_nop 1
	v_cndmask_b32_e64 v72, 0, 32, vcc
	v_ldexp_f32 v68, v68, v72
	v_log_f32_e32 v68, v68
	s_nop 0
	v_mul_f32_e32 v72, 0x3f317217, v68
	v_fma_f32 v72, v68, s5, -v72
	v_fmac_f32_e32 v72, 0x3377d1cf, v68
	v_fmac_f32_e32 v72, 0x3f317217, v68
	v_cmp_lt_f32_e64 s[12:13], |v68|, s76
	s_nop 1
	v_cndmask_b32_e64 v68, v68, v72, s[12:13]
	v_cndmask_b32_e32 v72, 0, v199, vcc
	v_sub_f32_e32 v68, v68, v72
	v_sub_f32_e32 v72, 1.0, v84
	v_cmp_gt_f32_e32 vcc, s4, v72
	s_nop 1
	v_cndmask_b32_e64 v84, 0, 32, vcc
	v_ldexp_f32 v72, v72, v84
	v_log_f32_e32 v72, v72
	s_nop 0
	v_mul_f32_e32 v84, 0x3f317217, v72
	v_fma_f32 v84, v72, s5, -v84
	v_fmac_f32_e32 v84, 0x3377d1cf, v72
	v_fmac_f32_e32 v84, 0x3f317217, v72
	v_cmp_lt_f32_e64 s[12:13], |v72|, s76
	s_nop 1
	v_cndmask_b32_e64 v72, v72, v84, s[12:13]
	v_cndmask_b32_e32 v84, 0, v199, vcc
	v_sub_f32_e32 v72, v72, v84
	v_mul_f32_e32 v84, 0x3fb8aa3b, v79
	v_exp_f32_e32 v84, v84
	s_nop 0
	v_add_f32_e32 v84, 1.0, v84
	v_rcp_f32_e32 v84, v84
	s_nop 0
	v_mul_f32_e32 v73, v84, v231
	v_mul_f32_e32 v84, 0x3fb8aa3b, v75
	v_exp_f32_e32 v84, v84
	v_min_f32_e32 v73, 0x3f7fffef, v73
	v_add_f32_e32 v84, 1.0, v84
	v_rcp_f32_e32 v84, v84
	s_nop 0
	v_mul_f32_e32 v69, v84, v235
	v_min_f32_e32 v84, 0x3f7fffef, v69
	v_sub_f32_e32 v69, 1.0, v73
	v_cmp_gt_f32_e32 vcc, s4, v69
	s_nop 1
	v_cndmask_b32_e64 v73, 0, 32, vcc
	v_ldexp_f32 v69, v69, v73
	v_log_f32_e32 v69, v69
	s_nop 0
	v_mul_f32_e32 v73, 0x3f317217, v69
	v_fma_f32 v73, v69, s5, -v73
	v_fmac_f32_e32 v73, 0x3377d1cf, v69
	v_fmac_f32_e32 v73, 0x3f317217, v69
	v_cmp_lt_f32_e64 s[12:13], |v69|, s76
	s_nop 1
	v_cndmask_b32_e64 v69, v69, v73, s[12:13]
	v_cndmask_b32_e32 v73, 0, v199, vcc
	v_sub_f32_e32 v69, v69, v73
	v_sub_f32_e32 v73, 1.0, v84
	v_cmp_gt_f32_e32 vcc, s4, v73
	s_nop 1
	v_cndmask_b32_e64 v84, 0, 32, vcc
	v_ldexp_f32 v73, v73, v84
	v_log_f32_e32 v73, v73
	s_nop 0
	v_mul_f32_e32 v84, 0x3f317217, v73
	v_fma_f32 v84, v73, s5, -v84
	v_fmac_f32_e32 v84, 0x3377d1cf, v73
	v_fmac_f32_e32 v84, 0x3f317217, v73
	v_cmp_lt_f32_e64 s[12:13], |v73|, s76
	s_mov_b64 s[4:5], 0
	s_nop 0
	v_cndmask_b32_e64 v73, v73, v84, s[12:13]
	v_cndmask_b32_e32 v84, 0, v199, vcc
	v_sub_f32_e32 v73, v73, v84
	v_lshl_add_u64 v[84:85], v[82:83], 2, s[86:87]
	global_store_dwordx4 v[84:85], v[66:69], off
	global_store_dwordx4 v[84:85], v[70:73], off offset:16

.LBB0_890:
	v_pk_mul_f32 v[72:73], v[64:65], v[144:145] op_sel_hi:[1,0]
	v_pk_mul_f32 v[74:75], v[62:63], v[144:145] op_sel_hi:[1,0]
	v_pk_mul_f32 v[68:69], v[60:61], v[144:145] op_sel_hi:[1,0]
	v_pk_mul_f32 v[70:71], v[58:59], v[144:145] op_sel_hi:[1,0]
	v_pk_mul_f32 v[62:63], v[56:57], v[144:145] op_sel_hi:[1,0]
	v_pk_mul_f32 v[64:65], v[54:55], v[144:145] op_sel_hi:[1,0]
	v_pk_mul_f32 v[58:59], v[52:53], v[144:145] op_sel_hi:[1,0]
	v_pk_mul_f32 v[60:61], v[50:51], v[144:145] op_sel_hi:[1,0]
	v_add_u32_e32 v66, s88, v175
	s_and_b64 vcc, exec, s[10:11]
	s_mov_b64 s[0:1], -1
	s_cbranch_vccnz .LBB0_892
	v_mul_f32_e32 v52, v75, v75
	v_fmac_f32_e32 v52, v74, v74
	v_fmac_f32_e32 v52, v72, v72
	v_fmac_f32_e32 v52, v73, v73
	v_fmac_f32_e32 v52, v70, v70
	v_fmac_f32_e32 v52, v71, v71
	v_fmac_f32_e32 v52, v68, v68
	v_fmac_f32_e32 v52, v69, v69
	v_fmac_f32_e32 v52, v64, v64
	v_fmac_f32_e32 v52, v65, v65
	v_fmac_f32_e32 v52, v62, v62
	v_fmac_f32_e32 v52, v63, v63
	v_fmac_f32_e32 v52, v60, v60
	v_fmac_f32_e32 v52, v61, v61
	v_pk_mul_f32 v[50:51], v[58:59], v[58:59]
	s_mov_b64 s[0:1], 0
	v_add_f32_e32 v50, v50, v52
	v_add_f32_e32 v50, v51, v50
	ds_bpermute_b32 v51, v174, v50
	s_waitcnt lgkmcnt(0)
	v_add_f32_e32 v50, v50, v51
	ds_bpermute_b32 v51, v173, v50
	s_waitcnt lgkmcnt(0)
	v_add_f32_e32 v50, v50, v51
	v_fmamk_f32 v50, v50, 0x3c800000, v188
	v_rsq_f32_e32 v50, v50
	s_nop 0
	v_mul_f32_e32 v67, 0x3e38aa3b, v50
	s_nop 0
	s_nop 0
	v_mul_f32_e32 v76, v74, v67
	v_mul_f32_e32 v84, v64, v67
	s_nop 0
	v_mul_f32_e32 v76, v204, v76
	v_mul_f32_e32 v54, v70, v67
	v_mul_f32_e32 v77, v208, v54
	v_mul_f32_e32 v50, v75, v67
	v_mul_f32_e32 v78, v205, v50
	v_mul_f32_e32 v50, v71, v67
	v_mul_f32_e32 v79, v209, v50
	v_mul_f32_e32 v50, v72, v67
	v_mul_f32_e32 v80, v206, v50
	v_mul_f32_e32 v50, v68, v67
	v_mul_f32_e32 v81, v210, v50
	v_mul_f32_e32 v50, v73, v67
	v_mul_f32_e32 v82, v207, v50
	v_mul_f32_e32 v50, v69, v67
	v_mul_f32_e32 v83, v211, v50
	s_nop 0
	s_nop 0
	s_nop 0
	v_mul_f32_e32 v84, v212, v84
	v_mul_f32_e32 v54, v60, v67
	v_mul_f32_e32 v85, v216, v54
	v_mul_f32_e32 v50, v65, v67
	v_mul_f32_e32 v86, v213, v50
	v_mul_f32_e32 v50, v61, v67
	v_mul_f32_e32 v87, v217, v50
	v_mul_f32_e32 v50, v62, v67
	v_mul_f32_e32 v88, v214, v50
	v_mul_f32_e32 v50, v58, v67
	v_mul_f32_e32 v89, v218, v50
	v_mul_f32_e32 v50, v63, v67
	v_mul_f32_e32 v90, v215, v50
	v_mul_f32_e32 v50, v59, v67
	v_ashrrev_i32_e32 v67, 31, v66
	v_lshlrev_b64 v[54:55], 9, v[66:67]
	v_lshl_add_u64 v[56:57], s[18:19], 0, v[54:55]
	v_lshl_add_u64 v[54:55], s[20:21], 0, v[54:55]
	v_lshl_add_u64 v[54:55], v[54:55], 0, v[126:127]
	v_add_co_u32_e32 v54, vcc, 0x3b6e9000, v54
	v_mul_f32_e32 v91, v219, v50
	v_cvt_pk_bf16_f32 v50, v76, v78
	v_cvt_pk_bf16_f32 v51, v80, v82
	v_cvt_pk_bf16_f32 v52, v77, v79
	v_cvt_pk_bf16_f32 v53, v81, v83
	v_lshl_add_u64 v[56:57], v[56:57], 0, v[126:127]
	v_addc_co_u32_e32 v55, vcc, 0, v55, vcc
	global_store_dwordx4 v[56:57], v[50:53], off
	s_nop 1
	v_cvt_pk_bf16_f32 v50, v84, v86
	v_cvt_pk_bf16_f32 v51, v88, v90
	v_cvt_pk_bf16_f32 v52, v85, v87
	v_cvt_pk_bf16_f32 v53, v89, v91
	global_store_dwordx4 v[54:55], v[50:53], off offset:320
.LBB0_892:
	s_andn2_b64 vcc, exec, s[0:1]
	s_cbranch_vccnz .LBB0_909
	v_mad_i64_i32 v[76:77], s[0:1], v66, s33, v[122:123]
	s_cmp_gt_i32 s71, 8
	s_mov_b64 s[0:1], -1
	s_cbranch_scc1 .LBB0_899
	s_cmp_lt_u32 s73, 5
	s_cselect_b64 s[0:1], -1, 0
	s_cmp_gt_u32 s73, 4
	s_cbranch_scc0 .LBB0_899
	s_andn2_b64 vcc, exec, s[28:29]
	s_mov_b64 s[4:5], -1
	s_cbranch_vccnz .LBB0_897
	v_lshl_add_u64 v[54:55], v[122:123], 2, s[16:17]
	s_nop 0
	s_nop 0
	s_nop 0
	v_mul_f32_e32 v67, 0x3fb8aa3b, v74
	v_exp_f32_e32 v67, v67
	s_mov_b32 s4, 0x800000
	s_mov_b32 s5, 0x3f317217
	s_mov_b32 s76, 0x7f800000
	v_add_f32_e32 v67, 1.0, v67
	v_rcp_f32_e32 v67, v67
	v_lshl_add_u64 v[78:79], v[76:77], 2, s[86:87]
	s_nop 0
	v_mul_f32_e32 v54, v67, v220
	v_mul_f32_e32 v67, 0x3fb8aa3b, v70
	v_exp_f32_e32 v67, v67
	v_min_f32_e32 v54, 0x3f7fffef, v54
	v_add_f32_e32 v67, 1.0, v67
	v_rcp_f32_e32 v67, v67
	s_nop 0
	v_mul_f32_e32 v50, v67, v224
	v_min_f32_e32 v67, 0x3f7fffef, v50
	v_sub_f32_e32 v50, 1.0, v54
	v_cmp_gt_f32_e32 vcc, s4, v50
	s_nop 1
	v_cndmask_b32_e64 v54, 0, 32, vcc
	v_ldexp_f32 v50, v50, v54
	v_log_f32_e32 v50, v50
	s_nop 0
	v_mul_f32_e32 v54, 0x3f317217, v50
	v_fma_f32 v54, v50, s5, -v54
	v_fmac_f32_e32 v54, 0x3377d1cf, v50
	v_fmac_f32_e32 v54, 0x3f317217, v50
	v_cmp_lt_f32_e64 s[12:13], |v50|, s76
	s_nop 1
	v_cndmask_b32_e64 v50, v50, v54, s[12:13]
	v_cndmask_b32_e32 v54, 0, v199, vcc
	v_sub_f32_e32 v50, v50, v54
	v_sub_f32_e32 v54, 1.0, v67
	v_cmp_gt_f32_e32 vcc, s4, v54
	s_nop 1
	v_cndmask_b32_e64 v67, 0, 32, vcc
	v_ldexp_f32 v54, v54, v67
	v_log_f32_e32 v54, v54
	s_nop 0
	v_mul_f32_e32 v67, 0x3f317217, v54
	v_fma_f32 v67, v54, s5, -v67
	v_fmac_f32_e32 v67, 0x3377d1cf, v54
	v_fmac_f32_e32 v67, 0x3f317217, v54
	v_cmp_lt_f32_e64 s[12:13], |v54|, s76
	s_nop 1
	v_cndmask_b32_e64 v54, v54, v67, s[12:13]
	v_cndmask_b32_e32 v67, 0, v199, vcc
	v_sub_f32_e32 v54, v54, v67
	v_mul_f32_e32 v67, 0x3fb8aa3b, v75
	v_exp_f32_e32 v67, v67
	s_nop 0
	v_add_f32_e32 v67, 1.0, v67
	v_rcp_f32_e32 v67, v67
	s_nop 0
	v_mul_f32_e32 v55, v67, v221
	v_mul_f32_e32 v67, 0x3fb8aa3b, v71
	v_exp_f32_e32 v67, v67
	v_min_f32_e32 v55, 0x3f7fffef, v55
	v_add_f32_e32 v67, 1.0, v67
	v_rcp_f32_e32 v67, v67
	s_nop 0
	v_mul_f32_e32 v51, v67, v225
	v_min_f32_e32 v67, 0x3f7fffef, v51
	v_sub_f32_e32 v51, 1.0, v55
	v_cmp_gt_f32_e32 vcc, s4, v51
	s_nop 1
	v_cndmask_b32_e64 v55, 0, 32, vcc
	v_ldexp_f32 v51, v51, v55
	v_log_f32_e32 v51, v51
	s_nop 0
	v_mul_f32_e32 v55, 0x3f317217, v51
	v_fma_f32 v55, v51, s5, -v55
	v_fmac_f32_e32 v55, 0x3377d1cf, v51
	v_fmac_f32_e32 v55, 0x3f317217, v51
	v_cmp_lt_f32_e64 s[12:13], |v51|, s76
	s_nop 1
	v_cndmask_b32_e64 v51, v51, v55, s[12:13]
	v_cndmask_b32_e32 v55, 0, v199, vcc
	v_sub_f32_e32 v51, v51, v55
	v_sub_f32_e32 v55, 1.0, v67
	v_cmp_gt_f32_e32 vcc, s4, v55
	s_nop 1
	v_cndmask_b32_e64 v67, 0, 32, vcc
	v_ldexp_f32 v55, v55, v67
	v_log_f32_e32 v55, v55
	s_nop 0
	v_mul_f32_e32 v67, 0x3f317217, v55
	v_fma_f32 v67, v55, s5, -v67
	v_fmac_f32_e32 v67, 0x3377d1cf, v55
	v_fmac_f32_e32 v67, 0x3f317217, v55
	v_cmp_lt_f32_e64 s[12:13], |v55|, s76
	s_nop 1
	v_cndmask_b32_e64 v55, v55, v67, s[12:13]
	v_cndmask_b32_e32 v67, 0, v199, vcc
	v_sub_f32_e32 v55, v55, v67
	v_mul_f32_e32 v67, 0x3fb8aa3b, v72
	v_exp_f32_e32 v67, v67
	s_nop 0
	v_add_f32_e32 v67, 1.0, v67
	v_rcp_f32_e32 v67, v67
	s_nop 0
	v_mul_f32_e32 v56, v67, v222
	v_mul_f32_e32 v67, 0x3fb8aa3b, v68
	v_exp_f32_e32 v67, v67
	v_min_f32_e32 v56, 0x3f7fffef, v56
	v_add_f32_e32 v67, 1.0, v67
	v_rcp_f32_e32 v67, v67
	s_nop 0
	v_mul_f32_e32 v52, v67, v226
	v_min_f32_e32 v67, 0x3f7fffef, v52
	v_sub_f32_e32 v52, 1.0, v56
	v_cmp_gt_f32_e32 vcc, s4, v52
	s_nop 1
	v_cndmask_b32_e64 v56, 0, 32, vcc
	v_ldexp_f32 v52, v52, v56
	v_log_f32_e32 v52, v52
	s_nop 0
	v_mul_f32_e32 v56, 0x3f317217, v52
	v_fma_f32 v56, v52, s5, -v56
	v_fmac_f32_e32 v56, 0x3377d1cf, v52
	v_fmac_f32_e32 v56, 0x3f317217, v52
	v_cmp_lt_f32_e64 s[12:13], |v52|, s76
	s_nop 1
	v_cndmask_b32_e64 v52, v52, v56, s[12:13]
	v_cndmask_b32_e32 v56, 0, v199, vcc
	v_sub_f32_e32 v52, v52, v56
	v_sub_f32_e32 v56, 1.0, v67
	v_cmp_gt_f32_e32 vcc, s4, v56
	s_nop 1
	v_cndmask_b32_e64 v67, 0, 32, vcc
	v_ldexp_f32 v56, v56, v67
	v_log_f32_e32 v56, v56
	s_nop 0
	v_mul_f32_e32 v67, 0x3f317217, v56
	v_fma_f32 v67, v56, s5, -v67
	v_fmac_f32_e32 v67, 0x3377d1cf, v56
	v_fmac_f32_e32 v67, 0x3f317217, v56
	v_cmp_lt_f32_e64 s[12:13], |v56|, s76
	s_nop 1
	v_cndmask_b32_e64 v56, v56, v67, s[12:13]
	v_cndmask_b32_e32 v67, 0, v199, vcc
	v_sub_f32_e32 v56, v56, v67
	v_mul_f32_e32 v67, 0x3fb8aa3b, v73
	v_exp_f32_e32 v67, v67
	s_nop 0
	v_add_f32_e32 v67, 1.0, v67
	v_rcp_f32_e32 v67, v67
	s_nop 0
	v_mul_f32_e32 v57, v67, v223
	v_mul_f32_e32 v67, 0x3fb8aa3b, v69
	v_exp_f32_e32 v67, v67
	v_min_f32_e32 v57, 0x3f7fffef, v57
	v_add_f32_e32 v67, 1.0, v67
	v_rcp_f32_e32 v67, v67
	s_nop 0
	v_mul_f32_e32 v53, v67, v227
	v_min_f32_e32 v67, 0x3f7fffef, v53
	v_sub_f32_e32 v53, 1.0, v57
	v_cmp_gt_f32_e32 vcc, s4, v53
	s_nop 1
	v_cndmask_b32_e64 v57, 0, 32, vcc
	v_ldexp_f32 v53, v53, v57
	v_log_f32_e32 v53, v53
	s_nop 0
	v_mul_f32_e32 v57, 0x3f317217, v53
	v_fma_f32 v57, v53, s5, -v57
	v_fmac_f32_e32 v57, 0x3377d1cf, v53
	v_fmac_f32_e32 v57, 0x3f317217, v53
	v_cmp_lt_f32_e64 s[12:13], |v53|, s76
	s_nop 1
	v_cndmask_b32_e64 v53, v53, v57, s[12:13]
	v_cndmask_b32_e32 v57, 0, v199, vcc
	v_sub_f32_e32 v53, v53, v57
	v_sub_f32_e32 v57, 1.0, v67
	v_cmp_gt_f32_e32 vcc, s4, v57
	s_nop 1
	v_cndmask_b32_e64 v67, 0, 32, vcc
	v_ldexp_f32 v57, v57, v67
	v_log_f32_e32 v57, v57
	s_nop 0
	v_mul_f32_e32 v67, 0x3f317217, v57
	v_fma_f32 v67, v57, s5, -v67
	v_fmac_f32_e32 v67, 0x3377d1cf, v57
	v_fmac_f32_e32 v67, 0x3f317217, v57
	v_cmp_lt_f32_e64 s[12:13], |v57|, s76
	s_mov_b64 s[4:5], 0
	s_nop 0
	v_cndmask_b32_e64 v57, v57, v67, s[12:13]
	v_cndmask_b32_e32 v67, 0, v199, vcc
	v_sub_f32_e32 v57, v57, v67
	global_store_dwordx4 v[78:79], v[50:53], off
	global_store_dwordx4 v[78:79], v[54:57], off offset:16

.LBB0_901:
	s_nop 1
	v_mad_i64_i32 v[50:51], s[0:1], v66, s33, 0
	v_lshl_add_u64 v[66:67], v[50:51], 0, v[124:125]
	s_cmp_gt_i32 s71, 8
	s_mov_b64 s[0:1], -1
	s_cbranch_scc1 .LBB0_907
	s_cmp_lt_u32 s73, 5
	s_cselect_b64 s[0:1], -1, 0
	s_cmp_gt_u32 s73, 4
	s_cbranch_scc0 .LBB0_907
	s_andn2_b64 vcc, exec, s[28:29]
	s_mov_b64 s[4:5], -1
	s_cbranch_vccnz .LBB0_905
	v_lshl_add_u64 v[54:55], v[122:123], 2, s[16:17]
	s_nop 0
	s_nop 0
	s_nop 0
	v_mul_f32_e32 v68, 0x3fb8aa3b, v64
	v_exp_f32_e32 v68, v68
	s_mov_b32 s4, 0x800000
	s_mov_b32 s5, 0x3f317217
	s_mov_b32 s76, 0x7f800000
	v_add_f32_e32 v68, 1.0, v68
	v_rcp_f32_e32 v68, v68
	s_nop 0
	v_mul_f32_e32 v54, v68, v228
	v_mul_f32_e32 v68, 0x3fb8aa3b, v60
	v_exp_f32_e32 v68, v68
	v_min_f32_e32 v54, 0x3f7fffef, v54
	v_add_f32_e32 v68, 1.0, v68
	v_rcp_f32_e32 v68, v68
	s_nop 0
	v_mul_f32_e32 v50, v68, v232
	v_min_f32_e32 v68, 0x3f7fffef, v50
	v_sub_f32_e32 v50, 1.0, v54
	v_cmp_gt_f32_e32 vcc, s4, v50
	s_nop 1
	v_cndmask_b32_e64 v54, 0, 32, vcc
	v_ldexp_f32 v50, v50, v54
	v_log_f32_e32 v50, v50
	s_nop 0
	v_mul_f32_e32 v54, 0x3f317217, v50
	v_fma_f32 v54, v50, s5, -v54
	v_fmac_f32_e32 v54, 0x3377d1cf, v50
	v_fmac_f32_e32 v54, 0x3f317217, v50
	v_cmp_lt_f32_e64 s[12:13], |v50|, s76
	s_nop 1
	v_cndmask_b32_e64 v50, v50, v54, s[12:13]
	v_cndmask_b32_e32 v54, 0, v199, vcc
	v_sub_f32_e32 v50, v50, v54
	v_sub_f32_e32 v54, 1.0, v68
	v_cmp_gt_f32_e32 vcc, s4, v54
	s_nop 1
	v_cndmask_b32_e64 v68, 0, 32, vcc
	v_ldexp_f32 v54, v54, v68
	v_log_f32_e32 v54, v54
	s_nop 0
	v_mul_f32_e32 v68, 0x3f317217, v54
	v_fma_f32 v68, v54, s5, -v68
	v_fmac_f32_e32 v68, 0x3377d1cf, v54
	v_fmac_f32_e32 v68, 0x3f317217, v54
	v_cmp_lt_f32_e64 s[12:13], |v54|, s76
	s_nop 1
	v_cndmask_b32_e64 v54, v54, v68, s[12:13]
	v_cndmask_b32_e32 v68, 0, v199, vcc
	v_sub_f32_e32 v54, v54, v68
	v_mul_f32_e32 v68, 0x3fb8aa3b, v65
	v_exp_f32_e32 v68, v68
	s_nop 0
	v_add_f32_e32 v68, 1.0, v68
	v_rcp_f32_e32 v68, v68
	s_nop 0
	v_mul_f32_e32 v55, v68, v229
	v_mul_f32_e32 v68, 0x3fb8aa3b, v61
	v_exp_f32_e32 v68, v68
	v_min_f32_e32 v55, 0x3f7fffef, v55
	v_add_f32_e32 v68, 1.0, v68
	v_rcp_f32_e32 v68, v68
	s_nop 0
	v_mul_f32_e32 v51, v68, v233
	v_min_f32_e32 v68, 0x3f7fffef, v51
	v_sub_f32_e32 v51, 1.0, v55
	v_cmp_gt_f32_e32 vcc, s4, v51
	s_nop 1
	v_cndmask_b32_e64 v55, 0, 32, vcc
	v_ldexp_f32 v51, v51, v55
	v_log_f32_e32 v51, v51
	s_nop 0
	v_mul_f32_e32 v55, 0x3f317217, v51
	v_fma_f32 v55, v51, s5, -v55
	v_fmac_f32_e32 v55, 0x3377d1cf, v51
	v_fmac_f32_e32 v55, 0x3f317217, v51
	v_cmp_lt_f32_e64 s[12:13], |v51|, s76
	s_nop 1
	v_cndmask_b32_e64 v51, v51, v55, s[12:13]
	v_cndmask_b32_e32 v55, 0, v199, vcc
	v_sub_f32_e32 v51, v51, v55
	v_sub_f32_e32 v55, 1.0, v68
	v_cmp_gt_f32_e32 vcc, s4, v55
	s_nop 1
	v_cndmask_b32_e64 v68, 0, 32, vcc
	v_ldexp_f32 v55, v55, v68
	v_log_f32_e32 v55, v55
	s_nop 0
	v_mul_f32_e32 v68, 0x3f317217, v55
	v_fma_f32 v68, v55, s5, -v68
	v_fmac_f32_e32 v68, 0x3377d1cf, v55
	v_fmac_f32_e32 v68, 0x3f317217, v55
	v_cmp_lt_f32_e64 s[12:13], |v55|, s76
	s_nop 1
	v_cndmask_b32_e64 v55, v55, v68, s[12:13]
	v_cndmask_b32_e32 v68, 0, v199, vcc
	v_sub_f32_e32 v55, v55, v68
	v_mul_f32_e32 v68, 0x3fb8aa3b, v62
	v_exp_f32_e32 v68, v68
	s_nop 0
	v_add_f32_e32 v68, 1.0, v68
	v_rcp_f32_e32 v68, v68
	s_nop 0
	v_mul_f32_e32 v56, v68, v230
	v_mul_f32_e32 v68, 0x3fb8aa3b, v58
	v_exp_f32_e32 v68, v68
	v_min_f32_e32 v56, 0x3f7fffef, v56
	v_add_f32_e32 v68, 1.0, v68
	v_rcp_f32_e32 v68, v68
	s_nop 0
	v_mul_f32_e32 v52, v68, v234
	v_min_f32_e32 v68, 0x3f7fffef, v52
	v_sub_f32_e32 v52, 1.0, v56
	v_cmp_gt_f32_e32 vcc, s4, v52
	s_nop 1
	v_cndmask_b32_e64 v56, 0, 32, vcc
	v_ldexp_f32 v52, v52, v56
	v_log_f32_e32 v52, v52
	s_nop 0
	v_mul_f32_e32 v56, 0x3f317217, v52
	v_fma_f32 v56, v52, s5, -v56
	v_fmac_f32_e32 v56, 0x3377d1cf, v52
	v_fmac_f32_e32 v56, 0x3f317217, v52
	v_cmp_lt_f32_e64 s[12:13], |v52|, s76
	s_nop 1
	v_cndmask_b32_e64 v52, v52, v56, s[12:13]
	v_cndmask_b32_e32 v56, 0, v199, vcc
	v_sub_f32_e32 v52, v52, v56
	v_sub_f32_e32 v56, 1.0, v68
	v_cmp_gt_f32_e32 vcc, s4, v56
	s_nop 1
	v_cndmask_b32_e64 v68, 0, 32, vcc
	v_ldexp_f32 v56, v56, v68
	v_log_f32_e32 v56, v56
	s_nop 0
	v_mul_f32_e32 v68, 0x3f317217, v56
	v_fma_f32 v68, v56, s5, -v68
	v_fmac_f32_e32 v68, 0x3377d1cf, v56
	v_fmac_f32_e32 v68, 0x3f317217, v56
	v_cmp_lt_f32_e64 s[12:13], |v56|, s76
	s_nop 1
	v_cndmask_b32_e64 v56, v56, v68, s[12:13]
	v_cndmask_b32_e32 v68, 0, v199, vcc
	v_sub_f32_e32 v56, v56, v68
	v_mul_f32_e32 v68, 0x3fb8aa3b, v63
	v_exp_f32_e32 v68, v68
	s_nop 0
	v_add_f32_e32 v68, 1.0, v68
	v_rcp_f32_e32 v68, v68
	s_nop 0
	v_mul_f32_e32 v57, v68, v231
	v_mul_f32_e32 v68, 0x3fb8aa3b, v59
	v_exp_f32_e32 v68, v68
	v_min_f32_e32 v57, 0x3f7fffef, v57
	v_add_f32_e32 v68, 1.0, v68
	v_rcp_f32_e32 v68, v68
	s_nop 0
	v_mul_f32_e32 v53, v68, v235
	v_min_f32_e32 v68, 0x3f7fffef, v53
	v_sub_f32_e32 v53, 1.0, v57
	v_cmp_gt_f32_e32 vcc, s4, v53
	s_nop 1
	v_cndmask_b32_e64 v57, 0, 32, vcc
	v_ldexp_f32 v53, v53, v57
	v_log_f32_e32 v53, v53
	s_nop 0
	v_mul_f32_e32 v57, 0x3f317217, v53
	v_fma_f32 v57, v53, s5, -v57
	v_fmac_f32_e32 v57, 0x3377d1cf, v53
	v_fmac_f32_e32 v57, 0x3f317217, v53
	v_cmp_lt_f32_e64 s[12:13], |v53|, s76
	s_nop 1
	v_cndmask_b32_e64 v53, v53, v57, s[12:13]
	v_cndmask_b32_e32 v57, 0, v199, vcc
	v_sub_f32_e32 v53, v53, v57
	v_sub_f32_e32 v57, 1.0, v68
	v_cmp_gt_f32_e32 vcc, s4, v57
	s_nop 1
	v_cndmask_b32_e64 v68, 0, 32, vcc
	v_ldexp_f32 v57, v57, v68
	v_log_f32_e32 v57, v57
	s_nop 0
	v_mul_f32_e32 v68, 0x3f317217, v57
	v_fma_f32 v68, v57, s5, -v68
	v_fmac_f32_e32 v68, 0x3377d1cf, v57
	v_fmac_f32_e32 v68, 0x3f317217, v57
	v_cmp_lt_f32_e64 s[12:13], |v57|, s76
	s_mov_b64 s[4:5], 0
	s_nop 0
	v_cndmask_b32_e64 v57, v57, v68, s[12:13]
	v_cndmask_b32_e32 v68, 0, v199, vcc
	v_sub_f32_e32 v57, v57, v68
	v_lshl_add_u64 v[68:69], v[66:67], 2, s[86:87]
	global_store_dwordx4 v[68:69], v[50:53], off
	global_store_dwordx4 v[68:69], v[54:57], off offset:16

.LBB0_909:
	s_nop 1
	v_mov_b32_e32 v50, v145
	v_pk_mul_f32 v[56:57], v[48:49], v[50:51] op_sel_hi:[1,0]
	v_pk_mul_f32 v[58:59], v[46:47], v[50:51] op_sel_hi:[1,0]
	v_pk_mul_f32 v[52:53], v[44:45], v[50:51] op_sel_hi:[1,0]
	v_pk_mul_f32 v[54:55], v[42:43], v[50:51] op_sel_hi:[1,0]
	v_pk_mul_f32 v[46:47], v[40:41], v[50:51] op_sel_hi:[1,0]
	v_pk_mul_f32 v[48:49], v[38:39], v[50:51] op_sel_hi:[1,0]
	v_pk_mul_f32 v[42:43], v[36:37], v[50:51] op_sel_hi:[1,0]
	v_pk_mul_f32 v[44:45], v[34:35], v[50:51] op_sel_hi:[1,0]
	v_add_u32_e32 v50, s60, v175
	s_and_b64 vcc, exec, s[10:11]
	s_mov_b64 s[0:1], -1
	s_cbranch_vccnz .LBB0_911
	v_mul_f32_e32 v36, v59, v59
	v_fmac_f32_e32 v36, v58, v58
	v_fmac_f32_e32 v36, v56, v56
	v_fmac_f32_e32 v36, v57, v57
	v_fmac_f32_e32 v36, v54, v54
	v_fmac_f32_e32 v36, v55, v55
	v_fmac_f32_e32 v36, v52, v52
	v_fmac_f32_e32 v36, v53, v53
	v_fmac_f32_e32 v36, v48, v48
	v_fmac_f32_e32 v36, v49, v49
	v_fmac_f32_e32 v36, v46, v46
	v_fmac_f32_e32 v36, v47, v47
	v_fmac_f32_e32 v36, v44, v44
	v_fmac_f32_e32 v36, v45, v45
	v_pk_mul_f32 v[34:35], v[42:43], v[42:43]
	s_mov_b64 s[0:1], 0
	v_add_f32_e32 v34, v34, v36
	v_add_f32_e32 v34, v35, v34
	ds_bpermute_b32 v35, v174, v34
	s_waitcnt lgkmcnt(0)
	v_add_f32_e32 v34, v34, v35
	ds_bpermute_b32 v35, v173, v34
	s_waitcnt lgkmcnt(0)
	v_add_f32_e32 v34, v34, v35
	v_fmamk_f32 v34, v34, 0x3c800000, v188
	v_rsq_f32_e32 v34, v34
	s_nop 0
	v_mul_f32_e32 v51, 0x3e38aa3b, v34
	s_nop 0
	s_nop 0
	v_mul_f32_e32 v60, v58, v51
	v_mul_f32_e32 v68, v48, v51
	s_nop 0
	v_mul_f32_e32 v60, v204, v60
	v_mul_f32_e32 v38, v54, v51
	v_mul_f32_e32 v61, v208, v38
	v_mul_f32_e32 v34, v59, v51
	v_mul_f32_e32 v62, v205, v34
	v_mul_f32_e32 v34, v55, v51
	v_mul_f32_e32 v63, v209, v34
	v_mul_f32_e32 v34, v56, v51
	v_mul_f32_e32 v64, v206, v34
	v_mul_f32_e32 v34, v52, v51
	v_mul_f32_e32 v65, v210, v34
	v_mul_f32_e32 v34, v57, v51
	v_mul_f32_e32 v66, v207, v34
	v_mul_f32_e32 v34, v53, v51
	v_mul_f32_e32 v67, v211, v34
	s_nop 0
	s_nop 0
	s_nop 0
	v_mul_f32_e32 v68, v212, v68
	v_mul_f32_e32 v38, v44, v51
	v_mul_f32_e32 v69, v216, v38
	v_mul_f32_e32 v34, v49, v51
	v_mul_f32_e32 v70, v213, v34
	v_mul_f32_e32 v34, v45, v51
	v_mul_f32_e32 v71, v217, v34
	v_mul_f32_e32 v34, v46, v51
	v_mul_f32_e32 v72, v214, v34
	v_mul_f32_e32 v34, v42, v51
	v_mul_f32_e32 v73, v218, v34
	v_mul_f32_e32 v34, v47, v51
	v_mul_f32_e32 v74, v215, v34
	v_mul_f32_e32 v34, v43, v51
	v_ashrrev_i32_e32 v51, 31, v50
	v_lshlrev_b64 v[38:39], 9, v[50:51]
	v_lshl_add_u64 v[40:41], s[18:19], 0, v[38:39]
	v_lshl_add_u64 v[38:39], s[20:21], 0, v[38:39]
	v_lshl_add_u64 v[38:39], v[38:39], 0, v[126:127]
	v_add_co_u32_e32 v38, vcc, 0x3b6e9000, v38
	v_mul_f32_e32 v75, v219, v34
	v_cvt_pk_bf16_f32 v34, v60, v62
	v_cvt_pk_bf16_f32 v35, v64, v66
	v_cvt_pk_bf16_f32 v36, v61, v63
	v_cvt_pk_bf16_f32 v37, v65, v67
	v_lshl_add_u64 v[40:41], v[40:41], 0, v[126:127]
	v_addc_co_u32_e32 v39, vcc, 0, v39, vcc
	global_store_dwordx4 v[40:41], v[34:37], off
	s_nop 1
	v_cvt_pk_bf16_f32 v34, v68, v70
	v_cvt_pk_bf16_f32 v35, v72, v74
	v_cvt_pk_bf16_f32 v36, v69, v71
	v_cvt_pk_bf16_f32 v37, v73, v75
	global_store_dwordx4 v[38:39], v[34:37], off offset:320
.LBB0_911:
	s_andn2_b64 vcc, exec, s[0:1]
	s_cbranch_vccnz .LBB0_928
	v_mad_i64_i32 v[60:61], s[0:1], v50, s33, v[122:123]
	s_cmp_gt_i32 s71, 8
	s_mov_b64 s[0:1], -1
	s_cbranch_scc1 .LBB0_918
	s_cmp_lt_u32 s73, 5
	s_cselect_b64 s[0:1], -1, 0
	s_cmp_gt_u32 s73, 4
	s_cbranch_scc0 .LBB0_918
	s_andn2_b64 vcc, exec, s[28:29]
	s_mov_b64 s[4:5], -1
	s_cbranch_vccnz .LBB0_916
	v_lshl_add_u64 v[38:39], v[122:123], 2, s[16:17]
	s_nop 0
	s_nop 0
	s_nop 0
	v_mul_f32_e32 v51, 0x3fb8aa3b, v58
	v_exp_f32_e32 v51, v51
	s_mov_b32 s4, 0x800000
	s_mov_b32 s5, 0x3f317217
	s_mov_b32 s76, 0x7f800000
	v_add_f32_e32 v51, 1.0, v51
	v_rcp_f32_e32 v51, v51
	v_lshl_add_u64 v[62:63], v[60:61], 2, s[86:87]
	s_nop 0
	v_mul_f32_e32 v38, v51, v220
	v_mul_f32_e32 v51, 0x3fb8aa3b, v54
	v_exp_f32_e32 v51, v51
	v_min_f32_e32 v38, 0x3f7fffef, v38
	v_add_f32_e32 v51, 1.0, v51
	v_rcp_f32_e32 v51, v51
	s_nop 0
	v_mul_f32_e32 v34, v51, v224
	v_min_f32_e32 v51, 0x3f7fffef, v34
	v_sub_f32_e32 v34, 1.0, v38
	v_cmp_gt_f32_e32 vcc, s4, v34
	s_nop 1
	v_cndmask_b32_e64 v38, 0, 32, vcc
	v_ldexp_f32 v34, v34, v38
	v_log_f32_e32 v34, v34
	s_nop 0
	v_mul_f32_e32 v38, 0x3f317217, v34
	v_fma_f32 v38, v34, s5, -v38
	v_fmac_f32_e32 v38, 0x3377d1cf, v34
	v_fmac_f32_e32 v38, 0x3f317217, v34
	v_cmp_lt_f32_e64 s[12:13], |v34|, s76
	s_nop 1
	v_cndmask_b32_e64 v34, v34, v38, s[12:13]
	v_cndmask_b32_e32 v38, 0, v199, vcc
	v_sub_f32_e32 v34, v34, v38
	v_sub_f32_e32 v38, 1.0, v51
	v_cmp_gt_f32_e32 vcc, s4, v38
	s_nop 1
	v_cndmask_b32_e64 v51, 0, 32, vcc
	v_ldexp_f32 v38, v38, v51
	v_log_f32_e32 v38, v38
	s_nop 0
	v_mul_f32_e32 v51, 0x3f317217, v38
	v_fma_f32 v51, v38, s5, -v51
	v_fmac_f32_e32 v51, 0x3377d1cf, v38
	v_fmac_f32_e32 v51, 0x3f317217, v38
	v_cmp_lt_f32_e64 s[12:13], |v38|, s76
	s_nop 1
	v_cndmask_b32_e64 v38, v38, v51, s[12:13]
	v_cndmask_b32_e32 v51, 0, v199, vcc
	v_sub_f32_e32 v38, v38, v51
	v_mul_f32_e32 v51, 0x3fb8aa3b, v59
	v_exp_f32_e32 v51, v51
	s_nop 0
	v_add_f32_e32 v51, 1.0, v51
	v_rcp_f32_e32 v51, v51
	s_nop 0
	v_mul_f32_e32 v39, v51, v221
	v_mul_f32_e32 v51, 0x3fb8aa3b, v55
	v_exp_f32_e32 v51, v51
	v_min_f32_e32 v39, 0x3f7fffef, v39
	v_add_f32_e32 v51, 1.0, v51
	v_rcp_f32_e32 v51, v51
	s_nop 0
	v_mul_f32_e32 v35, v51, v225
	v_min_f32_e32 v51, 0x3f7fffef, v35
	v_sub_f32_e32 v35, 1.0, v39
	v_cmp_gt_f32_e32 vcc, s4, v35
	s_nop 1
	v_cndmask_b32_e64 v39, 0, 32, vcc
	v_ldexp_f32 v35, v35, v39
	v_log_f32_e32 v35, v35
	s_nop 0
	v_mul_f32_e32 v39, 0x3f317217, v35
	v_fma_f32 v39, v35, s5, -v39
	v_fmac_f32_e32 v39, 0x3377d1cf, v35
	v_fmac_f32_e32 v39, 0x3f317217, v35
	v_cmp_lt_f32_e64 s[12:13], |v35|, s76
	s_nop 1
	v_cndmask_b32_e64 v35, v35, v39, s[12:13]
	v_cndmask_b32_e32 v39, 0, v199, vcc
	v_sub_f32_e32 v35, v35, v39
	v_sub_f32_e32 v39, 1.0, v51
	v_cmp_gt_f32_e32 vcc, s4, v39
	s_nop 1
	v_cndmask_b32_e64 v51, 0, 32, vcc
	v_ldexp_f32 v39, v39, v51
	v_log_f32_e32 v39, v39
	s_nop 0
	v_mul_f32_e32 v51, 0x3f317217, v39
	v_fma_f32 v51, v39, s5, -v51
	v_fmac_f32_e32 v51, 0x3377d1cf, v39
	v_fmac_f32_e32 v51, 0x3f317217, v39
	v_cmp_lt_f32_e64 s[12:13], |v39|, s76
	s_nop 1
	v_cndmask_b32_e64 v39, v39, v51, s[12:13]
	v_cndmask_b32_e32 v51, 0, v199, vcc
	v_sub_f32_e32 v39, v39, v51
	v_mul_f32_e32 v51, 0x3fb8aa3b, v56
	v_exp_f32_e32 v51, v51
	s_nop 0
	v_add_f32_e32 v51, 1.0, v51
	v_rcp_f32_e32 v51, v51
	s_nop 0
	v_mul_f32_e32 v40, v51, v222
	v_mul_f32_e32 v51, 0x3fb8aa3b, v52
	v_exp_f32_e32 v51, v51
	v_min_f32_e32 v40, 0x3f7fffef, v40
	v_add_f32_e32 v51, 1.0, v51
	v_rcp_f32_e32 v51, v51
	s_nop 0
	v_mul_f32_e32 v36, v51, v226
	v_min_f32_e32 v51, 0x3f7fffef, v36
	v_sub_f32_e32 v36, 1.0, v40
	v_cmp_gt_f32_e32 vcc, s4, v36
	s_nop 1
	v_cndmask_b32_e64 v40, 0, 32, vcc
	v_ldexp_f32 v36, v36, v40
	v_log_f32_e32 v36, v36
	s_nop 0
	v_mul_f32_e32 v40, 0x3f317217, v36
	v_fma_f32 v40, v36, s5, -v40
	v_fmac_f32_e32 v40, 0x3377d1cf, v36
	v_fmac_f32_e32 v40, 0x3f317217, v36
	v_cmp_lt_f32_e64 s[12:13], |v36|, s76
	s_nop 1
	v_cndmask_b32_e64 v36, v36, v40, s[12:13]
	v_cndmask_b32_e32 v40, 0, v199, vcc
	v_sub_f32_e32 v36, v36, v40
	v_sub_f32_e32 v40, 1.0, v51
	v_cmp_gt_f32_e32 vcc, s4, v40
	s_nop 1
	v_cndmask_b32_e64 v51, 0, 32, vcc
	v_ldexp_f32 v40, v40, v51
	v_log_f32_e32 v40, v40
	s_nop 0
	v_mul_f32_e32 v51, 0x3f317217, v40
	v_fma_f32 v51, v40, s5, -v51
	v_fmac_f32_e32 v51, 0x3377d1cf, v40
	v_fmac_f32_e32 v51, 0x3f317217, v40
	v_cmp_lt_f32_e64 s[12:13], |v40|, s76
	s_nop 1
	v_cndmask_b32_e64 v40, v40, v51, s[12:13]
	v_cndmask_b32_e32 v51, 0, v199, vcc
	v_sub_f32_e32 v40, v40, v51
	v_mul_f32_e32 v51, 0x3fb8aa3b, v57
	v_exp_f32_e32 v51, v51
	s_nop 0
	v_add_f32_e32 v51, 1.0, v51
	v_rcp_f32_e32 v51, v51
	s_nop 0
	v_mul_f32_e32 v41, v51, v223
	v_mul_f32_e32 v51, 0x3fb8aa3b, v53
	v_exp_f32_e32 v51, v51
	v_min_f32_e32 v41, 0x3f7fffef, v41
	v_add_f32_e32 v51, 1.0, v51
	v_rcp_f32_e32 v51, v51
	s_nop 0
	v_mul_f32_e32 v37, v51, v227
	v_min_f32_e32 v51, 0x3f7fffef, v37
	v_sub_f32_e32 v37, 1.0, v41
	v_cmp_gt_f32_e32 vcc, s4, v37
	s_nop 1
	v_cndmask_b32_e64 v41, 0, 32, vcc
	v_ldexp_f32 v37, v37, v41
	v_log_f32_e32 v37, v37
	s_nop 0
	v_mul_f32_e32 v41, 0x3f317217, v37
	v_fma_f32 v41, v37, s5, -v41
	v_fmac_f32_e32 v41, 0x3377d1cf, v37
	v_fmac_f32_e32 v41, 0x3f317217, v37
	v_cmp_lt_f32_e64 s[12:13], |v37|, s76
	s_nop 1
	v_cndmask_b32_e64 v37, v37, v41, s[12:13]
	v_cndmask_b32_e32 v41, 0, v199, vcc
	v_sub_f32_e32 v37, v37, v41
	v_sub_f32_e32 v41, 1.0, v51
	v_cmp_gt_f32_e32 vcc, s4, v41
	s_nop 1
	v_cndmask_b32_e64 v51, 0, 32, vcc
	v_ldexp_f32 v41, v41, v51
	v_log_f32_e32 v41, v41
	s_nop 0
	v_mul_f32_e32 v51, 0x3f317217, v41
	v_fma_f32 v51, v41, s5, -v51
	v_fmac_f32_e32 v51, 0x3377d1cf, v41
	v_fmac_f32_e32 v51, 0x3f317217, v41
	v_cmp_lt_f32_e64 s[12:13], |v41|, s76
	s_mov_b64 s[4:5], 0
	s_nop 0
	v_cndmask_b32_e64 v41, v41, v51, s[12:13]
	v_cndmask_b32_e32 v51, 0, v199, vcc
	v_sub_f32_e32 v41, v41, v51
	global_store_dwordx4 v[62:63], v[34:37], off
	global_store_dwordx4 v[62:63], v[38:41], off offset:16

.LBB0_920:
	s_nop 1
	v_mad_i64_i32 v[34:35], s[0:1], v50, s33, 0
	v_lshl_add_u64 v[50:51], v[34:35], 0, v[124:125]
	s_cmp_gt_i32 s71, 8
	s_mov_b64 s[0:1], -1
	s_cbranch_scc1 .LBB0_926
	s_cmp_lt_u32 s73, 5
	s_cselect_b64 s[0:1], -1, 0
	s_cmp_gt_u32 s73, 4
	s_cbranch_scc0 .LBB0_926
	s_andn2_b64 vcc, exec, s[28:29]
	s_mov_b64 s[4:5], -1
	s_cbranch_vccnz .LBB0_924
	v_lshl_add_u64 v[38:39], v[122:123], 2, s[16:17]
	s_nop 0
	s_nop 0
	s_nop 0
	v_mul_f32_e32 v52, 0x3fb8aa3b, v48
	v_exp_f32_e32 v52, v52
	s_mov_b32 s4, 0x800000
	s_mov_b32 s5, 0x3f317217
	s_mov_b32 s76, 0x7f800000
	v_add_f32_e32 v52, 1.0, v52
	v_rcp_f32_e32 v52, v52
	s_nop 0
	v_mul_f32_e32 v38, v52, v228
	v_mul_f32_e32 v52, 0x3fb8aa3b, v44
	v_exp_f32_e32 v52, v52
	v_min_f32_e32 v38, 0x3f7fffef, v38
	v_add_f32_e32 v52, 1.0, v52
	v_rcp_f32_e32 v52, v52
	s_nop 0
	v_mul_f32_e32 v34, v52, v232
	v_min_f32_e32 v52, 0x3f7fffef, v34
	v_sub_f32_e32 v34, 1.0, v38
	v_cmp_gt_f32_e32 vcc, s4, v34
	s_nop 1
	v_cndmask_b32_e64 v38, 0, 32, vcc
	v_ldexp_f32 v34, v34, v38
	v_log_f32_e32 v34, v34
	s_nop 0
	v_mul_f32_e32 v38, 0x3f317217, v34
	v_fma_f32 v38, v34, s5, -v38
	v_fmac_f32_e32 v38, 0x3377d1cf, v34
	v_fmac_f32_e32 v38, 0x3f317217, v34
	v_cmp_lt_f32_e64 s[12:13], |v34|, s76
	s_nop 1
	v_cndmask_b32_e64 v34, v34, v38, s[12:13]
	v_cndmask_b32_e32 v38, 0, v199, vcc
	v_sub_f32_e32 v34, v34, v38
	v_sub_f32_e32 v38, 1.0, v52
	v_cmp_gt_f32_e32 vcc, s4, v38
	s_nop 1
	v_cndmask_b32_e64 v52, 0, 32, vcc
	v_ldexp_f32 v38, v38, v52
	v_log_f32_e32 v38, v38
	s_nop 0
	v_mul_f32_e32 v52, 0x3f317217, v38
	v_fma_f32 v52, v38, s5, -v52
	v_fmac_f32_e32 v52, 0x3377d1cf, v38
	v_fmac_f32_e32 v52, 0x3f317217, v38
	v_cmp_lt_f32_e64 s[12:13], |v38|, s76
	s_nop 1
	v_cndmask_b32_e64 v38, v38, v52, s[12:13]
	v_cndmask_b32_e32 v52, 0, v199, vcc
	v_sub_f32_e32 v38, v38, v52
	v_mul_f32_e32 v52, 0x3fb8aa3b, v49
	v_exp_f32_e32 v52, v52
	s_nop 0
	v_add_f32_e32 v52, 1.0, v52
	v_rcp_f32_e32 v52, v52
	s_nop 0
	v_mul_f32_e32 v39, v52, v229
	v_mul_f32_e32 v52, 0x3fb8aa3b, v45
	v_exp_f32_e32 v52, v52
	v_min_f32_e32 v39, 0x3f7fffef, v39
	v_add_f32_e32 v52, 1.0, v52
	v_rcp_f32_e32 v52, v52
	s_nop 0
	v_mul_f32_e32 v35, v52, v233
	v_min_f32_e32 v52, 0x3f7fffef, v35
	v_sub_f32_e32 v35, 1.0, v39
	v_cmp_gt_f32_e32 vcc, s4, v35
	s_nop 1
	v_cndmask_b32_e64 v39, 0, 32, vcc
	v_ldexp_f32 v35, v35, v39
	v_log_f32_e32 v35, v35
	s_nop 0
	v_mul_f32_e32 v39, 0x3f317217, v35
	v_fma_f32 v39, v35, s5, -v39
	v_fmac_f32_e32 v39, 0x3377d1cf, v35
	v_fmac_f32_e32 v39, 0x3f317217, v35
	v_cmp_lt_f32_e64 s[12:13], |v35|, s76
	s_nop 1
	v_cndmask_b32_e64 v35, v35, v39, s[12:13]
	v_cndmask_b32_e32 v39, 0, v199, vcc
	v_sub_f32_e32 v35, v35, v39
	v_sub_f32_e32 v39, 1.0, v52
	v_cmp_gt_f32_e32 vcc, s4, v39
	s_nop 1
	v_cndmask_b32_e64 v52, 0, 32, vcc
	v_ldexp_f32 v39, v39, v52
	v_log_f32_e32 v39, v39
	s_nop 0
	v_mul_f32_e32 v52, 0x3f317217, v39
	v_fma_f32 v52, v39, s5, -v52
	v_fmac_f32_e32 v52, 0x3377d1cf, v39
	v_fmac_f32_e32 v52, 0x3f317217, v39
	v_cmp_lt_f32_e64 s[12:13], |v39|, s76
	s_nop 1
	v_cndmask_b32_e64 v39, v39, v52, s[12:13]
	v_cndmask_b32_e32 v52, 0, v199, vcc
	v_sub_f32_e32 v39, v39, v52
	v_mul_f32_e32 v52, 0x3fb8aa3b, v46
	v_exp_f32_e32 v52, v52
	s_nop 0
	v_add_f32_e32 v52, 1.0, v52
	v_rcp_f32_e32 v52, v52
	s_nop 0
	v_mul_f32_e32 v40, v52, v230
	v_mul_f32_e32 v52, 0x3fb8aa3b, v42
	v_exp_f32_e32 v52, v52
	v_min_f32_e32 v40, 0x3f7fffef, v40
	v_add_f32_e32 v52, 1.0, v52
	v_rcp_f32_e32 v52, v52
	s_nop 0
	v_mul_f32_e32 v36, v52, v234
	v_min_f32_e32 v52, 0x3f7fffef, v36
	v_sub_f32_e32 v36, 1.0, v40
	v_cmp_gt_f32_e32 vcc, s4, v36
	s_nop 1
	v_cndmask_b32_e64 v40, 0, 32, vcc
	v_ldexp_f32 v36, v36, v40
	v_log_f32_e32 v36, v36
	s_nop 0
	v_mul_f32_e32 v40, 0x3f317217, v36
	v_fma_f32 v40, v36, s5, -v40
	v_fmac_f32_e32 v40, 0x3377d1cf, v36
	v_fmac_f32_e32 v40, 0x3f317217, v36
	v_cmp_lt_f32_e64 s[12:13], |v36|, s76
	s_nop 1
	v_cndmask_b32_e64 v36, v36, v40, s[12:13]
	v_cndmask_b32_e32 v40, 0, v199, vcc
	v_sub_f32_e32 v36, v36, v40
	v_sub_f32_e32 v40, 1.0, v52
	v_cmp_gt_f32_e32 vcc, s4, v40
	s_nop 1
	v_cndmask_b32_e64 v52, 0, 32, vcc
	v_ldexp_f32 v40, v40, v52
	v_log_f32_e32 v40, v40
	s_nop 0
	v_mul_f32_e32 v52, 0x3f317217, v40
	v_fma_f32 v52, v40, s5, -v52
	v_fmac_f32_e32 v52, 0x3377d1cf, v40
	v_fmac_f32_e32 v52, 0x3f317217, v40
	v_cmp_lt_f32_e64 s[12:13], |v40|, s76
	s_nop 1
	v_cndmask_b32_e64 v40, v40, v52, s[12:13]
	v_cndmask_b32_e32 v52, 0, v199, vcc
	v_sub_f32_e32 v40, v40, v52
	v_mul_f32_e32 v52, 0x3fb8aa3b, v47
	v_exp_f32_e32 v52, v52
	s_nop 0
	v_add_f32_e32 v52, 1.0, v52
	v_rcp_f32_e32 v52, v52
	s_nop 0
	v_mul_f32_e32 v41, v52, v231
	v_mul_f32_e32 v52, 0x3fb8aa3b, v43
	v_exp_f32_e32 v52, v52
	v_min_f32_e32 v41, 0x3f7fffef, v41
	v_add_f32_e32 v52, 1.0, v52
	v_rcp_f32_e32 v52, v52
	s_nop 0
	v_mul_f32_e32 v37, v52, v235
	v_min_f32_e32 v52, 0x3f7fffef, v37
	v_sub_f32_e32 v37, 1.0, v41
	v_cmp_gt_f32_e32 vcc, s4, v37
	s_nop 1
	v_cndmask_b32_e64 v41, 0, 32, vcc
	v_ldexp_f32 v37, v37, v41
	v_log_f32_e32 v37, v37
	s_nop 0
	v_mul_f32_e32 v41, 0x3f317217, v37
	v_fma_f32 v41, v37, s5, -v41
	v_fmac_f32_e32 v41, 0x3377d1cf, v37
	v_fmac_f32_e32 v41, 0x3f317217, v37
	v_cmp_lt_f32_e64 s[12:13], |v37|, s76
	s_nop 1
	v_cndmask_b32_e64 v37, v37, v41, s[12:13]
	v_cndmask_b32_e32 v41, 0, v199, vcc
	v_sub_f32_e32 v37, v37, v41
	v_sub_f32_e32 v41, 1.0, v52
	v_cmp_gt_f32_e32 vcc, s4, v41
	s_nop 1
	v_cndmask_b32_e64 v52, 0, 32, vcc
	v_ldexp_f32 v41, v41, v52
	v_log_f32_e32 v41, v41
	s_nop 0
	v_mul_f32_e32 v52, 0x3f317217, v41
	v_fma_f32 v52, v41, s5, -v52
	v_fmac_f32_e32 v52, 0x3377d1cf, v41
	v_fmac_f32_e32 v52, 0x3f317217, v41
	v_cmp_lt_f32_e64 s[12:13], |v41|, s76
	s_mov_b64 s[4:5], 0
	s_nop 0
	v_cndmask_b32_e64 v41, v41, v52, s[12:13]
	v_cndmask_b32_e32 v52, 0, v199, vcc
	v_sub_f32_e32 v41, v41, v52
	v_lshl_add_u64 v[52:53], v[50:51], 2, s[86:87]
	global_store_dwordx4 v[52:53], v[34:37], off
	global_store_dwordx4 v[52:53], v[38:41], off offset:16

.LBB0_928:
	v_pk_mul_f32 v[40:41], v[32:33], v[142:143] op_sel_hi:[1,0]
	v_pk_mul_f32 v[42:43], v[30:31], v[142:143] op_sel_hi:[1,0]
	v_pk_mul_f32 v[36:37], v[28:29], v[142:143] op_sel_hi:[1,0]
	v_pk_mul_f32 v[38:39], v[26:27], v[142:143] op_sel_hi:[1,0]
	v_pk_mul_f32 v[30:31], v[24:25], v[142:143] op_sel_hi:[1,0]
	v_pk_mul_f32 v[32:33], v[22:23], v[142:143] op_sel_hi:[1,0]
	v_pk_mul_f32 v[26:27], v[20:21], v[142:143] op_sel_hi:[1,0]
	v_pk_mul_f32 v[28:29], v[18:19], v[142:143] op_sel_hi:[1,0]
	v_add_u32_e32 v34, s61, v175
	s_and_b64 vcc, exec, s[10:11]
	s_mov_b64 s[0:1], -1
	s_cbranch_vccnz .LBB0_930
	v_mul_f32_e32 v20, v43, v43
	v_fmac_f32_e32 v20, v42, v42
	v_fmac_f32_e32 v20, v40, v40
	v_fmac_f32_e32 v20, v41, v41
	v_fmac_f32_e32 v20, v38, v38
	v_fmac_f32_e32 v20, v39, v39
	v_fmac_f32_e32 v20, v36, v36
	v_fmac_f32_e32 v20, v37, v37
	v_fmac_f32_e32 v20, v32, v32
	v_fmac_f32_e32 v20, v33, v33
	v_fmac_f32_e32 v20, v30, v30
	v_fmac_f32_e32 v20, v31, v31
	v_fmac_f32_e32 v20, v28, v28
	v_fmac_f32_e32 v20, v29, v29
	v_pk_mul_f32 v[18:19], v[26:27], v[26:27]
	s_mov_b64 s[0:1], 0
	v_add_f32_e32 v18, v18, v20
	v_add_f32_e32 v18, v19, v18
	ds_bpermute_b32 v19, v174, v18
	s_waitcnt lgkmcnt(0)
	v_add_f32_e32 v18, v18, v19
	ds_bpermute_b32 v19, v173, v18
	s_waitcnt lgkmcnt(0)
	v_add_f32_e32 v18, v18, v19
	v_fmamk_f32 v18, v18, 0x3c800000, v188
	v_rsq_f32_e32 v18, v18
	s_nop 0
	v_mul_f32_e32 v35, 0x3e38aa3b, v18
	s_nop 0
	s_nop 0
	v_mul_f32_e32 v44, v42, v35
	v_mul_f32_e32 v52, v32, v35
	s_nop 0
	v_mul_f32_e32 v44, v204, v44
	v_mul_f32_e32 v22, v38, v35
	v_mul_f32_e32 v45, v208, v22
	v_mul_f32_e32 v18, v43, v35
	v_mul_f32_e32 v46, v205, v18
	v_mul_f32_e32 v18, v39, v35
	v_mul_f32_e32 v47, v209, v18
	v_mul_f32_e32 v18, v40, v35
	v_mul_f32_e32 v48, v206, v18
	v_mul_f32_e32 v18, v36, v35
	v_mul_f32_e32 v49, v210, v18
	v_mul_f32_e32 v18, v41, v35
	v_mul_f32_e32 v50, v207, v18
	v_mul_f32_e32 v18, v37, v35
	v_mul_f32_e32 v51, v211, v18
	s_nop 0
	s_nop 0
	s_nop 0
	v_mul_f32_e32 v52, v212, v52
	v_mul_f32_e32 v22, v28, v35
	v_mul_f32_e32 v53, v216, v22
	v_mul_f32_e32 v18, v33, v35
	v_mul_f32_e32 v54, v213, v18
	v_mul_f32_e32 v18, v29, v35
	v_mul_f32_e32 v55, v217, v18
	v_mul_f32_e32 v18, v30, v35
	v_mul_f32_e32 v56, v214, v18
	v_mul_f32_e32 v18, v26, v35
	v_mul_f32_e32 v57, v218, v18
	v_mul_f32_e32 v18, v31, v35
	v_mul_f32_e32 v58, v215, v18
	v_mul_f32_e32 v18, v27, v35
	v_ashrrev_i32_e32 v35, 31, v34
	v_lshlrev_b64 v[22:23], 9, v[34:35]
	v_lshl_add_u64 v[24:25], s[18:19], 0, v[22:23]
	v_lshl_add_u64 v[22:23], s[20:21], 0, v[22:23]
	v_lshl_add_u64 v[22:23], v[22:23], 0, v[126:127]
	v_add_co_u32_e32 v22, vcc, 0x3b6e9000, v22
	v_mul_f32_e32 v59, v219, v18
	v_cvt_pk_bf16_f32 v18, v44, v46
	v_cvt_pk_bf16_f32 v19, v48, v50
	v_cvt_pk_bf16_f32 v20, v45, v47
	v_cvt_pk_bf16_f32 v21, v49, v51
	v_lshl_add_u64 v[24:25], v[24:25], 0, v[126:127]
	v_addc_co_u32_e32 v23, vcc, 0, v23, vcc
	global_store_dwordx4 v[24:25], v[18:21], off
	s_nop 1
	v_cvt_pk_bf16_f32 v18, v52, v54
	v_cvt_pk_bf16_f32 v19, v56, v58
	v_cvt_pk_bf16_f32 v20, v53, v55
	v_cvt_pk_bf16_f32 v21, v57, v59
	global_store_dwordx4 v[22:23], v[18:21], off offset:320
.LBB0_930:
	s_andn2_b64 vcc, exec, s[0:1]
	s_cbranch_vccnz .LBB0_947
	v_mad_i64_i32 v[44:45], s[0:1], v34, s33, v[122:123]
	s_cmp_gt_i32 s71, 8
	s_mov_b64 s[0:1], -1
	s_cbranch_scc1 .LBB0_937
	s_cmp_lt_u32 s73, 5
	s_cselect_b64 s[0:1], -1, 0
	s_cmp_gt_u32 s73, 4
	s_cbranch_scc0 .LBB0_937
	s_andn2_b64 vcc, exec, s[28:29]
	s_mov_b64 s[4:5], -1
	s_cbranch_vccnz .LBB0_935
	v_lshl_add_u64 v[22:23], v[122:123], 2, s[16:17]
	s_nop 0
	s_nop 0
	s_nop 0
	v_mul_f32_e32 v35, 0x3fb8aa3b, v42
	v_exp_f32_e32 v35, v35
	s_mov_b32 s4, 0x800000
	s_mov_b32 s5, 0x3f317217
	s_mov_b32 s76, 0x7f800000
	v_add_f32_e32 v35, 1.0, v35
	v_rcp_f32_e32 v35, v35
	v_lshl_add_u64 v[46:47], v[44:45], 2, s[86:87]
	s_nop 0
	v_mul_f32_e32 v22, v35, v220
	v_mul_f32_e32 v35, 0x3fb8aa3b, v38
	v_exp_f32_e32 v35, v35
	v_min_f32_e32 v22, 0x3f7fffef, v22
	v_add_f32_e32 v35, 1.0, v35
	v_rcp_f32_e32 v35, v35
	s_nop 0
	v_mul_f32_e32 v18, v35, v224
	v_min_f32_e32 v35, 0x3f7fffef, v18
	v_sub_f32_e32 v18, 1.0, v22
	v_cmp_gt_f32_e32 vcc, s4, v18
	s_nop 1
	v_cndmask_b32_e64 v22, 0, 32, vcc
	v_ldexp_f32 v18, v18, v22
	v_log_f32_e32 v18, v18
	s_nop 0
	v_mul_f32_e32 v22, 0x3f317217, v18
	v_fma_f32 v22, v18, s5, -v22
	v_fmac_f32_e32 v22, 0x3377d1cf, v18
	v_fmac_f32_e32 v22, 0x3f317217, v18
	v_cmp_lt_f32_e64 s[12:13], |v18|, s76
	s_nop 1
	v_cndmask_b32_e64 v18, v18, v22, s[12:13]
	v_cndmask_b32_e32 v22, 0, v199, vcc
	v_sub_f32_e32 v18, v18, v22
	v_sub_f32_e32 v22, 1.0, v35
	v_cmp_gt_f32_e32 vcc, s4, v22
	s_nop 1
	v_cndmask_b32_e64 v35, 0, 32, vcc
	v_ldexp_f32 v22, v22, v35
	v_log_f32_e32 v22, v22
	s_nop 0
	v_mul_f32_e32 v35, 0x3f317217, v22
	v_fma_f32 v35, v22, s5, -v35
	v_fmac_f32_e32 v35, 0x3377d1cf, v22
	v_fmac_f32_e32 v35, 0x3f317217, v22
	v_cmp_lt_f32_e64 s[12:13], |v22|, s76
	s_nop 1
	v_cndmask_b32_e64 v22, v22, v35, s[12:13]
	v_cndmask_b32_e32 v35, 0, v199, vcc
	v_sub_f32_e32 v22, v22, v35
	v_mul_f32_e32 v35, 0x3fb8aa3b, v43
	v_exp_f32_e32 v35, v35
	s_nop 0
	v_add_f32_e32 v35, 1.0, v35
	v_rcp_f32_e32 v35, v35
	s_nop 0
	v_mul_f32_e32 v23, v35, v221
	v_mul_f32_e32 v35, 0x3fb8aa3b, v39
	v_exp_f32_e32 v35, v35
	v_min_f32_e32 v23, 0x3f7fffef, v23
	v_add_f32_e32 v35, 1.0, v35
	v_rcp_f32_e32 v35, v35
	s_nop 0
	v_mul_f32_e32 v19, v35, v225
	v_min_f32_e32 v35, 0x3f7fffef, v19
	v_sub_f32_e32 v19, 1.0, v23
	v_cmp_gt_f32_e32 vcc, s4, v19
	s_nop 1
	v_cndmask_b32_e64 v23, 0, 32, vcc
	v_ldexp_f32 v19, v19, v23
	v_log_f32_e32 v19, v19
	s_nop 0
	v_mul_f32_e32 v23, 0x3f317217, v19
	v_fma_f32 v23, v19, s5, -v23
	v_fmac_f32_e32 v23, 0x3377d1cf, v19
	v_fmac_f32_e32 v23, 0x3f317217, v19
	v_cmp_lt_f32_e64 s[12:13], |v19|, s76
	s_nop 1
	v_cndmask_b32_e64 v19, v19, v23, s[12:13]
	v_cndmask_b32_e32 v23, 0, v199, vcc
	v_sub_f32_e32 v19, v19, v23
	v_sub_f32_e32 v23, 1.0, v35
	v_cmp_gt_f32_e32 vcc, s4, v23
	s_nop 1
	v_cndmask_b32_e64 v35, 0, 32, vcc
	v_ldexp_f32 v23, v23, v35
	v_log_f32_e32 v23, v23
	s_nop 0
	v_mul_f32_e32 v35, 0x3f317217, v23
	v_fma_f32 v35, v23, s5, -v35
	v_fmac_f32_e32 v35, 0x3377d1cf, v23
	v_fmac_f32_e32 v35, 0x3f317217, v23
	v_cmp_lt_f32_e64 s[12:13], |v23|, s76
	s_nop 1
	v_cndmask_b32_e64 v23, v23, v35, s[12:13]
	v_cndmask_b32_e32 v35, 0, v199, vcc
	v_sub_f32_e32 v23, v23, v35
	v_mul_f32_e32 v35, 0x3fb8aa3b, v40
	v_exp_f32_e32 v35, v35
	s_nop 0
	v_add_f32_e32 v35, 1.0, v35
	v_rcp_f32_e32 v35, v35
	s_nop 0
	v_mul_f32_e32 v24, v35, v222
	v_mul_f32_e32 v35, 0x3fb8aa3b, v36
	v_exp_f32_e32 v35, v35
	v_min_f32_e32 v24, 0x3f7fffef, v24
	v_add_f32_e32 v35, 1.0, v35
	v_rcp_f32_e32 v35, v35
	s_nop 0
	v_mul_f32_e32 v20, v35, v226
	v_min_f32_e32 v35, 0x3f7fffef, v20
	v_sub_f32_e32 v20, 1.0, v24
	v_cmp_gt_f32_e32 vcc, s4, v20
	s_nop 1
	v_cndmask_b32_e64 v24, 0, 32, vcc
	v_ldexp_f32 v20, v20, v24
	v_log_f32_e32 v20, v20
	s_nop 0
	v_mul_f32_e32 v24, 0x3f317217, v20
	v_fma_f32 v24, v20, s5, -v24
	v_fmac_f32_e32 v24, 0x3377d1cf, v20
	v_fmac_f32_e32 v24, 0x3f317217, v20
	v_cmp_lt_f32_e64 s[12:13], |v20|, s76
	s_nop 1
	v_cndmask_b32_e64 v20, v20, v24, s[12:13]
	v_cndmask_b32_e32 v24, 0, v199, vcc
	v_sub_f32_e32 v20, v20, v24
	v_sub_f32_e32 v24, 1.0, v35
	v_cmp_gt_f32_e32 vcc, s4, v24
	s_nop 1
	v_cndmask_b32_e64 v35, 0, 32, vcc
	v_ldexp_f32 v24, v24, v35
	v_log_f32_e32 v24, v24
	s_nop 0
	v_mul_f32_e32 v35, 0x3f317217, v24
	v_fma_f32 v35, v24, s5, -v35
	v_fmac_f32_e32 v35, 0x3377d1cf, v24
	v_fmac_f32_e32 v35, 0x3f317217, v24
	v_cmp_lt_f32_e64 s[12:13], |v24|, s76
	s_nop 1
	v_cndmask_b32_e64 v24, v24, v35, s[12:13]
	v_cndmask_b32_e32 v35, 0, v199, vcc
	v_sub_f32_e32 v24, v24, v35
	v_mul_f32_e32 v35, 0x3fb8aa3b, v41
	v_exp_f32_e32 v35, v35
	s_nop 0
	v_add_f32_e32 v35, 1.0, v35
	v_rcp_f32_e32 v35, v35
	s_nop 0
	v_mul_f32_e32 v25, v35, v223
	v_mul_f32_e32 v35, 0x3fb8aa3b, v37
	v_exp_f32_e32 v35, v35
	v_min_f32_e32 v25, 0x3f7fffef, v25
	v_add_f32_e32 v35, 1.0, v35
	v_rcp_f32_e32 v35, v35
	s_nop 0
	v_mul_f32_e32 v21, v35, v227
	v_min_f32_e32 v35, 0x3f7fffef, v21
	v_sub_f32_e32 v21, 1.0, v25
	v_cmp_gt_f32_e32 vcc, s4, v21
	s_nop 1
	v_cndmask_b32_e64 v25, 0, 32, vcc
	v_ldexp_f32 v21, v21, v25
	v_log_f32_e32 v21, v21
	s_nop 0
	v_mul_f32_e32 v25, 0x3f317217, v21
	v_fma_f32 v25, v21, s5, -v25
	v_fmac_f32_e32 v25, 0x3377d1cf, v21
	v_fmac_f32_e32 v25, 0x3f317217, v21
	v_cmp_lt_f32_e64 s[12:13], |v21|, s76
	s_nop 1
	v_cndmask_b32_e64 v21, v21, v25, s[12:13]
	v_cndmask_b32_e32 v25, 0, v199, vcc
	v_sub_f32_e32 v21, v21, v25
	v_sub_f32_e32 v25, 1.0, v35
	v_cmp_gt_f32_e32 vcc, s4, v25
	s_nop 1
	v_cndmask_b32_e64 v35, 0, 32, vcc
	v_ldexp_f32 v25, v25, v35
	v_log_f32_e32 v25, v25
	s_nop 0
	v_mul_f32_e32 v35, 0x3f317217, v25
	v_fma_f32 v35, v25, s5, -v35
	v_fmac_f32_e32 v35, 0x3377d1cf, v25
	v_fmac_f32_e32 v35, 0x3f317217, v25
	v_cmp_lt_f32_e64 s[12:13], |v25|, s76
	s_mov_b64 s[4:5], 0
	s_nop 0
	v_cndmask_b32_e64 v25, v25, v35, s[12:13]
	v_cndmask_b32_e32 v35, 0, v199, vcc
	v_sub_f32_e32 v25, v25, v35
	global_store_dwordx4 v[46:47], v[18:21], off
	global_store_dwordx4 v[46:47], v[22:25], off offset:16

.LBB0_939:
	s_nop 1
	v_mad_i64_i32 v[18:19], s[0:1], v34, s33, 0
	v_lshl_add_u64 v[34:35], v[18:19], 0, v[124:125]
	s_cmp_gt_i32 s71, 8
	s_mov_b64 s[0:1], -1
	s_cbranch_scc1 .LBB0_945
	s_cmp_lt_u32 s73, 5
	s_cselect_b64 s[0:1], -1, 0
	s_cmp_gt_u32 s73, 4
	s_cbranch_scc0 .LBB0_945
	s_andn2_b64 vcc, exec, s[28:29]
	s_mov_b64 s[4:5], -1
	s_cbranch_vccnz .LBB0_943
	v_lshl_add_u64 v[22:23], v[122:123], 2, s[16:17]
	s_nop 0
	s_nop 0
	s_nop 0
	v_mul_f32_e32 v36, 0x3fb8aa3b, v32
	v_exp_f32_e32 v36, v36
	s_mov_b32 s4, 0x800000
	s_mov_b32 s5, 0x3f317217
	s_mov_b32 s76, 0x7f800000
	v_add_f32_e32 v36, 1.0, v36
	v_rcp_f32_e32 v36, v36
	s_nop 0
	v_mul_f32_e32 v22, v36, v228
	v_mul_f32_e32 v36, 0x3fb8aa3b, v28
	v_exp_f32_e32 v36, v36
	v_min_f32_e32 v22, 0x3f7fffef, v22
	v_add_f32_e32 v36, 1.0, v36
	v_rcp_f32_e32 v36, v36
	s_nop 0
	v_mul_f32_e32 v18, v36, v232
	v_min_f32_e32 v36, 0x3f7fffef, v18
	v_sub_f32_e32 v18, 1.0, v22
	v_cmp_gt_f32_e32 vcc, s4, v18
	s_nop 1
	v_cndmask_b32_e64 v22, 0, 32, vcc
	v_ldexp_f32 v18, v18, v22
	v_log_f32_e32 v18, v18
	s_nop 0
	v_mul_f32_e32 v22, 0x3f317217, v18
	v_fma_f32 v22, v18, s5, -v22
	v_fmac_f32_e32 v22, 0x3377d1cf, v18
	v_fmac_f32_e32 v22, 0x3f317217, v18
	v_cmp_lt_f32_e64 s[12:13], |v18|, s76
	s_nop 1
	v_cndmask_b32_e64 v18, v18, v22, s[12:13]
	v_cndmask_b32_e32 v22, 0, v199, vcc
	v_sub_f32_e32 v18, v18, v22
	v_sub_f32_e32 v22, 1.0, v36
	v_cmp_gt_f32_e32 vcc, s4, v22
	s_nop 1
	v_cndmask_b32_e64 v36, 0, 32, vcc
	v_ldexp_f32 v22, v22, v36
	v_log_f32_e32 v22, v22
	s_nop 0
	v_mul_f32_e32 v36, 0x3f317217, v22
	v_fma_f32 v36, v22, s5, -v36
	v_fmac_f32_e32 v36, 0x3377d1cf, v22
	v_fmac_f32_e32 v36, 0x3f317217, v22
	v_cmp_lt_f32_e64 s[12:13], |v22|, s76
	s_nop 1
	v_cndmask_b32_e64 v22, v22, v36, s[12:13]
	v_cndmask_b32_e32 v36, 0, v199, vcc
	v_sub_f32_e32 v22, v22, v36
	v_mul_f32_e32 v36, 0x3fb8aa3b, v33
	v_exp_f32_e32 v36, v36
	s_nop 0
	v_add_f32_e32 v36, 1.0, v36
	v_rcp_f32_e32 v36, v36
	s_nop 0
	v_mul_f32_e32 v23, v36, v229
	v_mul_f32_e32 v36, 0x3fb8aa3b, v29
	v_exp_f32_e32 v36, v36
	v_min_f32_e32 v23, 0x3f7fffef, v23
	v_add_f32_e32 v36, 1.0, v36
	v_rcp_f32_e32 v36, v36
	s_nop 0
	v_mul_f32_e32 v19, v36, v233
	v_min_f32_e32 v36, 0x3f7fffef, v19
	v_sub_f32_e32 v19, 1.0, v23
	v_cmp_gt_f32_e32 vcc, s4, v19
	s_nop 1
	v_cndmask_b32_e64 v23, 0, 32, vcc
	v_ldexp_f32 v19, v19, v23
	v_log_f32_e32 v19, v19
	s_nop 0
	v_mul_f32_e32 v23, 0x3f317217, v19
	v_fma_f32 v23, v19, s5, -v23
	v_fmac_f32_e32 v23, 0x3377d1cf, v19
	v_fmac_f32_e32 v23, 0x3f317217, v19
	v_cmp_lt_f32_e64 s[12:13], |v19|, s76
	s_nop 1
	v_cndmask_b32_e64 v19, v19, v23, s[12:13]
	v_cndmask_b32_e32 v23, 0, v199, vcc
	v_sub_f32_e32 v19, v19, v23
	v_sub_f32_e32 v23, 1.0, v36
	v_cmp_gt_f32_e32 vcc, s4, v23
	s_nop 1
	v_cndmask_b32_e64 v36, 0, 32, vcc
	v_ldexp_f32 v23, v23, v36
	v_log_f32_e32 v23, v23
	s_nop 0
	v_mul_f32_e32 v36, 0x3f317217, v23
	v_fma_f32 v36, v23, s5, -v36
	v_fmac_f32_e32 v36, 0x3377d1cf, v23
	v_fmac_f32_e32 v36, 0x3f317217, v23
	v_cmp_lt_f32_e64 s[12:13], |v23|, s76
	s_nop 1
	v_cndmask_b32_e64 v23, v23, v36, s[12:13]
	v_cndmask_b32_e32 v36, 0, v199, vcc
	v_sub_f32_e32 v23, v23, v36
	v_mul_f32_e32 v36, 0x3fb8aa3b, v30
	v_exp_f32_e32 v36, v36
	s_nop 0
	v_add_f32_e32 v36, 1.0, v36
	v_rcp_f32_e32 v36, v36
	s_nop 0
	v_mul_f32_e32 v24, v36, v230
	v_mul_f32_e32 v36, 0x3fb8aa3b, v26
	v_exp_f32_e32 v36, v36
	v_min_f32_e32 v24, 0x3f7fffef, v24
	v_add_f32_e32 v36, 1.0, v36
	v_rcp_f32_e32 v36, v36
	s_nop 0
	v_mul_f32_e32 v20, v36, v234
	v_min_f32_e32 v36, 0x3f7fffef, v20
	v_sub_f32_e32 v20, 1.0, v24
	v_cmp_gt_f32_e32 vcc, s4, v20
	s_nop 1
	v_cndmask_b32_e64 v24, 0, 32, vcc
	v_ldexp_f32 v20, v20, v24
	v_log_f32_e32 v20, v20
	s_nop 0
	v_mul_f32_e32 v24, 0x3f317217, v20
	v_fma_f32 v24, v20, s5, -v24
	v_fmac_f32_e32 v24, 0x3377d1cf, v20
	v_fmac_f32_e32 v24, 0x3f317217, v20
	v_cmp_lt_f32_e64 s[12:13], |v20|, s76
	s_nop 1
	v_cndmask_b32_e64 v20, v20, v24, s[12:13]
	v_cndmask_b32_e32 v24, 0, v199, vcc
	v_sub_f32_e32 v20, v20, v24
	v_sub_f32_e32 v24, 1.0, v36
	v_cmp_gt_f32_e32 vcc, s4, v24
	s_nop 1
	v_cndmask_b32_e64 v36, 0, 32, vcc
	v_ldexp_f32 v24, v24, v36
	v_log_f32_e32 v24, v24
	s_nop 0
	v_mul_f32_e32 v36, 0x3f317217, v24
	v_fma_f32 v36, v24, s5, -v36
	v_fmac_f32_e32 v36, 0x3377d1cf, v24
	v_fmac_f32_e32 v36, 0x3f317217, v24
	v_cmp_lt_f32_e64 s[12:13], |v24|, s76
	s_nop 1
	v_cndmask_b32_e64 v24, v24, v36, s[12:13]
	v_cndmask_b32_e32 v36, 0, v199, vcc
	v_sub_f32_e32 v24, v24, v36
	v_mul_f32_e32 v36, 0x3fb8aa3b, v31
	v_exp_f32_e32 v36, v36
	s_nop 0
	v_add_f32_e32 v36, 1.0, v36
	v_rcp_f32_e32 v36, v36
	s_nop 0
	v_mul_f32_e32 v25, v36, v231
	v_mul_f32_e32 v36, 0x3fb8aa3b, v27
	v_exp_f32_e32 v36, v36
	v_min_f32_e32 v25, 0x3f7fffef, v25
	v_add_f32_e32 v36, 1.0, v36
	v_rcp_f32_e32 v36, v36
	s_nop 0
	v_mul_f32_e32 v21, v36, v235
	v_min_f32_e32 v36, 0x3f7fffef, v21
	v_sub_f32_e32 v21, 1.0, v25
	v_cmp_gt_f32_e32 vcc, s4, v21
	s_nop 1
	v_cndmask_b32_e64 v25, 0, 32, vcc
	v_ldexp_f32 v21, v21, v25
	v_log_f32_e32 v21, v21
	s_nop 0
	v_mul_f32_e32 v25, 0x3f317217, v21
	v_fma_f32 v25, v21, s5, -v25
	v_fmac_f32_e32 v25, 0x3377d1cf, v21
	v_fmac_f32_e32 v25, 0x3f317217, v21
	v_cmp_lt_f32_e64 s[12:13], |v21|, s76
	s_nop 1
	v_cndmask_b32_e64 v21, v21, v25, s[12:13]
	v_cndmask_b32_e32 v25, 0, v199, vcc
	v_sub_f32_e32 v21, v21, v25
	v_sub_f32_e32 v25, 1.0, v36
	v_cmp_gt_f32_e32 vcc, s4, v25
	s_nop 1
	v_cndmask_b32_e64 v36, 0, 32, vcc
	v_ldexp_f32 v25, v25, v36
	v_log_f32_e32 v25, v25
	s_nop 0
	v_mul_f32_e32 v36, 0x3f317217, v25
	v_fma_f32 v36, v25, s5, -v36
	v_fmac_f32_e32 v36, 0x3377d1cf, v25
	v_fmac_f32_e32 v36, 0x3f317217, v25
	v_cmp_lt_f32_e64 s[12:13], |v25|, s76
	s_mov_b64 s[4:5], 0
	s_nop 0
	v_cndmask_b32_e64 v25, v25, v36, s[12:13]
	v_cndmask_b32_e32 v36, 0, v199, vcc
	v_sub_f32_e32 v25, v25, v36
	v_lshl_add_u64 v[36:37], v[34:35], 2, s[86:87]
	global_store_dwordx4 v[36:37], v[18:21], off
	global_store_dwordx4 v[36:37], v[22:25], off offset:16

.LBB0_947:
	s_nop 1
	v_mov_b32_e32 v18, v143
	v_pk_mul_f32 v[24:25], v[16:17], v[18:19] op_sel_hi:[1,0]
	v_pk_mul_f32 v[26:27], v[14:15], v[18:19] op_sel_hi:[1,0]
	v_pk_mul_f32 v[20:21], v[12:13], v[18:19] op_sel_hi:[1,0]
	v_pk_mul_f32 v[22:23], v[10:11], v[18:19] op_sel_hi:[1,0]
	v_pk_mul_f32 v[14:15], v[8:9], v[18:19] op_sel_hi:[1,0]
	v_pk_mul_f32 v[16:17], v[6:7], v[18:19] op_sel_hi:[1,0]
	v_pk_mul_f32 v[10:11], v[4:5], v[18:19] op_sel_hi:[1,0]
	v_pk_mul_f32 v[12:13], v[2:3], v[18:19] op_sel_hi:[1,0]
	v_add_u32_e32 v18, s62, v175
	s_and_b64 vcc, exec, s[10:11]
	s_mov_b64 s[0:1], -1
	s_cbranch_vccnz .LBB0_949
	v_mul_f32_e32 v4, v27, v27
	v_fmac_f32_e32 v4, v26, v26
	v_fmac_f32_e32 v4, v24, v24
	v_fmac_f32_e32 v4, v25, v25
	v_fmac_f32_e32 v4, v22, v22
	v_fmac_f32_e32 v4, v23, v23
	v_fmac_f32_e32 v4, v20, v20
	v_fmac_f32_e32 v4, v21, v21
	v_fmac_f32_e32 v4, v16, v16
	v_fmac_f32_e32 v4, v17, v17
	v_fmac_f32_e32 v4, v14, v14
	v_fmac_f32_e32 v4, v15, v15
	v_fmac_f32_e32 v4, v12, v12
	v_fmac_f32_e32 v4, v13, v13
	v_pk_mul_f32 v[2:3], v[10:11], v[10:11]
	s_mov_b64 s[0:1], 0
	v_add_f32_e32 v2, v2, v4
	v_add_f32_e32 v2, v3, v2
	ds_bpermute_b32 v3, v174, v2
	s_waitcnt lgkmcnt(0)
	v_add_f32_e32 v2, v2, v3
	ds_bpermute_b32 v3, v173, v2
	s_waitcnt lgkmcnt(0)
	v_add_f32_e32 v2, v2, v3
	v_fmamk_f32 v2, v2, 0x3c800000, v188
	v_rsq_f32_e32 v2, v2
	s_nop 0
	v_mul_f32_e32 v19, 0x3e38aa3b, v2
	s_nop 0
	s_nop 0
	v_mul_f32_e32 v28, v26, v19
	v_mul_f32_e32 v36, v16, v19
	s_nop 0
	v_mul_f32_e32 v28, v204, v28
	v_mul_f32_e32 v6, v22, v19
	v_mul_f32_e32 v29, v208, v6
	v_mul_f32_e32 v2, v27, v19
	v_mul_f32_e32 v30, v205, v2
	v_mul_f32_e32 v2, v23, v19
	v_mul_f32_e32 v31, v209, v2
	v_mul_f32_e32 v2, v24, v19
	v_mul_f32_e32 v32, v206, v2
	v_mul_f32_e32 v2, v20, v19
	v_mul_f32_e32 v33, v210, v2
	v_mul_f32_e32 v2, v25, v19
	v_mul_f32_e32 v34, v207, v2
	v_mul_f32_e32 v2, v21, v19
	v_mul_f32_e32 v35, v211, v2
	s_nop 0
	s_nop 0
	s_nop 0
	v_mul_f32_e32 v36, v212, v36
	v_mul_f32_e32 v6, v12, v19
	v_mul_f32_e32 v37, v216, v6
	v_mul_f32_e32 v2, v17, v19
	v_mul_f32_e32 v38, v213, v2
	v_mul_f32_e32 v2, v13, v19
	v_mul_f32_e32 v39, v217, v2
	v_mul_f32_e32 v2, v14, v19
	v_mul_f32_e32 v40, v214, v2
	v_mul_f32_e32 v2, v10, v19
	v_mul_f32_e32 v41, v218, v2
	v_mul_f32_e32 v2, v15, v19
	v_mul_f32_e32 v42, v215, v2
	v_mul_f32_e32 v2, v11, v19
	v_ashrrev_i32_e32 v19, 31, v18
	v_lshlrev_b64 v[6:7], 9, v[18:19]
	v_lshl_add_u64 v[8:9], s[18:19], 0, v[6:7]
	v_lshl_add_u64 v[6:7], s[20:21], 0, v[6:7]
	v_lshl_add_u64 v[6:7], v[6:7], 0, v[126:127]
	v_add_co_u32_e32 v6, vcc, 0x3b6e9000, v6
	v_mul_f32_e32 v43, v219, v2
	v_cvt_pk_bf16_f32 v2, v28, v30
	v_cvt_pk_bf16_f32 v3, v32, v34
	v_cvt_pk_bf16_f32 v4, v29, v31
	v_cvt_pk_bf16_f32 v5, v33, v35
	v_lshl_add_u64 v[8:9], v[8:9], 0, v[126:127]
	v_addc_co_u32_e32 v7, vcc, 0, v7, vcc
	global_store_dwordx4 v[8:9], v[2:5], off
	s_nop 1
	v_cvt_pk_bf16_f32 v2, v36, v38
	v_cvt_pk_bf16_f32 v3, v40, v42
	v_cvt_pk_bf16_f32 v4, v37, v39
	v_cvt_pk_bf16_f32 v5, v41, v43
	global_store_dwordx4 v[6:7], v[2:5], off offset:320
.LBB0_949:
	s_andn2_b64 vcc, exec, s[0:1]
	s_cbranch_vccnz .LBB0_794
	v_mad_i64_i32 v[28:29], s[0:1], v18, s33, v[122:123]
	s_cmp_gt_i32 s71, 8
	s_mov_b64 s[0:1], -1
	s_cbranch_scc1 .LBB0_956
	s_cmp_lt_u32 s73, 5
	s_cselect_b64 s[0:1], -1, 0
	s_cmp_gt_u32 s73, 4
	s_cbranch_scc0 .LBB0_956
	s_andn2_b64 vcc, exec, s[28:29]
	s_mov_b64 s[4:5], -1
	s_cbranch_vccnz .LBB0_954
	v_lshl_add_u64 v[6:7], v[122:123], 2, s[16:17]
	s_nop 0
	s_nop 0
	s_nop 0
	v_mul_f32_e32 v19, 0x3fb8aa3b, v26
	v_exp_f32_e32 v19, v19
	s_mov_b32 s4, 0x800000
	s_mov_b32 s5, 0x3f317217
	s_mov_b32 s12, 0x7f800000
	v_add_f32_e32 v19, 1.0, v19
	v_rcp_f32_e32 v19, v19
	v_lshl_add_u64 v[30:31], v[28:29], 2, s[86:87]
	s_nop 0
	v_mul_f32_e32 v6, v19, v220
	v_mul_f32_e32 v19, 0x3fb8aa3b, v22
	v_exp_f32_e32 v19, v19
	v_min_f32_e32 v6, 0x3f7fffef, v6
	v_add_f32_e32 v19, 1.0, v19
	v_rcp_f32_e32 v19, v19
	s_nop 0
	v_mul_f32_e32 v2, v19, v224
	v_min_f32_e32 v19, 0x3f7fffef, v2
	v_sub_f32_e32 v2, 1.0, v6
	v_cmp_gt_f32_e32 vcc, s4, v2
	s_nop 1
	v_cndmask_b32_e64 v6, 0, 32, vcc
	v_ldexp_f32 v2, v2, v6
	v_log_f32_e32 v2, v2
	s_nop 0
	v_mul_f32_e32 v6, 0x3f317217, v2
	v_fma_f32 v6, v2, s5, -v6
	v_fmac_f32_e32 v6, 0x3377d1cf, v2
	v_fmac_f32_e32 v6, 0x3f317217, v2
	v_cmp_lt_f32_e64 s[10:11], |v2|, s12
	s_nop 1
	v_cndmask_b32_e64 v2, v2, v6, s[10:11]
	v_cndmask_b32_e32 v6, 0, v199, vcc
	v_sub_f32_e32 v2, v2, v6
	v_sub_f32_e32 v6, 1.0, v19
	v_cmp_gt_f32_e32 vcc, s4, v6
	s_nop 1
	v_cndmask_b32_e64 v19, 0, 32, vcc
	v_ldexp_f32 v6, v6, v19
	v_log_f32_e32 v6, v6
	s_nop 0
	v_mul_f32_e32 v19, 0x3f317217, v6
	v_fma_f32 v19, v6, s5, -v19
	v_fmac_f32_e32 v19, 0x3377d1cf, v6
	v_fmac_f32_e32 v19, 0x3f317217, v6
	v_cmp_lt_f32_e64 s[10:11], |v6|, s12
	s_nop 1
	v_cndmask_b32_e64 v6, v6, v19, s[10:11]
	v_cndmask_b32_e32 v19, 0, v199, vcc
	v_sub_f32_e32 v6, v6, v19
	v_mul_f32_e32 v19, 0x3fb8aa3b, v27
	v_exp_f32_e32 v19, v19
	s_nop 0
	v_add_f32_e32 v19, 1.0, v19
	v_rcp_f32_e32 v19, v19
	s_nop 0
	v_mul_f32_e32 v7, v19, v221
	v_mul_f32_e32 v19, 0x3fb8aa3b, v23
	v_exp_f32_e32 v19, v19
	v_min_f32_e32 v7, 0x3f7fffef, v7
	v_add_f32_e32 v19, 1.0, v19
	v_rcp_f32_e32 v19, v19
	s_nop 0
	v_mul_f32_e32 v3, v19, v225
	v_min_f32_e32 v19, 0x3f7fffef, v3
	v_sub_f32_e32 v3, 1.0, v7
	v_cmp_gt_f32_e32 vcc, s4, v3
	s_nop 1
	v_cndmask_b32_e64 v7, 0, 32, vcc
	v_ldexp_f32 v3, v3, v7
	v_log_f32_e32 v3, v3
	s_nop 0
	v_mul_f32_e32 v7, 0x3f317217, v3
	v_fma_f32 v7, v3, s5, -v7
	v_fmac_f32_e32 v7, 0x3377d1cf, v3
	v_fmac_f32_e32 v7, 0x3f317217, v3
	v_cmp_lt_f32_e64 s[10:11], |v3|, s12
	s_nop 1
	v_cndmask_b32_e64 v3, v3, v7, s[10:11]
	v_cndmask_b32_e32 v7, 0, v199, vcc
	v_sub_f32_e32 v3, v3, v7
	v_sub_f32_e32 v7, 1.0, v19
	v_cmp_gt_f32_e32 vcc, s4, v7
	s_nop 1
	v_cndmask_b32_e64 v19, 0, 32, vcc
	v_ldexp_f32 v7, v7, v19
	v_log_f32_e32 v7, v7
	s_nop 0
	v_mul_f32_e32 v19, 0x3f317217, v7
	v_fma_f32 v19, v7, s5, -v19
	v_fmac_f32_e32 v19, 0x3377d1cf, v7
	v_fmac_f32_e32 v19, 0x3f317217, v7
	v_cmp_lt_f32_e64 s[10:11], |v7|, s12
	s_nop 1
	v_cndmask_b32_e64 v7, v7, v19, s[10:11]
	v_cndmask_b32_e32 v19, 0, v199, vcc
	v_sub_f32_e32 v7, v7, v19
	v_mul_f32_e32 v19, 0x3fb8aa3b, v24
	v_exp_f32_e32 v19, v19
	s_nop 0
	v_add_f32_e32 v19, 1.0, v19
	v_rcp_f32_e32 v19, v19
	s_nop 0
	v_mul_f32_e32 v8, v19, v222
	v_mul_f32_e32 v19, 0x3fb8aa3b, v20
	v_exp_f32_e32 v19, v19
	v_min_f32_e32 v8, 0x3f7fffef, v8
	v_add_f32_e32 v19, 1.0, v19
	v_rcp_f32_e32 v19, v19
	s_nop 0
	v_mul_f32_e32 v4, v19, v226
	v_min_f32_e32 v19, 0x3f7fffef, v4
	v_sub_f32_e32 v4, 1.0, v8
	v_cmp_gt_f32_e32 vcc, s4, v4
	s_nop 1
	v_cndmask_b32_e64 v8, 0, 32, vcc
	v_ldexp_f32 v4, v4, v8
	v_log_f32_e32 v4, v4
	s_nop 0
	v_mul_f32_e32 v8, 0x3f317217, v4
	v_fma_f32 v8, v4, s5, -v8
	v_fmac_f32_e32 v8, 0x3377d1cf, v4
	v_fmac_f32_e32 v8, 0x3f317217, v4
	v_cmp_lt_f32_e64 s[10:11], |v4|, s12
	s_nop 1
	v_cndmask_b32_e64 v4, v4, v8, s[10:11]
	v_cndmask_b32_e32 v8, 0, v199, vcc
	v_sub_f32_e32 v4, v4, v8
	v_sub_f32_e32 v8, 1.0, v19
	v_cmp_gt_f32_e32 vcc, s4, v8
	s_nop 1
	v_cndmask_b32_e64 v19, 0, 32, vcc
	v_ldexp_f32 v8, v8, v19
	v_log_f32_e32 v8, v8
	s_nop 0
	v_mul_f32_e32 v19, 0x3f317217, v8
	v_fma_f32 v19, v8, s5, -v19
	v_fmac_f32_e32 v19, 0x3377d1cf, v8
	v_fmac_f32_e32 v19, 0x3f317217, v8
	v_cmp_lt_f32_e64 s[10:11], |v8|, s12
	s_nop 1
	v_cndmask_b32_e64 v8, v8, v19, s[10:11]
	v_cndmask_b32_e32 v19, 0, v199, vcc
	v_sub_f32_e32 v8, v8, v19
	v_mul_f32_e32 v19, 0x3fb8aa3b, v25
	v_exp_f32_e32 v19, v19
	s_nop 0
	v_add_f32_e32 v19, 1.0, v19
	v_rcp_f32_e32 v19, v19
	s_nop 0
	v_mul_f32_e32 v9, v19, v223
	v_mul_f32_e32 v19, 0x3fb8aa3b, v21
	v_exp_f32_e32 v19, v19
	v_min_f32_e32 v9, 0x3f7fffef, v9
	v_add_f32_e32 v19, 1.0, v19
	v_rcp_f32_e32 v19, v19
	s_nop 0
	v_mul_f32_e32 v5, v19, v227
	v_min_f32_e32 v19, 0x3f7fffef, v5
	v_sub_f32_e32 v5, 1.0, v9
	v_cmp_gt_f32_e32 vcc, s4, v5
	s_nop 1
	v_cndmask_b32_e64 v9, 0, 32, vcc
	v_ldexp_f32 v5, v5, v9
	v_log_f32_e32 v5, v5
	s_nop 0
	v_mul_f32_e32 v9, 0x3f317217, v5
	v_fma_f32 v9, v5, s5, -v9
	v_fmac_f32_e32 v9, 0x3377d1cf, v5
	v_fmac_f32_e32 v9, 0x3f317217, v5
	v_cmp_lt_f32_e64 s[10:11], |v5|, s12
	s_nop 1
	v_cndmask_b32_e64 v5, v5, v9, s[10:11]
	v_cndmask_b32_e32 v9, 0, v199, vcc
	v_sub_f32_e32 v5, v5, v9
	v_sub_f32_e32 v9, 1.0, v19
	v_cmp_gt_f32_e32 vcc, s4, v9
	s_nop 1
	v_cndmask_b32_e64 v19, 0, 32, vcc
	v_ldexp_f32 v9, v9, v19
	v_log_f32_e32 v9, v9
	s_nop 0
	v_mul_f32_e32 v19, 0x3f317217, v9
	v_fma_f32 v19, v9, s5, -v19
	v_fmac_f32_e32 v19, 0x3377d1cf, v9
	v_fmac_f32_e32 v19, 0x3f317217, v9
	v_cmp_lt_f32_e64 s[10:11], |v9|, s12
	s_mov_b64 s[4:5], 0
	s_nop 0
	v_cndmask_b32_e64 v9, v9, v19, s[10:11]
	v_cndmask_b32_e32 v19, 0, v199, vcc
	v_sub_f32_e32 v9, v9, v19
	global_store_dwordx4 v[30:31], v[2:5], off
	global_store_dwordx4 v[30:31], v[6:9], off offset:16

.LBB0_958:
	s_nop 1
	v_mad_i64_i32 v[2:3], s[0:1], v18, s33, 0
	v_lshl_add_u64 v[18:19], v[2:3], 0, v[124:125]
	s_cmp_gt_i32 s71, 8
	s_mov_b64 s[0:1], -1
	s_cbranch_scc1 .LBB0_964
	s_cmp_lt_u32 s73, 5
	s_cselect_b64 s[0:1], -1, 0
	s_cmp_gt_u32 s73, 4
	s_cbranch_scc0 .LBB0_964
	s_andn2_b64 vcc, exec, s[28:29]
	s_mov_b64 s[4:5], -1
	s_cbranch_vccnz .LBB0_962
	v_lshl_add_u64 v[6:7], v[122:123], 2, s[16:17]
	s_nop 0
	s_nop 0
	s_nop 0
	v_mul_f32_e32 v20, 0x3fb8aa3b, v16
	v_exp_f32_e32 v20, v20
	s_mov_b32 s4, 0x800000
	s_mov_b32 s5, 0x3f317217
	s_mov_b32 s12, 0x7f800000
	v_add_f32_e32 v20, 1.0, v20
	v_rcp_f32_e32 v20, v20
	s_nop 0
	v_mul_f32_e32 v6, v20, v228
	v_mul_f32_e32 v20, 0x3fb8aa3b, v12
	v_exp_f32_e32 v20, v20
	v_min_f32_e32 v6, 0x3f7fffef, v6
	v_add_f32_e32 v20, 1.0, v20
	v_rcp_f32_e32 v20, v20
	s_nop 0
	v_mul_f32_e32 v2, v20, v232
	v_min_f32_e32 v20, 0x3f7fffef, v2
	v_sub_f32_e32 v2, 1.0, v6
	v_cmp_gt_f32_e32 vcc, s4, v2
	s_nop 1
	v_cndmask_b32_e64 v6, 0, 32, vcc
	v_ldexp_f32 v2, v2, v6
	v_log_f32_e32 v2, v2
	s_nop 0
	v_mul_f32_e32 v6, 0x3f317217, v2
	v_fma_f32 v6, v2, s5, -v6
	v_fmac_f32_e32 v6, 0x3377d1cf, v2
	v_fmac_f32_e32 v6, 0x3f317217, v2
	v_cmp_lt_f32_e64 s[10:11], |v2|, s12
	s_nop 1
	v_cndmask_b32_e64 v2, v2, v6, s[10:11]
	v_cndmask_b32_e32 v6, 0, v199, vcc
	v_sub_f32_e32 v2, v2, v6
	v_sub_f32_e32 v6, 1.0, v20
	v_cmp_gt_f32_e32 vcc, s4, v6
	s_nop 1
	v_cndmask_b32_e64 v20, 0, 32, vcc
	v_ldexp_f32 v6, v6, v20
	v_log_f32_e32 v6, v6
	s_nop 0
	v_mul_f32_e32 v20, 0x3f317217, v6
	v_fma_f32 v20, v6, s5, -v20
	v_fmac_f32_e32 v20, 0x3377d1cf, v6
	v_fmac_f32_e32 v20, 0x3f317217, v6
	v_cmp_lt_f32_e64 s[10:11], |v6|, s12
	s_nop 1
	v_cndmask_b32_e64 v6, v6, v20, s[10:11]
	v_cndmask_b32_e32 v20, 0, v199, vcc
	v_sub_f32_e32 v6, v6, v20
	v_mul_f32_e32 v20, 0x3fb8aa3b, v17
	v_exp_f32_e32 v20, v20
	s_nop 0
	v_add_f32_e32 v20, 1.0, v20
	v_rcp_f32_e32 v20, v20
	s_nop 0
	v_mul_f32_e32 v7, v20, v229
	v_mul_f32_e32 v20, 0x3fb8aa3b, v13
	v_exp_f32_e32 v20, v20
	v_min_f32_e32 v7, 0x3f7fffef, v7
	v_add_f32_e32 v20, 1.0, v20
	v_rcp_f32_e32 v20, v20
	s_nop 0
	v_mul_f32_e32 v3, v20, v233
	v_min_f32_e32 v20, 0x3f7fffef, v3
	v_sub_f32_e32 v3, 1.0, v7
	v_cmp_gt_f32_e32 vcc, s4, v3
	s_nop 1
	v_cndmask_b32_e64 v7, 0, 32, vcc
	v_ldexp_f32 v3, v3, v7
	v_log_f32_e32 v3, v3
	s_nop 0
	v_mul_f32_e32 v7, 0x3f317217, v3
	v_fma_f32 v7, v3, s5, -v7
	v_fmac_f32_e32 v7, 0x3377d1cf, v3
	v_fmac_f32_e32 v7, 0x3f317217, v3
	v_cmp_lt_f32_e64 s[10:11], |v3|, s12
	s_nop 1
	v_cndmask_b32_e64 v3, v3, v7, s[10:11]
	v_cndmask_b32_e32 v7, 0, v199, vcc
	v_sub_f32_e32 v3, v3, v7
	v_sub_f32_e32 v7, 1.0, v20
	v_cmp_gt_f32_e32 vcc, s4, v7
	s_nop 1
	v_cndmask_b32_e64 v20, 0, 32, vcc
	v_ldexp_f32 v7, v7, v20
	v_log_f32_e32 v7, v7
	s_nop 0
	v_mul_f32_e32 v20, 0x3f317217, v7
	v_fma_f32 v20, v7, s5, -v20
	v_fmac_f32_e32 v20, 0x3377d1cf, v7
	v_fmac_f32_e32 v20, 0x3f317217, v7
	v_cmp_lt_f32_e64 s[10:11], |v7|, s12
	s_nop 1
	v_cndmask_b32_e64 v7, v7, v20, s[10:11]
	v_cndmask_b32_e32 v20, 0, v199, vcc
	v_sub_f32_e32 v7, v7, v20
	v_mul_f32_e32 v20, 0x3fb8aa3b, v14
	v_exp_f32_e32 v20, v20
	s_nop 0
	v_add_f32_e32 v20, 1.0, v20
	v_rcp_f32_e32 v20, v20
	s_nop 0
	v_mul_f32_e32 v8, v20, v230
	v_mul_f32_e32 v20, 0x3fb8aa3b, v10
	v_exp_f32_e32 v20, v20
	v_min_f32_e32 v8, 0x3f7fffef, v8
	v_add_f32_e32 v20, 1.0, v20
	v_rcp_f32_e32 v20, v20
	s_nop 0
	v_mul_f32_e32 v4, v20, v234
	v_min_f32_e32 v20, 0x3f7fffef, v4
	v_sub_f32_e32 v4, 1.0, v8
	v_cmp_gt_f32_e32 vcc, s4, v4
	s_nop 1
	v_cndmask_b32_e64 v8, 0, 32, vcc
	v_ldexp_f32 v4, v4, v8
	v_log_f32_e32 v4, v4
	s_nop 0
	v_mul_f32_e32 v8, 0x3f317217, v4
	v_fma_f32 v8, v4, s5, -v8
	v_fmac_f32_e32 v8, 0x3377d1cf, v4
	v_fmac_f32_e32 v8, 0x3f317217, v4
	v_cmp_lt_f32_e64 s[10:11], |v4|, s12
	s_nop 1
	v_cndmask_b32_e64 v4, v4, v8, s[10:11]
	v_cndmask_b32_e32 v8, 0, v199, vcc
	v_sub_f32_e32 v4, v4, v8
	v_sub_f32_e32 v8, 1.0, v20
	v_cmp_gt_f32_e32 vcc, s4, v8
	s_nop 1
	v_cndmask_b32_e64 v20, 0, 32, vcc
	v_ldexp_f32 v8, v8, v20
	v_log_f32_e32 v8, v8
	s_nop 0
	v_mul_f32_e32 v20, 0x3f317217, v8
	v_fma_f32 v20, v8, s5, -v20
	v_fmac_f32_e32 v20, 0x3377d1cf, v8
	v_fmac_f32_e32 v20, 0x3f317217, v8
	v_cmp_lt_f32_e64 s[10:11], |v8|, s12
	s_nop 1
	v_cndmask_b32_e64 v8, v8, v20, s[10:11]
	v_cndmask_b32_e32 v20, 0, v199, vcc
	v_sub_f32_e32 v8, v8, v20
	v_mul_f32_e32 v20, 0x3fb8aa3b, v15
	v_exp_f32_e32 v20, v20
	s_nop 0
	v_add_f32_e32 v20, 1.0, v20
	v_rcp_f32_e32 v20, v20
	s_nop 0
	v_mul_f32_e32 v9, v20, v231
	v_mul_f32_e32 v20, 0x3fb8aa3b, v11
	v_exp_f32_e32 v20, v20
	v_min_f32_e32 v9, 0x3f7fffef, v9
	v_add_f32_e32 v20, 1.0, v20
	v_rcp_f32_e32 v20, v20
	s_nop 0
	v_mul_f32_e32 v5, v20, v235
	v_min_f32_e32 v20, 0x3f7fffef, v5
	v_sub_f32_e32 v5, 1.0, v9
	v_cmp_gt_f32_e32 vcc, s4, v5
	s_nop 1
	v_cndmask_b32_e64 v9, 0, 32, vcc
	v_ldexp_f32 v5, v5, v9
	v_log_f32_e32 v5, v5
	s_nop 0
	v_mul_f32_e32 v9, 0x3f317217, v5
	v_fma_f32 v9, v5, s5, -v9
	v_fmac_f32_e32 v9, 0x3377d1cf, v5
	v_fmac_f32_e32 v9, 0x3f317217, v5
	v_cmp_lt_f32_e64 s[10:11], |v5|, s12
	s_nop 1
	v_cndmask_b32_e64 v5, v5, v9, s[10:11]
	v_cndmask_b32_e32 v9, 0, v199, vcc
	v_sub_f32_e32 v5, v5, v9
	v_sub_f32_e32 v9, 1.0, v20
	v_cmp_gt_f32_e32 vcc, s4, v9
	s_nop 1
	v_cndmask_b32_e64 v20, 0, 32, vcc
	v_ldexp_f32 v9, v9, v20
	v_log_f32_e32 v9, v9
	s_nop 0
	v_mul_f32_e32 v20, 0x3f317217, v9
	v_fma_f32 v20, v9, s5, -v20
	v_fmac_f32_e32 v20, 0x3377d1cf, v9
	v_fmac_f32_e32 v20, 0x3f317217, v9
	v_cmp_lt_f32_e64 s[10:11], |v9|, s12
	s_mov_b64 s[4:5], 0
	s_nop 0
	v_cndmask_b32_e64 v9, v9, v20, s[10:11]
	v_cndmask_b32_e32 v20, 0, v199, vcc
	v_sub_f32_e32 v9, v9, v20
	v_lshl_add_u64 v[20:21], v[18:19], 2, s[86:87]
	global_store_dwordx4 v[20:21], v[2:5], off
	global_store_dwordx4 v[20:21], v[6:9], off offset:16

.LBB0_966:
	s_andn2_b64 vcc, exec, s[28:29]
	s_mov_b64 s[0:1], -1
	s_cbranch_vccnz .LBB0_968
	v_lshl_add_u64 v[118:119], v[122:123], 2, s[16:17]
	s_nop 0
	s_nop 0
	s_nop 0
	v_mul_f32_e32 v148, 0x3fb8aa3b, v156
	v_exp_f32_e32 v148, v148
	s_mov_b32 s0, 0x800000
	s_mov_b32 s1, 0x3f317217
	s_mov_b32 s4, 0x7f800000
	v_add_f32_e32 v148, 1.0, v148
	v_rcp_f32_e32 v148, v148
	v_lshl_add_u64 v[160:161], v[158:159], 2, s[86:87]
	s_nop 0
	v_mul_f32_e32 v118, v148, v228
	v_mul_f32_e32 v148, 0x3fb8aa3b, v152
	v_exp_f32_e32 v148, v148
	v_min_f32_e32 v118, 0x3f7fffef, v118
	v_add_f32_e32 v148, 1.0, v148
	v_rcp_f32_e32 v148, v148
	s_nop 0
	v_mul_f32_e32 v114, v148, v232
	v_min_f32_e32 v148, 0x3f7fffef, v114
	v_sub_f32_e32 v114, 1.0, v118
	v_cmp_gt_f32_e32 vcc, s0, v114
	s_nop 1
	v_cndmask_b32_e64 v118, 0, 32, vcc
	v_ldexp_f32 v114, v114, v118
	v_log_f32_e32 v114, v114
	s_nop 0
	v_mul_f32_e32 v118, 0x3f317217, v114
	v_fma_f32 v118, v114, s1, -v118
	v_fmac_f32_e32 v118, 0x3377d1cf, v114
	v_fmac_f32_e32 v118, 0x3f317217, v114
	v_cmp_lt_f32_e64 s[10:11], |v114|, s4
	s_nop 1
	v_cndmask_b32_e64 v114, v114, v118, s[10:11]
	v_cndmask_b32_e32 v118, 0, v199, vcc
	v_sub_f32_e32 v114, v114, v118
	v_sub_f32_e32 v118, 1.0, v148
	v_cmp_gt_f32_e32 vcc, s0, v118
	s_nop 1
	v_cndmask_b32_e64 v148, 0, 32, vcc
	v_ldexp_f32 v118, v118, v148
	v_log_f32_e32 v118, v118
	s_nop 0
	v_mul_f32_e32 v148, 0x3f317217, v118
	v_fma_f32 v148, v118, s1, -v148
	v_fmac_f32_e32 v148, 0x3377d1cf, v118
	v_fmac_f32_e32 v148, 0x3f317217, v118
	v_cmp_lt_f32_e64 s[10:11], |v118|, s4
	s_nop 1
	v_cndmask_b32_e64 v118, v118, v148, s[10:11]
	v_cndmask_b32_e32 v148, 0, v199, vcc
	v_sub_f32_e32 v118, v118, v148
	v_mul_f32_e32 v148, 0x3fb8aa3b, v157
	v_exp_f32_e32 v148, v148
	s_nop 0
	v_add_f32_e32 v148, 1.0, v148
	v_rcp_f32_e32 v148, v148
	s_nop 0
	v_mul_f32_e32 v119, v148, v229
	v_mul_f32_e32 v148, 0x3fb8aa3b, v153
	v_exp_f32_e32 v148, v148
	v_min_f32_e32 v119, 0x3f7fffef, v119
	v_add_f32_e32 v148, 1.0, v148
	v_rcp_f32_e32 v148, v148
	s_nop 0
	v_mul_f32_e32 v115, v148, v233
	v_min_f32_e32 v148, 0x3f7fffef, v115
	v_sub_f32_e32 v115, 1.0, v119
	v_cmp_gt_f32_e32 vcc, s0, v115
	s_nop 1
	v_cndmask_b32_e64 v119, 0, 32, vcc
	v_ldexp_f32 v115, v115, v119
	v_log_f32_e32 v115, v115
	s_nop 0
	v_mul_f32_e32 v119, 0x3f317217, v115
	v_fma_f32 v119, v115, s1, -v119
	v_fmac_f32_e32 v119, 0x3377d1cf, v115
	v_fmac_f32_e32 v119, 0x3f317217, v115
	v_cmp_lt_f32_e64 s[10:11], |v115|, s4
	s_nop 1
	v_cndmask_b32_e64 v115, v115, v119, s[10:11]
	v_cndmask_b32_e32 v119, 0, v199, vcc
	v_sub_f32_e32 v115, v115, v119
	v_sub_f32_e32 v119, 1.0, v148
	v_cmp_gt_f32_e32 vcc, s0, v119
	s_nop 1
	v_cndmask_b32_e64 v148, 0, 32, vcc
	v_ldexp_f32 v119, v119, v148
	v_log_f32_e32 v119, v119
	s_nop 0
	v_mul_f32_e32 v148, 0x3f317217, v119
	v_fma_f32 v148, v119, s1, -v148
	v_fmac_f32_e32 v148, 0x3377d1cf, v119
	v_fmac_f32_e32 v148, 0x3f317217, v119
	v_cmp_lt_f32_e64 s[10:11], |v119|, s4
	s_nop 1
	v_cndmask_b32_e64 v119, v119, v148, s[10:11]
	v_cndmask_b32_e32 v148, 0, v199, vcc
	v_sub_f32_e32 v119, v119, v148
	v_mul_f32_e32 v148, 0x3fb8aa3b, v154
	v_exp_f32_e32 v148, v148
	s_nop 0
	v_add_f32_e32 v148, 1.0, v148
	v_rcp_f32_e32 v148, v148
	s_nop 0
	v_mul_f32_e32 v120, v148, v230
	v_mul_f32_e32 v148, 0x3fb8aa3b, v150
	v_exp_f32_e32 v148, v148
	v_min_f32_e32 v120, 0x3f7fffef, v120
	v_add_f32_e32 v148, 1.0, v148
	v_rcp_f32_e32 v148, v148
	s_nop 0
	v_mul_f32_e32 v116, v148, v234
	v_min_f32_e32 v148, 0x3f7fffef, v116
	v_sub_f32_e32 v116, 1.0, v120
	v_cmp_gt_f32_e32 vcc, s0, v116
	s_nop 1
	v_cndmask_b32_e64 v120, 0, 32, vcc
	v_ldexp_f32 v116, v116, v120
	v_log_f32_e32 v116, v116
	s_nop 0
	v_mul_f32_e32 v120, 0x3f317217, v116
	v_fma_f32 v120, v116, s1, -v120
	v_fmac_f32_e32 v120, 0x3377d1cf, v116
	v_fmac_f32_e32 v120, 0x3f317217, v116
	v_cmp_lt_f32_e64 s[10:11], |v116|, s4
	s_nop 1
	v_cndmask_b32_e64 v116, v116, v120, s[10:11]
	v_cndmask_b32_e32 v120, 0, v199, vcc
	v_sub_f32_e32 v116, v116, v120
	v_sub_f32_e32 v120, 1.0, v148
	v_cmp_gt_f32_e32 vcc, s0, v120
	s_nop 1
	v_cndmask_b32_e64 v148, 0, 32, vcc
	v_ldexp_f32 v120, v120, v148
	v_log_f32_e32 v120, v120
	s_nop 0
	v_mul_f32_e32 v148, 0x3f317217, v120
	v_fma_f32 v148, v120, s1, -v148
	v_fmac_f32_e32 v148, 0x3377d1cf, v120
	v_fmac_f32_e32 v148, 0x3f317217, v120
	v_cmp_lt_f32_e64 s[10:11], |v120|, s4
	s_nop 1
	v_cndmask_b32_e64 v120, v120, v148, s[10:11]
	v_cndmask_b32_e32 v148, 0, v199, vcc
	v_sub_f32_e32 v120, v120, v148
	v_mul_f32_e32 v148, 0x3fb8aa3b, v155
	v_exp_f32_e32 v148, v148
	s_nop 0
	v_add_f32_e32 v148, 1.0, v148
	v_rcp_f32_e32 v148, v148
	s_nop 0
	v_mul_f32_e32 v121, v148, v231
	v_mul_f32_e32 v148, 0x3fb8aa3b, v151
	v_exp_f32_e32 v148, v148
	v_min_f32_e32 v121, 0x3f7fffef, v121
	v_add_f32_e32 v148, 1.0, v148
	v_rcp_f32_e32 v148, v148
	s_nop 0
	v_mul_f32_e32 v117, v148, v235
	v_min_f32_e32 v148, 0x3f7fffef, v117
	v_sub_f32_e32 v117, 1.0, v121
	v_cmp_gt_f32_e32 vcc, s0, v117
	s_nop 1
	v_cndmask_b32_e64 v121, 0, 32, vcc
	v_ldexp_f32 v117, v117, v121
	v_log_f32_e32 v117, v117
	s_nop 0
	v_mul_f32_e32 v121, 0x3f317217, v117
	v_fma_f32 v121, v117, s1, -v121
	v_fmac_f32_e32 v121, 0x3377d1cf, v117
	v_fmac_f32_e32 v121, 0x3f317217, v117
	v_cmp_lt_f32_e64 s[10:11], |v117|, s4
	s_nop 1
	v_cndmask_b32_e64 v117, v117, v121, s[10:11]
	v_cndmask_b32_e32 v121, 0, v199, vcc
	v_sub_f32_e32 v117, v117, v121
	v_sub_f32_e32 v121, 1.0, v148
	v_cmp_gt_f32_e32 vcc, s0, v121
	s_nop 1
	v_cndmask_b32_e64 v148, 0, 32, vcc
	v_ldexp_f32 v121, v121, v148
	v_log_f32_e32 v121, v121
	s_nop 0
	v_mul_f32_e32 v148, 0x3f317217, v121
	v_fma_f32 v148, v121, s1, -v148
	v_fmac_f32_e32 v148, 0x3377d1cf, v121
	v_fmac_f32_e32 v148, 0x3f317217, v121
	v_cmp_lt_f32_e64 s[10:11], |v121|, s4
	s_mov_b64 s[0:1], 0
	s_nop 0
	v_cndmask_b32_e64 v121, v121, v148, s[10:11]
	v_cndmask_b32_e32 v148, 0, v199, vcc
	v_sub_f32_e32 v121, v121, v148
	global_store_dwordx4 v[160:161], v[114:117], off
	global_store_dwordx4 v[160:161], v[118:121], off offset:16
